# m1+m2 + all s_setprio removed (A/B of priority flips)
# speedup vs baseline: 1.0086x; 1.0086x over previous
; #define PG8_STAGE(bufoff, gbase, voff) do { _Pragma("unroll") for (int _i = 0; _i < 2; ++_i) \
;         __builtin_amdgcn_global_load_lds((const unsigned*)((const char*)(gbase) + (voff)[_i]), (PG8_LAS unsigned*)(lds + (bufoff) + ldsw + _i * 8192), 16, 0, 0); } while (0)
; #define PG8_LDA(dst, b, h) do { _Pragma("unroll") for (int m = 0; m < 4; ++m) _Pragma("unroll") for (int k = 0; k < 2; ++k) dst[m][k] = *(const PG8_LAS bf16x8*)(lds + PG8_SA(b, h) + aoff + m * 2048 + k * 1024); } while (0)
; #define PG8_LDB(dst, b, h) do { _Pragma("unroll") for (int n = 0; n < 2; ++n) _Pragma("unroll") for (int k = 0; k < 2; ++k) dst[n][k] = *(const PG8_LAS bf16x8*)(lds + PG8_SB(b, h) + boff + n * 2048 + k * 1024); } while (0)
; #define PG8_MMA(ai, bj, At, Bt) do { __builtin_amdgcn_s_setprio(1); _Pragma("unroll") for (int m = 0; m < 4; ++m) _Pragma("unroll") for (int n = 0; n < 2; ++n) _Pragma("unroll") for (int k = 0; k < 2; ++k) \
;         acc[ai][bj][m][n] = __builtin_amdgcn_mfma_f32_16x16x32_bf16(Bt[n][k], At[m][k], acc[ai][bj][m][n], 0, 0, 0); __builtin_amdgcn_s_setprio(0); } while (0)
; #define PG8_WAIT_V(n) asm volatile("s_waitcnt vmcnt(" #n ")" ::: "memory")
; #define PG8_WAIT_L(n) asm volatile("s_waitcnt lgkmcnt(" #n ")" ::: "memory")
; #define PG8_BAR __builtin_amdgcn_s_barrier()
; #define PG8_SCHED __builtin_amdgcn_sched_barrier(0)
; template <class Epi, class Sched, bool ALIGN_EPI = false, bool SP2 = false>
; __device__ __forceinline__ void gemm_phase(PG8_LAS unsigned char* lds, const Gemm g, const Sched& S, const Epi& E, const int tid) {
;     ...
;             const bool last = (t == nt - 2);
;             const char* a1 = cA + (size_t)(t + 1) * kstep;
;             const char* a2 = last ? nA : cA + (size_t)(t + 2) * kstep; const char* b2 = last ? nB : cB + (size_t)(t + 2) * kstep;
;             const char* a3 = a2 + kstep; const char* b3 = b2 + kstep;
;             if (last && has_next) S.a_ready(nxt);
;             if constexpr (SP2) {
;             PG8_LDB(B0, 0, 0); PG8_LDB(B1, 0, 1); PG8_SCHED; PG8_LDA(At, 0, 0); PG8_STAGE(PG8_SA(1, 1), a1 + hstep, voffA);
;             PG8_WAIT_V(8); PG8_WAIT_L(0); PG8_BAR; PG8_MMA(0, 0, At, B0); PG8_MMA(0, 1, At, B1); PG8_BAR; PG8_SCHED;
;             PG8_LDA(At, 0, 1); PG8_STAGE(PG8_SB(0, 0), b2, voffB); PG8_STAGE(PG8_SB(0, 1), b2 + hstep, voffB); PG8_STAGE(PG8_SA(0, 0), a2, voffA);
.LBB0_38:
	s_add_u32 s58, s44, 0xfffc0080
	s_addc_u32 s59, s45, -1
	s_add_i32 s73, 0, 0x10000
	s_cmp_eq_u32 s72, 12
	s_cselect_b32 s79, s17, s59
	s_cselect_b32 s78, s60, s58
	v_add_u32_e32 v138, s73, v140
	s_cselect_b32 s59, s15, s71
	s_cselect_b32 s58, s70, s62
	s_add_i32 s76, 0, 0x14000
	ds_read_b128 v[142:145], v138
	ds_read_b128 v[146:149], v138 offset:1024
	ds_read_b128 v[150:153], v138 offset:2048
	ds_read_b128 v[154:157], v138 offset:3072
	v_add_u32_e32 v138, s76, v140
	ds_read_b128 v[158:161], v138
	ds_read_b128 v[162:165], v138 offset:1024
	ds_read_b128 v[166:169], v138 offset:2048
	ds_read_b128 v[170:173], v138 offset:3072
	v_lshl_add_u64 v[138:139], s[44:45], 0, v[134:135]
	s_add_i32 m0, s38, 0xc000
	ds_read_b128 v[174:177], v141
	ds_read_b128 v[178:181], v141 offset:1024
	ds_read_b128 v[182:185], v141 offset:2048
	ds_read_b128 v[186:189], v141 offset:3072
	ds_read_b128 v[212:215], v141 offset:4096
	ds_read_b128 v[216:219], v141 offset:5120
	ds_read_b128 v[232:235], v141 offset:6144
	ds_read_b128 v[236:239], v141 offset:7168
	global_load_lds_dwordx4 v[138:139], off
	v_lshl_add_u64 v[138:139], s[44:45], 0, v[136:137]
	s_add_i32 m0, s38, 0xe000
	s_nop 0
	global_load_lds_dwordx4 v[138:139], off
	s_waitcnt vmcnt(8)
	s_waitcnt lgkmcnt(0)
	s_barrier
	s_waitcnt lgkmcnt(0)
	v_mfma_f32_16x16x32_bf16 v[124:127], v[142:145], v[174:177], v[124:127]
	v_mfma_f32_16x16x32_bf16 v[120:123], v[150:153], v[174:177], v[120:123]
	v_mfma_f32_16x16x32_bf16 v[108:111], v[142:145], v[182:185], v[108:111]
	v_mfma_f32_16x16x32_bf16 v[104:107], v[150:153], v[182:185], v[104:107]
	v_mfma_f32_16x16x32_bf16 v[92:95], v[142:145], v[212:215], v[92:95]
	v_mfma_f32_16x16x32_bf16 v[88:91], v[150:153], v[212:215], v[88:91]
	v_mfma_f32_16x16x32_bf16 v[76:79], v[142:145], v[232:235], v[76:79]
	v_mfma_f32_16x16x32_bf16 v[72:75], v[150:153], v[232:235], v[72:75]
	v_mfma_f32_16x16x32_bf16 v[124:127], v[146:149], v[178:181], v[124:127]
	v_mfma_f32_16x16x32_bf16 v[120:123], v[154:157], v[178:181], v[120:123]
	v_mfma_f32_16x16x32_bf16 v[108:111], v[146:149], v[186:189], v[108:111]
	v_mfma_f32_16x16x32_bf16 v[104:107], v[154:157], v[186:189], v[104:107]
	v_mfma_f32_16x16x32_bf16 v[92:95], v[146:149], v[216:219], v[92:95]
	v_mfma_f32_16x16x32_bf16 v[88:91], v[154:157], v[216:219], v[88:91]
	v_mfma_f32_16x16x32_bf16 v[76:79], v[146:149], v[236:239], v[76:79]
	v_mfma_f32_16x16x32_bf16 v[72:75], v[154:157], v[236:239], v[72:75]
	v_mfma_f32_16x16x32_bf16 v[116:119], v[158:161], v[174:177], v[116:119]
	v_mfma_f32_16x16x32_bf16 v[112:115], v[166:169], v[174:177], v[112:115]
	v_mfma_f32_16x16x32_bf16 v[100:103], v[158:161], v[182:185], v[100:103]
	v_mfma_f32_16x16x32_bf16 v[96:99], v[166:169], v[182:185], v[96:99]
	v_mfma_f32_16x16x32_bf16 v[84:87], v[158:161], v[212:215], v[84:87]
	v_mfma_f32_16x16x32_bf16 v[80:83], v[166:169], v[212:215], v[80:83]
	v_mfma_f32_16x16x32_bf16 v[68:71], v[158:161], v[232:235], v[68:71]
	v_mfma_f32_16x16x32_bf16 v[64:67], v[166:169], v[232:235], v[64:67]
	v_mfma_f32_16x16x32_bf16 v[116:119], v[162:165], v[178:181], v[116:119]
	v_mfma_f32_16x16x32_bf16 v[112:115], v[170:173], v[178:181], v[112:115]
	v_mfma_f32_16x16x32_bf16 v[100:103], v[162:165], v[186:189], v[100:103]
	v_mfma_f32_16x16x32_bf16 v[96:99], v[170:173], v[186:189], v[96:99]
	v_mfma_f32_16x16x32_bf16 v[84:87], v[162:165], v[216:219], v[84:87]
	v_mfma_f32_16x16x32_bf16 v[80:83], v[170:173], v[216:219], v[80:83]
	v_mfma_f32_16x16x32_bf16 v[68:71], v[162:165], v[236:239], v[68:71]
	v_mfma_f32_16x16x32_bf16 v[64:67], v[170:173], v[236:239], v[64:67]
	s_barrier
	s_add_i32 s73, s73, s35
	v_lshl_add_u64 v[138:139], s[58:59], 0, v[192:193]
	s_mov_b32 m0, s73
	ds_read_b128 v[174:177], v141 offset:16384
	ds_read_b128 v[178:181], v141 offset:17408
	ds_read_b128 v[182:185], v141 offset:18432
	ds_read_b128 v[186:189], v141 offset:19456
	ds_read_b128 v[212:215], v141 offset:20480
	ds_read_b128 v[216:219], v141 offset:21504
	ds_read_b128 v[232:235], v141 offset:22528
	ds_read_b128 v[236:239], v141 offset:23552
	global_load_lds_dwordx4 v[138:139], off
	s_add_i32 m0, s73, 0x2000
	s_add_u32 s74, s58, 0x40000
	v_lshl_add_u64 v[190:191], s[58:59], 0, v[132:133]
	s_addc_u32 s75, s59, 0
	s_add_i32 s73, s76, s35
	global_load_lds_dwordx4 v[190:191], off
	v_lshl_add_u64 v[194:195], s[74:75], 0, v[192:193]
	s_mov_b32 m0, s73
	v_lshl_add_u64 v[196:197], s[78:79], 0, v[130:131]
	global_load_lds_dwordx4 v[194:195], off
	v_lshl_add_u64 v[194:195], s[74:75], 0, v[132:133]
	s_add_i32 m0, s73, 0x2000
	s_nop 0
	global_load_lds_dwordx4 v[194:195], off
	v_lshl_add_u64 v[194:195], s[78:79], 0, v[128:129]
	s_mov_b32 m0, s38
	s_nop 0
	global_load_lds_dwordx4 v[194:195], off
	s_mov_b32 m0, s40
	s_nop 0
	global_load_lds_dwordx4 v[196:197], off
	s_waitcnt vmcnt(8)
	s_waitcnt lgkmcnt(0)
	s_barrier
; #define PG8_STAGE(bufoff, gbase, voff) do { _Pragma("unroll") for (int _i = 0; _i < 2; ++_i) \
;         __builtin_amdgcn_global_load_lds((const unsigned*)((const char*)(gbase) + (voff)[_i]), (PG8_LAS unsigned*)(lds + (bufoff) + ldsw + _i * 8192), 16, 0, 0); } while (0)
; #define PG8_LDA(dst, b, h) do { _Pragma("unroll") for (int m = 0; m < 4; ++m) _Pragma("unroll") for (int k = 0; k < 2; ++k) dst[m][k] = *(const PG8_LAS bf16x8*)(lds + PG8_SA(b, h) + aoff + m * 2048 + k * 1024); } while (0)
; #define PG8_LDB(dst, b, h) do { _Pragma("unroll") for (int n = 0; n < 2; ++n) _Pragma("unroll") for (int k = 0; k < 2; ++k) dst[n][k] = *(const PG8_LAS bf16x8*)(lds + PG8_SB(b, h) + boff + n * 2048 + k * 1024); } while (0)
; #define PG8_MMA(ai, bj, At, Bt) do { __builtin_amdgcn_s_setprio(1); _Pragma("unroll") for (int m = 0; m < 4; ++m) _Pragma("unroll") for (int n = 0; n < 2; ++n) _Pragma("unroll") for (int k = 0; k < 2; ++k) \
;         acc[ai][bj][m][n] = __builtin_amdgcn_mfma_f32_16x16x32_bf16(Bt[n][k], At[m][k], acc[ai][bj][m][n], 0, 0, 0); __builtin_amdgcn_s_setprio(0); } while (0)
; #define PG8_WAIT_V(n) asm volatile("s_waitcnt vmcnt(" #n ")" ::: "memory")
; #define PG8_WAIT_L(n) asm volatile("s_waitcnt lgkmcnt(" #n ")" ::: "memory")
; #define PG8_BAR __builtin_amdgcn_s_barrier()
; #define PG8_SCHED __builtin_amdgcn_sched_barrier(0)
; template <class Epi, class Sched, bool ALIGN_EPI = false, bool SP2 = false>
; __device__ __forceinline__ void gemm_phase(PG8_LAS unsigned char* lds, const Gemm g, const Sched& S, const Epi& E, const int tid) {
;     ...
;             PG8_WAIT_V(8); PG8_WAIT_L(0); PG8_BAR; PG8_MMA(1, 0, At, B0); PG8_MMA(1, 1, At, B1); PG8_BAR; PG8_SCHED;
;             PG8_LDB(B0, 1, 0); PG8_LDB(B1, 1, 1); PG8_SCHED; PG8_LDA(At, 1, 0); PG8_STAGE(PG8_SA(0, 1), a2 + hstep, voffA);
;             PG8_WAIT_V(8); PG8_WAIT_L(0); PG8_BAR; PG8_MMA(0, 0, At, B0); PG8_MMA(0, 1, At, B1); PG8_BAR; PG8_SCHED;
	s_waitcnt lgkmcnt(0)
	v_mfma_f32_16x16x32_bf16 v[60:63], v[142:145], v[174:177], v[60:63]
	v_mfma_f32_16x16x32_bf16 v[56:59], v[150:153], v[174:177], v[56:59]
	v_mfma_f32_16x16x32_bf16 v[44:47], v[142:145], v[182:185], v[44:47]
	v_mfma_f32_16x16x32_bf16 v[40:43], v[150:153], v[182:185], v[40:43]
	v_mfma_f32_16x16x32_bf16 v[28:31], v[142:145], v[212:215], v[28:31]
	v_mfma_f32_16x16x32_bf16 v[24:27], v[150:153], v[212:215], v[24:27]
	v_mfma_f32_16x16x32_bf16 v[12:15], v[142:145], v[232:235], v[12:15]
	v_mfma_f32_16x16x32_bf16 v[8:11], v[150:153], v[232:235], v[8:11]
	v_mfma_f32_16x16x32_bf16 v[60:63], v[146:149], v[178:181], v[60:63]
	v_mfma_f32_16x16x32_bf16 v[56:59], v[154:157], v[178:181], v[56:59]
	v_mfma_f32_16x16x32_bf16 v[44:47], v[146:149], v[186:189], v[44:47]
	v_mfma_f32_16x16x32_bf16 v[40:43], v[154:157], v[186:189], v[40:43]
	v_mfma_f32_16x16x32_bf16 v[28:31], v[146:149], v[216:219], v[28:31]
	v_mfma_f32_16x16x32_bf16 v[24:27], v[154:157], v[216:219], v[24:27]
	v_mfma_f32_16x16x32_bf16 v[12:15], v[146:149], v[236:239], v[12:15]
	v_mfma_f32_16x16x32_bf16 v[8:11], v[154:157], v[236:239], v[8:11]
	v_mfma_f32_16x16x32_bf16 v[52:55], v[158:161], v[174:177], v[52:55]
	v_mfma_f32_16x16x32_bf16 v[48:51], v[166:169], v[174:177], v[48:51]
	v_mfma_f32_16x16x32_bf16 v[36:39], v[158:161], v[182:185], v[36:39]
	v_mfma_f32_16x16x32_bf16 v[32:35], v[166:169], v[182:185], v[32:35]
	v_mfma_f32_16x16x32_bf16 v[20:23], v[158:161], v[212:215], v[20:23]
	v_mfma_f32_16x16x32_bf16 v[16:19], v[166:169], v[212:215], v[16:19]
	v_mfma_f32_16x16x32_bf16 v[4:7], v[158:161], v[232:235], v[4:7]
	v_mfma_f32_16x16x32_bf16 v[0:3], v[166:169], v[232:235], v[0:3]
	v_mfma_f32_16x16x32_bf16 v[52:55], v[162:165], v[178:181], v[52:55]
	v_mfma_f32_16x16x32_bf16 v[48:51], v[170:173], v[178:181], v[48:51]
	v_mfma_f32_16x16x32_bf16 v[36:39], v[162:165], v[186:189], v[36:39]
	v_mfma_f32_16x16x32_bf16 v[32:35], v[170:173], v[186:189], v[32:35]
	v_mfma_f32_16x16x32_bf16 v[20:23], v[162:165], v[216:219], v[20:23]
	v_mfma_f32_16x16x32_bf16 v[16:19], v[170:173], v[216:219], v[16:19]
	v_mfma_f32_16x16x32_bf16 v[4:7], v[162:165], v[236:239], v[4:7]
	v_mfma_f32_16x16x32_bf16 v[0:3], v[170:173], v[236:239], v[0:3]
	s_barrier
	s_add_i32 s73, 0, 0x18000
	s_add_i32 s76, 0, 0x1c000
	v_add_u32_e32 v154, s73, v140
	v_add_u32_e32 v170, s76, v140
	ds_read_b128 v[142:145], v154
	ds_read_b128 v[146:149], v154 offset:1024
	ds_read_b128 v[150:153], v154 offset:2048
	ds_read_b128 v[154:157], v154 offset:3072
	ds_read_b128 v[158:161], v170
	ds_read_b128 v[162:165], v170 offset:1024
	ds_read_b128 v[166:169], v170 offset:2048
	ds_read_b128 v[170:173], v170 offset:3072
	s_add_u32 s74, s78, 0x40000
	s_addc_u32 s75, s79, 0
	s_mov_b32 m0, s41
	v_lshl_add_u64 v[202:203], s[74:75], 0, v[128:129]
	ds_read_b128 v[174:177], v141 offset:32768
	ds_read_b128 v[178:181], v141 offset:33792
	ds_read_b128 v[182:185], v141 offset:34816
	ds_read_b128 v[186:189], v141 offset:35840
	ds_read_b128 v[212:215], v141 offset:36864
	ds_read_b128 v[216:219], v141 offset:37888
	ds_read_b128 v[232:235], v141 offset:38912
	ds_read_b128 v[236:239], v141 offset:39936
	global_load_lds_dwordx4 v[202:203], off
	v_lshl_add_u64 v[202:203], s[74:75], 0, v[130:131]
	s_mov_b32 m0, s46
	s_nop 0
	global_load_lds_dwordx4 v[202:203], off
	s_waitcnt vmcnt(8)
	s_waitcnt lgkmcnt(0)
	s_barrier
	s_waitcnt lgkmcnt(0)
	v_mfma_f32_16x16x32_bf16 v[124:127], v[142:145], v[174:177], v[124:127]
	v_mfma_f32_16x16x32_bf16 v[120:123], v[150:153], v[174:177], v[120:123]
	v_mfma_f32_16x16x32_bf16 v[108:111], v[142:145], v[182:185], v[108:111]
	v_mfma_f32_16x16x32_bf16 v[104:107], v[150:153], v[182:185], v[104:107]
	v_mfma_f32_16x16x32_bf16 v[92:95], v[142:145], v[212:215], v[92:95]
	v_mfma_f32_16x16x32_bf16 v[88:91], v[150:153], v[212:215], v[88:91]
	v_mfma_f32_16x16x32_bf16 v[76:79], v[142:145], v[232:235], v[76:79]
	v_mfma_f32_16x16x32_bf16 v[72:75], v[150:153], v[232:235], v[72:75]
	v_mfma_f32_16x16x32_bf16 v[124:127], v[146:149], v[178:181], v[124:127]
	v_mfma_f32_16x16x32_bf16 v[120:123], v[154:157], v[178:181], v[120:123]
	v_mfma_f32_16x16x32_bf16 v[108:111], v[146:149], v[186:189], v[108:111]
	v_mfma_f32_16x16x32_bf16 v[104:107], v[154:157], v[186:189], v[104:107]
	v_mfma_f32_16x16x32_bf16 v[92:95], v[146:149], v[216:219], v[92:95]
	v_mfma_f32_16x16x32_bf16 v[88:91], v[154:157], v[216:219], v[88:91]
	v_mfma_f32_16x16x32_bf16 v[76:79], v[146:149], v[236:239], v[76:79]
	v_mfma_f32_16x16x32_bf16 v[72:75], v[154:157], v[236:239], v[72:75]
	v_mfma_f32_16x16x32_bf16 v[116:119], v[158:161], v[174:177], v[116:119]
	v_mfma_f32_16x16x32_bf16 v[112:115], v[166:169], v[174:177], v[112:115]
	v_mfma_f32_16x16x32_bf16 v[100:103], v[158:161], v[182:185], v[100:103]
	v_mfma_f32_16x16x32_bf16 v[96:99], v[166:169], v[182:185], v[96:99]
	v_mfma_f32_16x16x32_bf16 v[84:87], v[158:161], v[212:215], v[84:87]
	v_mfma_f32_16x16x32_bf16 v[80:83], v[166:169], v[212:215], v[80:83]
	v_mfma_f32_16x16x32_bf16 v[68:71], v[158:161], v[232:235], v[68:71]
	v_mfma_f32_16x16x32_bf16 v[64:67], v[166:169], v[232:235], v[64:67]
	v_mfma_f32_16x16x32_bf16 v[116:119], v[162:165], v[178:181], v[116:119]
	v_mfma_f32_16x16x32_bf16 v[112:115], v[170:173], v[178:181], v[112:115]
	v_mfma_f32_16x16x32_bf16 v[100:103], v[162:165], v[186:189], v[100:103]
	v_mfma_f32_16x16x32_bf16 v[96:99], v[170:173], v[186:189], v[96:99]
	v_mfma_f32_16x16x32_bf16 v[84:87], v[162:165], v[216:219], v[84:87]
	v_mfma_f32_16x16x32_bf16 v[80:83], v[170:173], v[216:219], v[80:83]
	v_mfma_f32_16x16x32_bf16 v[68:71], v[162:165], v[236:239], v[68:71]
	v_mfma_f32_16x16x32_bf16 v[64:67], v[170:173], v[236:239], v[64:67]
	s_barrier
; #define PG8_STAGE(bufoff, gbase, voff) do { _Pragma("unroll") for (int _i = 0; _i < 2; ++_i) \
;         __builtin_amdgcn_global_load_lds((const unsigned*)((const char*)(gbase) + (voff)[_i]), (PG8_LAS unsigned*)(lds + (bufoff) + ldsw + _i * 8192), 16, 0, 0); } while (0)
; #define PG8_LDA(dst, b, h) do { _Pragma("unroll") for (int m = 0; m < 4; ++m) _Pragma("unroll") for (int k = 0; k < 2; ++k) dst[m][k] = *(const PG8_LAS bf16x8*)(lds + PG8_SA(b, h) + aoff + m * 2048 + k * 1024); } while (0)
; #define PG8_MMA(ai, bj, At, Bt) do { __builtin_amdgcn_s_setprio(1); _Pragma("unroll") for (int m = 0; m < 4; ++m) _Pragma("unroll") for (int n = 0; n < 2; ++n) _Pragma("unroll") for (int k = 0; k < 2; ++k) \
;         acc[ai][bj][m][n] = __builtin_amdgcn_mfma_f32_16x16x32_bf16(Bt[n][k], At[m][k], acc[ai][bj][m][n], 0, 0, 0); __builtin_amdgcn_s_setprio(0); } while (0)
; #define PG8_WAIT_V(n) asm volatile("s_waitcnt vmcnt(" #n ")" ::: "memory")
; #define PG8_WAIT_L(n) asm volatile("s_waitcnt lgkmcnt(" #n ")" ::: "memory")
; #define PG8_BAR __builtin_amdgcn_s_barrier()
; #define PG8_SCHED __builtin_amdgcn_sched_barrier(0)
; template <class Epi, class Sched, bool ALIGN_EPI = false, bool SP2 = false>
; __device__ __forceinline__ void gemm_phase(PG8_LAS unsigned char* lds, const Gemm g, const Sched& S, const Epi& E, const int tid) {
;     ...
;             PG8_LDA(At, 1, 1); PG8_STAGE(PG8_SB(1, 0), b3, voffB); PG8_STAGE(PG8_SB(1, 1), b3 + hstep, voffB); PG8_STAGE(PG8_SA(1, 0), a3, voffA);
;             PG8_WAIT_V(8); PG8_WAIT_L(0); PG8_BAR; PG8_MMA(1, 0, At, B0); PG8_MMA(1, 1, At, B1); PG8_BAR; PG8_SCHED;
	s_add_i32 s73, s73, s35
	v_lshl_add_u64 v[138:139], v[138:139], 0, s[36:37]
	s_mov_b32 m0, s73
	ds_read_b128 v[174:177], v141 offset:49152
	ds_read_b128 v[178:181], v141 offset:50176
	ds_read_b128 v[182:185], v141 offset:51200
	ds_read_b128 v[186:189], v141 offset:52224
	ds_read_b128 v[212:215], v141 offset:53248
	ds_read_b128 v[216:219], v141 offset:54272
	ds_read_b128 v[232:235], v141 offset:55296
	ds_read_b128 v[236:239], v141 offset:56320
	global_load_lds_dwordx4 v[138:139], off
	s_add_i32 m0, s73, 0x2000
	s_add_u32 s58, s58, 0x40080
	v_lshl_add_u64 v[138:139], v[190:191], 0, s[36:37]
	s_addc_u32 s59, s59, 0
	s_add_i32 s73, s76, s35
	global_load_lds_dwordx4 v[138:139], off
	v_lshl_add_u64 v[138:139], s[58:59], 0, v[192:193]
	s_mov_b32 m0, s73
	s_nop 0
	global_load_lds_dwordx4 v[138:139], off
	v_lshl_add_u64 v[138:139], s[58:59], 0, v[132:133]
	s_add_i32 m0, s73, 0x2000
	s_nop 0
	global_load_lds_dwordx4 v[138:139], off
	v_lshl_add_u64 v[138:139], v[194:195], 0, s[36:37]
	s_mov_b32 m0, s47
	s_nop 0
	global_load_lds_dwordx4 v[138:139], off
	v_lshl_add_u64 v[138:139], v[196:197], 0, s[36:37]
	s_mov_b32 m0, s53
	s_nop 0
	global_load_lds_dwordx4 v[138:139], off
	s_waitcnt vmcnt(8)
	s_waitcnt lgkmcnt(0)
	s_barrier
	s_waitcnt lgkmcnt(0)
	v_mfma_f32_16x16x32_bf16 v[60:63], v[142:145], v[174:177], v[60:63]
	v_mfma_f32_16x16x32_bf16 v[56:59], v[150:153], v[174:177], v[56:59]
	v_mfma_f32_16x16x32_bf16 v[44:47], v[142:145], v[182:185], v[44:47]
	v_mfma_f32_16x16x32_bf16 v[40:43], v[150:153], v[182:185], v[40:43]
	v_mfma_f32_16x16x32_bf16 v[28:31], v[142:145], v[212:215], v[28:31]
	v_mfma_f32_16x16x32_bf16 v[24:27], v[150:153], v[212:215], v[24:27]
	v_mfma_f32_16x16x32_bf16 v[12:15], v[142:145], v[232:235], v[12:15]
	v_mfma_f32_16x16x32_bf16 v[8:11], v[150:153], v[232:235], v[8:11]
	v_mfma_f32_16x16x32_bf16 v[60:63], v[146:149], v[178:181], v[60:63]
	v_mfma_f32_16x16x32_bf16 v[56:59], v[154:157], v[178:181], v[56:59]
	v_mfma_f32_16x16x32_bf16 v[44:47], v[146:149], v[186:189], v[44:47]
	v_mfma_f32_16x16x32_bf16 v[40:43], v[154:157], v[186:189], v[40:43]
	v_mfma_f32_16x16x32_bf16 v[28:31], v[146:149], v[216:219], v[28:31]
	v_mfma_f32_16x16x32_bf16 v[24:27], v[154:157], v[216:219], v[24:27]
	v_mfma_f32_16x16x32_bf16 v[12:15], v[146:149], v[236:239], v[12:15]
	v_mfma_f32_16x16x32_bf16 v[8:11], v[154:157], v[236:239], v[8:11]
	v_mfma_f32_16x16x32_bf16 v[52:55], v[158:161], v[174:177], v[52:55]
	v_mfma_f32_16x16x32_bf16 v[48:51], v[166:169], v[174:177], v[48:51]
	v_mfma_f32_16x16x32_bf16 v[36:39], v[158:161], v[182:185], v[36:39]
	v_mfma_f32_16x16x32_bf16 v[32:35], v[166:169], v[182:185], v[32:35]
	v_mfma_f32_16x16x32_bf16 v[20:23], v[158:161], v[212:215], v[20:23]
	v_mfma_f32_16x16x32_bf16 v[16:19], v[166:169], v[212:215], v[16:19]
	v_mfma_f32_16x16x32_bf16 v[4:7], v[158:161], v[232:235], v[4:7]
	v_mfma_f32_16x16x32_bf16 v[0:3], v[166:169], v[232:235], v[0:3]
	v_mfma_f32_16x16x32_bf16 v[52:55], v[162:165], v[178:181], v[52:55]
	v_mfma_f32_16x16x32_bf16 v[48:51], v[170:173], v[178:181], v[48:51]
	v_mfma_f32_16x16x32_bf16 v[36:39], v[162:165], v[186:189], v[36:39]
	v_mfma_f32_16x16x32_bf16 v[32:35], v[170:173], v[186:189], v[32:35]
	v_mfma_f32_16x16x32_bf16 v[20:23], v[162:165], v[216:219], v[20:23]
	v_mfma_f32_16x16x32_bf16 v[16:19], v[170:173], v[216:219], v[16:19]
	v_mfma_f32_16x16x32_bf16 v[4:7], v[162:165], v[236:239], v[4:7]
	v_mfma_f32_16x16x32_bf16 v[0:3], v[170:173], v[236:239], v[0:3]
	s_barrier
	s_add_i32 s72, s72, 2
	s_add_u32 s44, s44, 0x100
	s_addc_u32 s45, s45, 0
	s_add_u32 s62, s62, 0x100
	s_addc_u32 s71, s71, 0
	s_cmp_gt_u32 s72, 13
	s_cbranch_scc0 .LBB0_38
	s_and_b64 vcc, exec, s[10:11]
	s_mov_b64 s[72:73], 0x20000
	s_cbranch_vccz .LBB0_41
	s_barrier

; #define PG8_STAGE(bufoff, gbase, voff) do { _Pragma("unroll") for (int _i = 0; _i < 2; ++_i) \
;         __builtin_amdgcn_global_load_lds((const unsigned*)((const char*)(gbase) + (voff)[_i]), (PG8_LAS unsigned*)(lds + (bufoff) + ldsw + _i * 8192), 16, 0, 0); } while (0)
; #define PG8_LDA(dst, b, h) do { _Pragma("unroll") for (int m = 0; m < 4; ++m) _Pragma("unroll") for (int k = 0; k < 2; ++k) dst[m][k] = *(const PG8_LAS bf16x8*)(lds + PG8_SA(b, h) + aoff + m * 2048 + k * 1024); } while (0)
; #define PG8_LDB(dst, b, h) do { _Pragma("unroll") for (int n = 0; n < 2; ++n) _Pragma("unroll") for (int k = 0; k < 2; ++k) dst[n][k] = *(const PG8_LAS bf16x8*)(lds + PG8_SB(b, h) + boff + n * 2048 + k * 1024); } while (0)
; #define PG8_MMA(ai, bj, At, Bt) do { __builtin_amdgcn_s_setprio(1); _Pragma("unroll") for (int m = 0; m < 4; ++m) _Pragma("unroll") for (int n = 0; n < 2; ++n) _Pragma("unroll") for (int k = 0; k < 2; ++k) \
;         acc[ai][bj][m][n] = __builtin_amdgcn_mfma_f32_16x16x32_bf16(Bt[n][k], At[m][k], acc[ai][bj][m][n], 0, 0, 0); __builtin_amdgcn_s_setprio(0); } while (0)
; template <class Epi, class Sched, bool ALIGN_EPI = false, bool SP2 = false>
; __device__ __forceinline__ void gemm_phase(PG8_LAS unsigned char* lds, const Gemm g, const Sched& S, const Epi& E, const int tid) {
;     ...
;         const bool has_next = S.next(ui + 1, nxt);
;         const char* nA = has_next ? (const char*)g.A + (size_t)nxt.pm * tstep : cA; const char* nB = has_next ? (const char*)g.Bt + (size_t)nxt.pn * tstep : cB;
;         for (int t = 0; t < nt; t += 2) {
;             const bool last = (t == nt - 2);
;             const char* a1 = cA + (size_t)(t + 1) * kstep;
;             const char* a2 = last ? nA : cA + (size_t)(t + 2) * kstep; const char* b2 = last ? nB : cB + (size_t)(t + 2) * kstep;
;             const char* a3 = a2 + kstep; const char* b3 = b2 + kstep;
;             if (last && has_next) S.a_ready(nxt);
;             if constexpr (SP2) {
;             PG8_LDB(B0, 0, 0); PG8_LDB(B1, 0, 1); PG8_SCHED; PG8_LDA(At, 0, 0); PG8_STAGE(PG8_SA(1, 1), a1 + hstep, voffA);
;             PG8_WAIT_V(8); PG8_WAIT_L(0); PG8_BAR; PG8_MMA(0, 0, At, B0); PG8_MMA(0, 1, At, B1); PG8_BAR; PG8_SCHED;
;             PG8_LDA(At, 0, 1); PG8_STAGE(PG8_SB(0, 0), b2, voffB); PG8_STAGE(PG8_SB(0, 1), b2 + hstep, voffB); PG8_STAGE(PG8_SA(0, 0), a2, voffA);
.LBB0_61:
	s_ashr_i32 s23, s22, 31
	s_lshl_b64 s[44:45], s[22:23], 17
	s_add_u32 s44, s0, s44
	s_addc_u32 s45, s1, s45
	s_and_b64 s[58:59], s[6:7], exec
	s_cselect_b32 s87, s45, s81
	s_cselect_b32 s86, s44, s80
	s_ashr_i32 s21, s20, 31
	s_lshl_b64 s[58:59], s[20:21], 17
	s_add_u32 s58, s2, s58
	s_addc_u32 s59, s26, s59
	s_and_b64 s[70:71], s[6:7], exec
	s_cselect_b32 s85, s59, s83
	s_cselect_b32 s84, s58, s82
	s_add_i32 s62, 0, 0x10000
	s_add_i32 s55, 0, 0x14000
	v_add_u32_e32 v204, s62, v140
	v_add_u32_e32 v205, s55, v140
	ds_read_b128 v[0:3], v204
	ds_read_b128 v[4:7], v204 offset:1024
	ds_read_b128 v[8:11], v204 offset:2048
	ds_read_b128 v[12:15], v204 offset:3072
	ds_read_b128 v[16:19], v205
	ds_read_b128 v[20:23], v205 offset:1024
	ds_read_b128 v[24:27], v205 offset:2048
	ds_read_b128 v[28:31], v205 offset:3072
	v_mov_b64_e32 v[228:229], 0xff
	v_mov_b64_e32 v[200:201], 0x100
	v_mov_b64_e32 v[198:199], 0x1ff
	v_mov_b64_e32 v[252:253], 0x200
	s_add_u32 s72, s80, 0x10080
	s_addc_u32 s73, s81, 0
	s_add_i32 s71, s35, 0xc000
	v_lshl_add_u64 v[64:65], s[72:73], 0, v[128:129]
	s_mov_b32 m0, s71
	s_add_i32 s21, s35, 0xe000
	ds_read_b128 v[32:35], v141
	ds_read_b128 v[36:39], v141 offset:1024
	ds_read_b128 v[40:43], v141 offset:2048
	ds_read_b128 v[44:47], v141 offset:3072
	ds_read_b128 v[48:51], v141 offset:4096
	ds_read_b128 v[52:55], v141 offset:5120
	ds_read_b128 v[56:59], v141 offset:6144
	ds_read_b128 v[60:63], v141 offset:7168
	global_load_lds_dwordx4 v[64:65], off
	v_lshl_add_u64 v[64:65], s[72:73], 0, v[130:131]
	s_mov_b32 m0, s21
	s_nop 0
	global_load_lds_dwordx4 v[64:65], off
	s_waitcnt vmcnt(8)
	s_waitcnt lgkmcnt(0)
	s_barrier
	s_waitcnt lgkmcnt(0)
	v_mfma_f32_16x16x32_bf16 v[64:67], v[0:3], v[32:35], 0
	v_mfma_f32_16x16x32_bf16 v[68:71], v[8:11], v[32:35], 0
	v_mfma_f32_16x16x32_bf16 v[72:75], v[0:3], v[40:43], 0
	v_mfma_f32_16x16x32_bf16 v[76:79], v[8:11], v[40:43], 0
	v_mfma_f32_16x16x32_bf16 v[80:83], v[0:3], v[48:51], 0
	v_mfma_f32_16x16x32_bf16 v[84:87], v[8:11], v[48:51], 0
	v_mfma_f32_16x16x32_bf16 v[88:91], v[0:3], v[56:59], 0
	v_mfma_f32_16x16x32_bf16 v[92:95], v[8:11], v[56:59], 0
	v_mfma_f32_16x16x32_bf16 v[64:67], v[4:7], v[36:39], v[64:67]
	v_mfma_f32_16x16x32_bf16 v[68:71], v[12:15], v[36:39], v[68:71]
	v_mfma_f32_16x16x32_bf16 v[72:75], v[4:7], v[44:47], v[72:75]
	v_mfma_f32_16x16x32_bf16 v[76:79], v[12:15], v[44:47], v[76:79]
	v_mfma_f32_16x16x32_bf16 v[80:83], v[4:7], v[52:55], v[80:83]
	v_mfma_f32_16x16x32_bf16 v[84:87], v[12:15], v[52:55], v[84:87]
	v_mfma_f32_16x16x32_bf16 v[88:91], v[4:7], v[60:63], v[88:91]
	v_mfma_f32_16x16x32_bf16 v[92:95], v[12:15], v[60:63], v[92:95]
	v_mfma_f32_16x16x32_bf16 v[96:99], v[16:19], v[32:35], 0
	v_mfma_f32_16x16x32_bf16 v[32:35], v[24:27], v[32:35], 0
	v_mfma_f32_16x16x32_bf16 v[96:99], v[20:23], v[36:39], v[96:99]
	v_mfma_f32_16x16x32_bf16 v[32:35], v[28:31], v[36:39], v[32:35]
	v_mfma_f32_16x16x32_bf16 v[36:39], v[16:19], v[40:43], 0
	v_mfma_f32_16x16x32_bf16 v[40:43], v[24:27], v[40:43], 0
	v_mfma_f32_16x16x32_bf16 v[36:39], v[20:23], v[44:47], v[36:39]
	v_mfma_f32_16x16x32_bf16 v[40:43], v[28:31], v[44:47], v[40:43]
	v_mfma_f32_16x16x32_bf16 v[44:47], v[16:19], v[48:51], 0
	v_mfma_f32_16x16x32_bf16 v[48:51], v[24:27], v[48:51], 0
	v_mfma_f32_16x16x32_bf16 v[44:47], v[20:23], v[52:55], v[44:47]
	v_mfma_f32_16x16x32_bf16 v[48:51], v[28:31], v[52:55], v[48:51]
	v_mfma_f32_16x16x32_bf16 v[52:55], v[16:19], v[56:59], 0
	v_mfma_f32_16x16x32_bf16 v[56:59], v[24:27], v[56:59], 0
	v_mfma_f32_16x16x32_bf16 v[52:55], v[20:23], v[60:63], v[52:55]
	v_mfma_f32_16x16x32_bf16 v[56:59], v[28:31], v[60:63], v[56:59]
	s_barrier
	s_add_i32 s62, s62, s34
	v_lshl_add_u64 v[138:139], s[82:83], 0, v[192:193]
	s_mov_b64 s[74:75], 0x100
	s_add_i32 s23, s62, 0x2000
	v_lshl_add_u64 v[134:135], v[138:139], 0, s[74:75]
	s_mov_b32 m0, s62
	v_lshl_add_u64 v[190:191], s[82:83], 0, v[132:133]
	s_add_u32 s72, s82, 0x10100
	ds_read_b128 v[60:63], v141 offset:16384
	ds_read_b128 v[100:103], v141 offset:17408
	ds_read_b128 v[104:107], v141 offset:18432
	ds_read_b128 v[108:111], v141 offset:19456
	ds_read_b128 v[112:115], v141 offset:20480
	ds_read_b128 v[116:119], v141 offset:21504
	ds_read_b128 v[120:123], v141 offset:22528
	ds_read_b128 v[124:127], v141 offset:23552
	global_load_lds_dwordx4 v[134:135], off
	v_lshl_add_u64 v[134:135], v[190:191], 0, s[74:75]
	s_mov_b32 m0, s23
	s_addc_u32 s73, s83, 0
	s_add_i32 s55, s55, s34
	global_load_lds_dwordx4 v[134:135], off
	v_lshl_add_u64 v[134:135], s[72:73], 0, v[192:193]
	s_mov_b32 m0, s55
	s_add_i32 s60, s55, 0x2000
	global_load_lds_dwordx4 v[134:135], off
	v_lshl_add_u64 v[134:135], s[72:73], 0, v[132:133]
	s_mov_b32 m0, s60
	v_lshl_add_u64 v[194:195], s[80:81], 0, v[128:129]
	global_load_lds_dwordx4 v[134:135], off
	v_lshl_add_u64 v[134:135], v[194:195], 0, s[74:75]
	s_mov_b32 m0, s35
	v_lshl_add_u64 v[196:197], s[80:81], 0, v[130:131]
	global_load_lds_dwordx4 v[134:135], off
	v_lshl_add_u64 v[134:135], v[196:197], 0, s[74:75]
	s_mov_b32 m0, s38
	s_nop 0
	global_load_lds_dwordx4 v[134:135], off
	s_waitcnt vmcnt(8)
	s_waitcnt lgkmcnt(0)
	s_barrier
; #define PG8_STAGE(bufoff, gbase, voff) do { _Pragma("unroll") for (int _i = 0; _i < 2; ++_i) \
;         __builtin_amdgcn_global_load_lds((const unsigned*)((const char*)(gbase) + (voff)[_i]), (PG8_LAS unsigned*)(lds + (bufoff) + ldsw + _i * 8192), 16, 0, 0); } while (0)
; #define PG8_LDA(dst, b, h) do { _Pragma("unroll") for (int m = 0; m < 4; ++m) _Pragma("unroll") for (int k = 0; k < 2; ++k) dst[m][k] = *(const PG8_LAS bf16x8*)(lds + PG8_SA(b, h) + aoff + m * 2048 + k * 1024); } while (0)
; #define PG8_LDB(dst, b, h) do { _Pragma("unroll") for (int n = 0; n < 2; ++n) _Pragma("unroll") for (int k = 0; k < 2; ++k) dst[n][k] = *(const PG8_LAS bf16x8*)(lds + PG8_SB(b, h) + boff + n * 2048 + k * 1024); } while (0)
; #define PG8_MMA(ai, bj, At, Bt) do { __builtin_amdgcn_s_setprio(1); _Pragma("unroll") for (int m = 0; m < 4; ++m) _Pragma("unroll") for (int n = 0; n < 2; ++n) _Pragma("unroll") for (int k = 0; k < 2; ++k) \
;         acc[ai][bj][m][n] = __builtin_amdgcn_mfma_f32_16x16x32_bf16(Bt[n][k], At[m][k], acc[ai][bj][m][n], 0, 0, 0); __builtin_amdgcn_s_setprio(0); } while (0)
; #define PG8_WAIT_V(n) asm volatile("s_waitcnt vmcnt(" #n ")" ::: "memory")
; #define PG8_WAIT_L(n) asm volatile("s_waitcnt lgkmcnt(" #n ")" ::: "memory")
; #define PG8_BAR __builtin_amdgcn_s_barrier()
; #define PG8_SCHED __builtin_amdgcn_sched_barrier(0)
; template <class Epi, class Sched, bool ALIGN_EPI = false, bool SP2 = false>
; __device__ __forceinline__ void gemm_phase(PG8_LAS unsigned char* lds, const Gemm g, const Sched& S, const Epi& E, const int tid) {
;     ...
;             PG8_WAIT_V(8); PG8_WAIT_L(0); PG8_BAR; PG8_MMA(1, 0, At, B0); PG8_MMA(1, 1, At, B1); PG8_BAR; PG8_SCHED;
;             PG8_LDB(B0, 1, 0); PG8_LDB(B1, 1, 1); PG8_SCHED; PG8_LDA(At, 1, 0); PG8_STAGE(PG8_SA(0, 1), a2 + hstep, voffA);
;             PG8_WAIT_V(8); PG8_WAIT_L(0); PG8_BAR; PG8_MMA(0, 0, At, B0); PG8_MMA(0, 1, At, B1); PG8_BAR; PG8_SCHED;
	s_waitcnt lgkmcnt(0)
	v_mfma_f32_16x16x32_bf16 v[134:137], v[0:3], v[60:63], 0
	v_mfma_f32_16x16x32_bf16 v[146:149], v[0:3], v[104:107], 0
	v_mfma_f32_16x16x32_bf16 v[154:157], v[0:3], v[112:115], 0
	v_mfma_f32_16x16x32_bf16 v[0:3], v[0:3], v[120:123], 0
	v_mfma_f32_16x16x32_bf16 v[134:137], v[4:7], v[100:103], v[134:137]
	v_mfma_f32_16x16x32_bf16 v[146:149], v[4:7], v[108:111], v[146:149]
	v_mfma_f32_16x16x32_bf16 v[154:157], v[4:7], v[116:119], v[154:157]
	v_mfma_f32_16x16x32_bf16 v[0:3], v[4:7], v[124:127], v[0:3]
	v_mfma_f32_16x16x32_bf16 v[4:7], v[8:11], v[120:123], 0
	v_mfma_f32_16x16x32_bf16 v[142:145], v[8:11], v[60:63], 0
	v_mfma_f32_16x16x32_bf16 v[150:153], v[8:11], v[104:107], 0
	v_mfma_f32_16x16x32_bf16 v[158:161], v[8:11], v[112:115], 0
	v_mfma_f32_16x16x32_bf16 v[4:7], v[12:15], v[124:127], v[4:7]
	v_mfma_f32_16x16x32_bf16 v[142:145], v[12:15], v[100:103], v[142:145]
	v_mfma_f32_16x16x32_bf16 v[150:153], v[12:15], v[108:111], v[150:153]
	v_mfma_f32_16x16x32_bf16 v[158:161], v[12:15], v[116:119], v[158:161]
	v_mfma_f32_16x16x32_bf16 v[8:11], v[16:19], v[60:63], 0
	v_mfma_f32_16x16x32_bf16 v[12:15], v[24:27], v[60:63], 0
	v_mfma_f32_16x16x32_bf16 v[8:11], v[20:23], v[100:103], v[8:11]
	v_mfma_f32_16x16x32_bf16 v[12:15], v[28:31], v[100:103], v[12:15]
	v_mfma_f32_16x16x32_bf16 v[60:63], v[16:19], v[104:107], 0
	v_mfma_f32_16x16x32_bf16 v[100:103], v[24:27], v[104:107], 0
	v_mfma_f32_16x16x32_bf16 v[104:107], v[16:19], v[112:115], 0
	v_mfma_f32_16x16x32_bf16 v[16:19], v[16:19], v[120:123], 0
	v_mfma_f32_16x16x32_bf16 v[60:63], v[20:23], v[108:111], v[60:63]
	v_mfma_f32_16x16x32_bf16 v[100:103], v[28:31], v[108:111], v[100:103]
	v_mfma_f32_16x16x32_bf16 v[104:107], v[20:23], v[116:119], v[104:107]
	v_mfma_f32_16x16x32_bf16 v[108:111], v[24:27], v[112:115], 0
	v_mfma_f32_16x16x32_bf16 v[16:19], v[20:23], v[124:127], v[16:19]
	v_mfma_f32_16x16x32_bf16 v[20:23], v[24:27], v[120:123], 0
	v_mfma_f32_16x16x32_bf16 v[108:111], v[28:31], v[116:119], v[108:111]
	v_mfma_f32_16x16x32_bf16 v[20:23], v[28:31], v[124:127], v[20:23]
	s_barrier
	s_add_i32 s74, 0, 0x18000
	s_add_i32 s75, 0, 0x1c000
	v_add_u32_e32 v206, s74, v140
	v_add_u32_e32 v207, s75, v140
	ds_read_b128 v[24:27], v206
	ds_read_b128 v[28:31], v206 offset:1024
	ds_read_b128 v[112:115], v206 offset:2048
	ds_read_b128 v[116:119], v206 offset:3072
	ds_read_b128 v[120:123], v207
	ds_read_b128 v[124:127], v207 offset:1024
	ds_read_b128 v[162:165], v207 offset:2048
	ds_read_b128 v[166:169], v207 offset:3072
	s_add_u32 s72, s80, 0x10100
	s_addc_u32 s73, s81, 0
	s_mov_b32 m0, s40
	v_lshl_add_u64 v[202:203], s[72:73], 0, v[128:129]
	ds_read_b128 v[170:173], v141 offset:32768
	ds_read_b128 v[174:177], v141 offset:33792
	ds_read_b128 v[178:181], v141 offset:34816
	ds_read_b128 v[182:185], v141 offset:35840
	ds_read_b128 v[186:189], v141 offset:36864
	ds_read_b128 v[212:215], v141 offset:37888
	ds_read_b128 v[216:219], v141 offset:38912
	ds_read_b128 v[232:235], v141 offset:39936
	global_load_lds_dwordx4 v[202:203], off
	v_lshl_add_u64 v[202:203], s[72:73], 0, v[130:131]
	s_mov_b32 m0, s41
	s_nop 0
	global_load_lds_dwordx4 v[202:203], off
	s_waitcnt vmcnt(8)
	s_waitcnt lgkmcnt(0)
	s_barrier
	s_waitcnt lgkmcnt(0)
	v_mfma_f32_16x16x32_bf16 v[64:67], v[24:27], v[170:173], v[64:67]
	v_mfma_f32_16x16x32_bf16 v[68:71], v[112:115], v[170:173], v[68:71]
	v_mfma_f32_16x16x32_bf16 v[72:75], v[24:27], v[178:181], v[72:75]
	v_mfma_f32_16x16x32_bf16 v[76:79], v[112:115], v[178:181], v[76:79]
	v_mfma_f32_16x16x32_bf16 v[80:83], v[24:27], v[186:189], v[80:83]
	v_mfma_f32_16x16x32_bf16 v[84:87], v[112:115], v[186:189], v[84:87]
	v_mfma_f32_16x16x32_bf16 v[88:91], v[24:27], v[216:219], v[88:91]
	v_mfma_f32_16x16x32_bf16 v[92:95], v[112:115], v[216:219], v[92:95]
	v_mfma_f32_16x16x32_bf16 v[64:67], v[28:31], v[174:177], v[64:67]
	v_mfma_f32_16x16x32_bf16 v[68:71], v[116:119], v[174:177], v[68:71]
	v_mfma_f32_16x16x32_bf16 v[72:75], v[28:31], v[182:185], v[72:75]
	v_mfma_f32_16x16x32_bf16 v[76:79], v[116:119], v[182:185], v[76:79]
	v_mfma_f32_16x16x32_bf16 v[80:83], v[28:31], v[212:215], v[80:83]
	v_mfma_f32_16x16x32_bf16 v[84:87], v[116:119], v[212:215], v[84:87]
	v_mfma_f32_16x16x32_bf16 v[88:91], v[28:31], v[232:235], v[88:91]
	v_mfma_f32_16x16x32_bf16 v[92:95], v[116:119], v[232:235], v[92:95]
	v_mfma_f32_16x16x32_bf16 v[96:99], v[120:123], v[170:173], v[96:99]
	v_mfma_f32_16x16x32_bf16 v[32:35], v[162:165], v[170:173], v[32:35]
	v_mfma_f32_16x16x32_bf16 v[36:39], v[120:123], v[178:181], v[36:39]
	v_mfma_f32_16x16x32_bf16 v[40:43], v[162:165], v[178:181], v[40:43]
	v_mfma_f32_16x16x32_bf16 v[44:47], v[120:123], v[186:189], v[44:47]
	v_mfma_f32_16x16x32_bf16 v[48:51], v[162:165], v[186:189], v[48:51]
	v_mfma_f32_16x16x32_bf16 v[52:55], v[120:123], v[216:219], v[52:55]
	v_mfma_f32_16x16x32_bf16 v[56:59], v[162:165], v[216:219], v[56:59]
	v_mfma_f32_16x16x32_bf16 v[96:99], v[124:127], v[174:177], v[96:99]
	v_mfma_f32_16x16x32_bf16 v[32:35], v[166:169], v[174:177], v[32:35]
	v_mfma_f32_16x16x32_bf16 v[36:39], v[124:127], v[182:185], v[36:39]
	v_mfma_f32_16x16x32_bf16 v[40:43], v[166:169], v[182:185], v[40:43]
	v_mfma_f32_16x16x32_bf16 v[44:47], v[124:127], v[212:215], v[44:47]
	v_mfma_f32_16x16x32_bf16 v[48:51], v[166:169], v[212:215], v[48:51]
	v_mfma_f32_16x16x32_bf16 v[52:55], v[124:127], v[232:235], v[52:55]
	v_mfma_f32_16x16x32_bf16 v[56:59], v[166:169], v[232:235], v[56:59]
	s_barrier
; #define PG8_STAGE(bufoff, gbase, voff) do { _Pragma("unroll") for (int _i = 0; _i < 2; ++_i) \
;         __builtin_amdgcn_global_load_lds((const unsigned*)((const char*)(gbase) + (voff)[_i]), (PG8_LAS unsigned*)(lds + (bufoff) + ldsw + _i * 8192), 16, 0, 0); } while (0)
; #define PG8_LDA(dst, b, h) do { _Pragma("unroll") for (int m = 0; m < 4; ++m) _Pragma("unroll") for (int k = 0; k < 2; ++k) dst[m][k] = *(const PG8_LAS bf16x8*)(lds + PG8_SA(b, h) + aoff + m * 2048 + k * 1024); } while (0)
; #define PG8_LDB(dst, b, h) do { _Pragma("unroll") for (int n = 0; n < 2; ++n) _Pragma("unroll") for (int k = 0; k < 2; ++k) dst[n][k] = *(const PG8_LAS bf16x8*)(lds + PG8_SB(b, h) + boff + n * 2048 + k * 1024); } while (0)
; #define PG8_MMA(ai, bj, At, Bt) do { __builtin_amdgcn_s_setprio(1); _Pragma("unroll") for (int m = 0; m < 4; ++m) _Pragma("unroll") for (int n = 0; n < 2; ++n) _Pragma("unroll") for (int k = 0; k < 2; ++k) \
;         acc[ai][bj][m][n] = __builtin_amdgcn_mfma_f32_16x16x32_bf16(Bt[n][k], At[m][k], acc[ai][bj][m][n], 0, 0, 0); __builtin_amdgcn_s_setprio(0); } while (0)
; #define PG8_BAR __builtin_amdgcn_s_barrier()
; template <class Epi, class Sched, bool ALIGN_EPI = false, bool SP2 = false>
; __device__ __forceinline__ void gemm_phase(PG8_LAS unsigned char* lds, const Gemm g, const Sched& S, const Epi& E, const int tid) {
;     ...
;             PG8_LDB(B0, 0, 0); PG8_LDB(B1, 0, 1); PG8_SCHED; PG8_LDA(At, 0, 0); PG8_STAGE(PG8_SA(1, 1), a1 + hstep, voffA);
;             PG8_WAIT_V(8); PG8_WAIT_L(0); PG8_BAR; PG8_MMA(0, 0, At, B0); PG8_MMA(0, 1, At, B1); PG8_BAR; PG8_SCHED;
;             PG8_LDA(At, 0, 1); PG8_STAGE(PG8_SB(0, 0), b2, voffB); PG8_STAGE(PG8_SB(0, 1), b2 + hstep, voffB); PG8_STAGE(PG8_SA(0, 0), a2, voffA);
;             PG8_WAIT_V(8); PG8_WAIT_L(0); PG8_BAR; PG8_MMA(1, 0, At, B0); PG8_MMA(1, 1, At, B1); PG8_BAR; PG8_SCHED;
;             PG8_LDB(B0, 1, 0); PG8_LDB(B1, 1, 1); PG8_SCHED; PG8_LDA(At, 1, 0); PG8_STAGE(PG8_SA(0, 1), a2 + hstep, voffA);
;             PG8_WAIT_V(8); PG8_WAIT_L(0); PG8_BAR; PG8_MMA(0, 0, At, B0); PG8_MMA(0, 1, At, B1); PG8_BAR; PG8_SCHED;
;             PG8_LDA(At, 1, 1); PG8_STAGE(PG8_SB(1, 0), b3, voffB); PG8_STAGE(PG8_SB(1, 1), b3 + hstep, voffB); PG8_STAGE(PG8_SA(1, 0), a3, voffA);
;             PG8_WAIT_V(8); PG8_WAIT_L(0); PG8_BAR; PG8_MMA(1, 0, At, B0); PG8_MMA(1, 1, At, B1); PG8_BAR; PG8_SCHED;
	s_add_i32 s74, s74, s34
	s_mov_b64 s[88:89], 0x180
	s_add_i32 s70, s74, 0x2000
	v_lshl_add_u64 v[138:139], v[138:139], 0, s[88:89]
	s_mov_b32 m0, s74
	s_add_u32 s76, s82, 0x10180
	ds_read_b128 v[170:173], v141 offset:49152
	ds_read_b128 v[174:177], v141 offset:50176
	ds_read_b128 v[178:181], v141 offset:51200
	ds_read_b128 v[182:185], v141 offset:52224
	ds_read_b128 v[186:189], v141 offset:53248
	ds_read_b128 v[212:215], v141 offset:54272
	ds_read_b128 v[216:219], v141 offset:55296
	ds_read_b128 v[232:235], v141 offset:56320
	global_load_lds_dwordx4 v[138:139], off
	v_lshl_add_u64 v[138:139], v[190:191], 0, s[88:89]
	s_mov_b32 m0, s70
	s_addc_u32 s77, s83, 0
	s_add_i32 s72, s75, s34
	global_load_lds_dwordx4 v[138:139], off
	v_lshl_add_u64 v[138:139], s[76:77], 0, v[192:193]
	s_mov_b32 m0, s72
	s_add_i32 s73, s72, 0x2000
	global_load_lds_dwordx4 v[138:139], off
	v_lshl_add_u64 v[138:139], s[76:77], 0, v[132:133]
	s_mov_b32 m0, s73
	s_nop 0
	global_load_lds_dwordx4 v[138:139], off
	v_lshl_add_u64 v[138:139], v[194:195], 0, s[88:89]
	s_mov_b32 m0, s46
	s_nop 0
	global_load_lds_dwordx4 v[138:139], off
	v_lshl_add_u64 v[138:139], v[196:197], 0, s[88:89]
	s_mov_b32 m0, s47
	s_nop 0
	global_load_lds_dwordx4 v[138:139], off
	s_waitcnt vmcnt(8)
	s_waitcnt lgkmcnt(0)
	s_barrier
	s_waitcnt lgkmcnt(0)
	v_mfma_f32_16x16x32_bf16 v[0:3], v[24:27], v[216:219], v[0:3]
	v_mfma_f32_16x16x32_bf16 v[4:7], v[112:115], v[216:219], v[4:7]
	v_mfma_f32_16x16x32_bf16 v[134:137], v[24:27], v[170:173], v[134:137]
	v_mfma_f32_16x16x32_bf16 v[142:145], v[112:115], v[170:173], v[142:145]
	v_mfma_f32_16x16x32_bf16 v[146:149], v[24:27], v[178:181], v[146:149]
	v_mfma_f32_16x16x32_bf16 v[150:153], v[112:115], v[178:181], v[150:153]
	v_mfma_f32_16x16x32_bf16 v[154:157], v[24:27], v[186:189], v[154:157]
	v_mfma_f32_16x16x32_bf16 v[158:161], v[112:115], v[186:189], v[158:161]
	v_mfma_f32_16x16x32_bf16 v[0:3], v[28:31], v[232:235], v[0:3]
	v_mfma_f32_16x16x32_bf16 v[4:7], v[116:119], v[232:235], v[4:7]
	v_mfma_f32_16x16x32_bf16 v[134:137], v[28:31], v[174:177], v[134:137]
	v_mfma_f32_16x16x32_bf16 v[142:145], v[116:119], v[174:177], v[142:145]
	v_mfma_f32_16x16x32_bf16 v[146:149], v[28:31], v[182:185], v[146:149]
	v_mfma_f32_16x16x32_bf16 v[150:153], v[116:119], v[182:185], v[150:153]
	v_mfma_f32_16x16x32_bf16 v[154:157], v[28:31], v[212:215], v[154:157]
	v_mfma_f32_16x16x32_bf16 v[158:161], v[116:119], v[212:215], v[158:161]
	v_mfma_f32_16x16x32_bf16 v[8:11], v[120:123], v[170:173], v[8:11]
	v_mfma_f32_16x16x32_bf16 v[12:15], v[162:165], v[170:173], v[12:15]
	v_mfma_f32_16x16x32_bf16 v[24:27], v[120:123], v[178:181], v[60:63]
	v_mfma_f32_16x16x32_bf16 v[28:31], v[162:165], v[178:181], v[100:103]
	v_mfma_f32_16x16x32_bf16 v[60:63], v[120:123], v[186:189], v[104:107]
	v_mfma_f32_16x16x32_bf16 v[100:103], v[162:165], v[186:189], v[108:111]
	v_mfma_f32_16x16x32_bf16 v[16:19], v[120:123], v[216:219], v[16:19]
	v_mfma_f32_16x16x32_bf16 v[20:23], v[162:165], v[216:219], v[20:23]
	v_mfma_f32_16x16x32_bf16 v[8:11], v[124:127], v[174:177], v[8:11]
	v_mfma_f32_16x16x32_bf16 v[12:15], v[166:169], v[174:177], v[12:15]
	v_mfma_f32_16x16x32_bf16 v[24:27], v[124:127], v[182:185], v[24:27]
	v_mfma_f32_16x16x32_bf16 v[28:31], v[166:169], v[182:185], v[28:31]
	v_mfma_f32_16x16x32_bf16 v[60:63], v[124:127], v[212:215], v[60:63]
	v_mfma_f32_16x16x32_bf16 v[100:103], v[166:169], v[212:215], v[100:103]
	v_mfma_f32_16x16x32_bf16 v[16:19], v[124:127], v[232:235], v[16:19]
	v_mfma_f32_16x16x32_bf16 v[20:23], v[166:169], v[232:235], v[20:23]
	s_barrier
	ds_read_b128 v[104:107], v204
	ds_read_b128 v[108:111], v204 offset:1024
	ds_read_b128 v[112:115], v204 offset:2048
	ds_read_b128 v[116:119], v204 offset:3072
	ds_read_b128 v[120:123], v205
	ds_read_b128 v[124:127], v205 offset:1024
	ds_read_b128 v[162:165], v205 offset:2048
	ds_read_b128 v[166:169], v205 offset:3072
	s_add_u32 s76, s80, 0x10180
	s_addc_u32 s77, s81, 0
	s_mov_b32 m0, s71
	v_lshl_add_u64 v[138:139], s[76:77], 0, v[128:129]
	ds_read_b128 v[170:173], v141
	ds_read_b128 v[174:177], v141 offset:1024
	ds_read_b128 v[178:181], v141 offset:2048
	ds_read_b128 v[182:185], v141 offset:3072
	ds_read_b128 v[186:189], v141 offset:4096
	ds_read_b128 v[212:215], v141 offset:5120
	ds_read_b128 v[216:219], v141 offset:6144
	ds_read_b128 v[232:235], v141 offset:7168
	global_load_lds_dwordx4 v[138:139], off
	v_lshl_add_u64 v[138:139], s[76:77], 0, v[130:131]
	s_mov_b32 m0, s21
	s_nop 0
	global_load_lds_dwordx4 v[138:139], off
	s_waitcnt vmcnt(8)
	s_waitcnt lgkmcnt(0)
	s_barrier
; #define PG8_STAGE(bufoff, gbase, voff) do { _Pragma("unroll") for (int _i = 0; _i < 2; ++_i) \
;         __builtin_amdgcn_global_load_lds((const unsigned*)((const char*)(gbase) + (voff)[_i]), (PG8_LAS unsigned*)(lds + (bufoff) + ldsw + _i * 8192), 16, 0, 0); } while (0)
; #define PG8_LDA(dst, b, h) do { _Pragma("unroll") for (int m = 0; m < 4; ++m) _Pragma("unroll") for (int k = 0; k < 2; ++k) dst[m][k] = *(const PG8_LAS bf16x8*)(lds + PG8_SA(b, h) + aoff + m * 2048 + k * 1024); } while (0)
; #define PG8_MMA(ai, bj, At, Bt) do { __builtin_amdgcn_s_setprio(1); _Pragma("unroll") for (int m = 0; m < 4; ++m) _Pragma("unroll") for (int n = 0; n < 2; ++n) _Pragma("unroll") for (int k = 0; k < 2; ++k) \
;         acc[ai][bj][m][n] = __builtin_amdgcn_mfma_f32_16x16x32_bf16(Bt[n][k], At[m][k], acc[ai][bj][m][n], 0, 0, 0); __builtin_amdgcn_s_setprio(0); } while (0)
; #define PG8_WAIT_V(n) asm volatile("s_waitcnt vmcnt(" #n ")" ::: "memory")
; #define PG8_WAIT_L(n) asm volatile("s_waitcnt lgkmcnt(" #n ")" ::: "memory")
; #define PG8_BAR __builtin_amdgcn_s_barrier()
; #define PG8_SCHED __builtin_amdgcn_sched_barrier(0)
; template <class Epi, class Sched, bool ALIGN_EPI = false, bool SP2 = false>
; __device__ __forceinline__ void gemm_phase(PG8_LAS unsigned char* lds, const Gemm g, const Sched& S, const Epi& E, const int tid) {
;     ...
;             PG8_WAIT_V(8); PG8_WAIT_L(0); PG8_BAR; PG8_MMA(0, 0, At, B0); PG8_MMA(0, 1, At, B1); PG8_BAR; PG8_SCHED;
;             PG8_LDA(At, 0, 1); PG8_STAGE(PG8_SB(0, 0), b2, voffB); PG8_STAGE(PG8_SB(0, 1), b2 + hstep, voffB); PG8_STAGE(PG8_SA(0, 0), a2, voffA);
;             PG8_WAIT_V(8); PG8_WAIT_L(0); PG8_BAR; PG8_MMA(1, 0, At, B0); PG8_MMA(1, 1, At, B1); PG8_BAR; PG8_SCHED;
	s_waitcnt lgkmcnt(0)
	v_mfma_f32_16x16x32_bf16 v[64:67], v[104:107], v[170:173], v[64:67]
	v_mfma_f32_16x16x32_bf16 v[68:71], v[112:115], v[170:173], v[68:71]
	v_mfma_f32_16x16x32_bf16 v[72:75], v[104:107], v[178:181], v[72:75]
	v_mfma_f32_16x16x32_bf16 v[76:79], v[112:115], v[178:181], v[76:79]
	v_mfma_f32_16x16x32_bf16 v[80:83], v[104:107], v[186:189], v[80:83]
	v_mfma_f32_16x16x32_bf16 v[84:87], v[112:115], v[186:189], v[84:87]
	v_mfma_f32_16x16x32_bf16 v[88:91], v[104:107], v[216:219], v[88:91]
	v_mfma_f32_16x16x32_bf16 v[64:67], v[108:111], v[174:177], v[64:67]
	v_mfma_f32_16x16x32_bf16 v[68:71], v[116:119], v[174:177], v[68:71]
	v_mfma_f32_16x16x32_bf16 v[72:75], v[108:111], v[182:185], v[72:75]
	v_mfma_f32_16x16x32_bf16 v[76:79], v[116:119], v[182:185], v[76:79]
	v_mfma_f32_16x16x32_bf16 v[80:83], v[108:111], v[212:215], v[80:83]
	v_mfma_f32_16x16x32_bf16 v[84:87], v[116:119], v[212:215], v[84:87]
	v_mfma_f32_16x16x32_bf16 v[236:239], v[108:111], v[232:235], v[88:91]
	v_mfma_f32_16x16x32_bf16 v[88:91], v[112:115], v[216:219], v[92:95]
	v_mfma_f32_16x16x32_bf16 v[240:243], v[116:119], v[232:235], v[88:91]
	v_mfma_f32_16x16x32_bf16 v[88:91], v[120:123], v[170:173], v[96:99]
	v_mfma_f32_16x16x32_bf16 v[32:35], v[162:165], v[170:173], v[32:35]
	v_mfma_f32_16x16x32_bf16 v[36:39], v[120:123], v[178:181], v[36:39]
	v_mfma_f32_16x16x32_bf16 v[40:43], v[162:165], v[178:181], v[40:43]
	v_mfma_f32_16x16x32_bf16 v[44:47], v[120:123], v[186:189], v[44:47]
	v_mfma_f32_16x16x32_bf16 v[48:51], v[162:165], v[186:189], v[48:51]
	v_mfma_f32_16x16x32_bf16 v[52:55], v[120:123], v[216:219], v[52:55]
	v_mfma_f32_16x16x32_bf16 v[56:59], v[162:165], v[216:219], v[56:59]
	v_mfma_f32_16x16x32_bf16 v[96:99], v[124:127], v[174:177], v[88:91]
	v_mfma_f32_16x16x32_bf16 v[32:35], v[166:169], v[174:177], v[32:35]
	v_mfma_f32_16x16x32_bf16 v[36:39], v[124:127], v[182:185], v[36:39]
	v_mfma_f32_16x16x32_bf16 v[40:43], v[166:169], v[182:185], v[40:43]
	v_mfma_f32_16x16x32_bf16 v[44:47], v[124:127], v[212:215], v[44:47]
	v_mfma_f32_16x16x32_bf16 v[48:51], v[166:169], v[212:215], v[48:51]
	v_mfma_f32_16x16x32_bf16 v[52:55], v[124:127], v[232:235], v[52:55]
	v_mfma_f32_16x16x32_bf16 v[56:59], v[166:169], v[232:235], v[56:59]
	s_barrier
	s_mov_b32 m0, s62
	v_lshl_add_u64 v[138:139], s[84:85], 0, v[192:193]
	s_add_u32 s76, s84, 0x10000
	ds_read_b128 v[88:91], v141 offset:16384
	ds_read_b128 v[92:95], v141 offset:17408
	ds_read_b128 v[170:173], v141 offset:18432
	ds_read_b128 v[174:177], v141 offset:19456
	ds_read_b128 v[178:181], v141 offset:20480
	ds_read_b128 v[182:185], v141 offset:21504
	ds_read_b128 v[186:189], v141 offset:22528
	ds_read_b128 v[212:215], v141 offset:23552
	global_load_lds_dwordx4 v[138:139], off
	v_lshl_add_u64 v[190:191], s[84:85], 0, v[132:133]
	s_mov_b32 m0, s23
	s_addc_u32 s77, s85, 0
	global_load_lds_dwordx4 v[190:191], off
	v_lshl_add_u64 v[194:195], s[76:77], 0, v[192:193]
	s_mov_b32 m0, s55
	v_lshl_add_u64 v[220:221], s[86:87], 0, v[128:129]
	global_load_lds_dwordx4 v[194:195], off
	v_lshl_add_u64 v[194:195], s[76:77], 0, v[132:133]
	s_mov_b32 m0, s60
	v_lshl_add_u64 v[230:231], s[86:87], 0, v[130:131]
	global_load_lds_dwordx4 v[194:195], off
	s_mov_b32 m0, s35
	s_nop 0
	global_load_lds_dwordx4 v[220:221], off
	s_mov_b32 m0, s38
	s_nop 0
	global_load_lds_dwordx4 v[230:231], off
	s_waitcnt vmcnt(8)
	s_waitcnt lgkmcnt(0)
	s_barrier
	s_waitcnt lgkmcnt(0)
	v_mfma_f32_16x16x32_bf16 v[0:3], v[104:107], v[186:189], v[0:3]
	v_mfma_f32_16x16x32_bf16 v[4:7], v[112:115], v[186:189], v[4:7]
	v_mfma_f32_16x16x32_bf16 v[134:137], v[104:107], v[88:91], v[134:137]
	v_mfma_f32_16x16x32_bf16 v[142:145], v[112:115], v[88:91], v[142:145]
	v_mfma_f32_16x16x32_bf16 v[146:149], v[104:107], v[170:173], v[146:149]
	v_mfma_f32_16x16x32_bf16 v[150:153], v[112:115], v[170:173], v[150:153]
	v_mfma_f32_16x16x32_bf16 v[154:157], v[104:107], v[178:181], v[154:157]
	v_mfma_f32_16x16x32_bf16 v[158:161], v[112:115], v[178:181], v[158:161]
	v_mfma_f32_16x16x32_bf16 v[0:3], v[108:111], v[212:215], v[0:3]
	v_mfma_f32_16x16x32_bf16 v[4:7], v[116:119], v[212:215], v[4:7]
	v_mfma_f32_16x16x32_bf16 v[134:137], v[108:111], v[92:95], v[134:137]
	v_mfma_f32_16x16x32_bf16 v[142:145], v[116:119], v[92:95], v[142:145]
	v_mfma_f32_16x16x32_bf16 v[146:149], v[108:111], v[174:177], v[146:149]
	v_mfma_f32_16x16x32_bf16 v[150:153], v[116:119], v[174:177], v[150:153]
	v_mfma_f32_16x16x32_bf16 v[154:157], v[108:111], v[182:185], v[154:157]
	v_mfma_f32_16x16x32_bf16 v[158:161], v[116:119], v[182:185], v[158:161]
	v_mfma_f32_16x16x32_bf16 v[8:11], v[120:123], v[88:91], v[8:11]
	v_mfma_f32_16x16x32_bf16 v[216:219], v[124:127], v[92:95], v[8:11]
	v_mfma_f32_16x16x32_bf16 v[8:11], v[162:165], v[88:91], v[12:15]
	v_mfma_f32_16x16x32_bf16 v[232:235], v[166:169], v[92:95], v[8:11]
	v_mfma_f32_16x16x32_bf16 v[8:11], v[120:123], v[170:173], v[24:27]
	v_mfma_f32_16x16x32_bf16 v[244:247], v[124:127], v[174:177], v[8:11]
	v_mfma_f32_16x16x32_bf16 v[8:11], v[162:165], v[170:173], v[28:31]
	v_mfma_f32_16x16x32_bf16 v[170:173], v[166:169], v[174:177], v[8:11]
	v_mfma_f32_16x16x32_bf16 v[8:11], v[120:123], v[178:181], v[60:63]
	v_mfma_f32_16x16x32_bf16 v[174:177], v[124:127], v[182:185], v[8:11]
	v_mfma_f32_16x16x32_bf16 v[8:11], v[162:165], v[178:181], v[100:103]
	v_mfma_f32_16x16x32_bf16 v[178:181], v[166:169], v[182:185], v[8:11]
	v_mfma_f32_16x16x32_bf16 v[8:11], v[120:123], v[186:189], v[16:19]
	v_mfma_f32_16x16x32_bf16 v[182:185], v[124:127], v[212:215], v[8:11]
	v_mfma_f32_16x16x32_bf16 v[8:11], v[162:165], v[186:189], v[20:23]
	v_mfma_f32_16x16x32_bf16 v[162:165], v[166:169], v[212:215], v[8:11]
	s_barrier
; #define PG8_STAGE(bufoff, gbase, voff) do { _Pragma("unroll") for (int _i = 0; _i < 2; ++_i) \
;         __builtin_amdgcn_global_load_lds((const unsigned*)((const char*)(gbase) + (voff)[_i]), (PG8_LAS unsigned*)(lds + (bufoff) + ldsw + _i * 8192), 16, 0, 0); } while (0)
; #define PG8_LDA(dst, b, h) do { _Pragma("unroll") for (int m = 0; m < 4; ++m) _Pragma("unroll") for (int k = 0; k < 2; ++k) dst[m][k] = *(const PG8_LAS bf16x8*)(lds + PG8_SA(b, h) + aoff + m * 2048 + k * 1024); } while (0)
; #define PG8_LDB(dst, b, h) do { _Pragma("unroll") for (int n = 0; n < 2; ++n) _Pragma("unroll") for (int k = 0; k < 2; ++k) dst[n][k] = *(const PG8_LAS bf16x8*)(lds + PG8_SB(b, h) + boff + n * 2048 + k * 1024); } while (0)
; #define PG8_MMA(ai, bj, At, Bt) do { __builtin_amdgcn_s_setprio(1); _Pragma("unroll") for (int m = 0; m < 4; ++m) _Pragma("unroll") for (int n = 0; n < 2; ++n) _Pragma("unroll") for (int k = 0; k < 2; ++k) \
;         acc[ai][bj][m][n] = __builtin_amdgcn_mfma_f32_16x16x32_bf16(Bt[n][k], At[m][k], acc[ai][bj][m][n], 0, 0, 0); __builtin_amdgcn_s_setprio(0); } while (0)
; #define PG8_WAIT_V(n) asm volatile("s_waitcnt vmcnt(" #n ")" ::: "memory")
; #define PG8_WAIT_L(n) asm volatile("s_waitcnt lgkmcnt(" #n ")" ::: "memory")
; #define PG8_BAR __builtin_amdgcn_s_barrier()
; #define PG8_SCHED __builtin_amdgcn_sched_barrier(0)
; template <class Epi, class Sched, bool ALIGN_EPI = false, bool SP2 = false>
; __device__ __forceinline__ void gemm_phase(PG8_LAS unsigned char* lds, const Gemm g, const Sched& S, const Epi& E, const int tid) {
;     ...
;             PG8_LDB(B0, 1, 0); PG8_LDB(B1, 1, 1); PG8_SCHED; PG8_LDA(At, 1, 0); PG8_STAGE(PG8_SA(0, 1), a2 + hstep, voffA);
;             PG8_WAIT_V(8); PG8_WAIT_L(0); PG8_BAR; PG8_MMA(0, 0, At, B0); PG8_MMA(0, 1, At, B1); PG8_BAR; PG8_SCHED;
;             PG8_LDA(At, 1, 1); PG8_STAGE(PG8_SB(1, 0), b3, voffB); PG8_STAGE(PG8_SB(1, 1), b3 + hstep, voffB); PG8_STAGE(PG8_SA(1, 0), a3, voffA);
;             PG8_WAIT_V(8); PG8_WAIT_L(0); PG8_BAR; PG8_MMA(1, 0, At, B0); PG8_MMA(1, 1, At, B1); PG8_BAR; PG8_SCHED;
	s_nop 4
	ds_read_b128 v[8:11], v206
	ds_read_b128 v[12:15], v206 offset:1024
	ds_read_b128 v[16:19], v206 offset:2048
	ds_read_b128 v[20:23], v206 offset:3072
	ds_read_b128 v[166:169], v207
	ds_read_b128 v[186:189], v207 offset:1024
	ds_read_b128 v[212:215], v207 offset:2048
	ds_read_b128 v[248:251], v207 offset:3072
	s_add_u32 s76, s86, 0x10000
	s_addc_u32 s77, s87, 0
	s_mov_b32 m0, s40
	v_lshl_add_u64 v[88:89], s[76:77], 0, v[128:129]
	ds_read_b128 v[24:27], v141 offset:32768
	ds_read_b128 v[28:31], v141 offset:33792
	ds_read_b128 v[60:63], v141 offset:34816
	ds_read_b128 v[100:103], v141 offset:35840
	ds_read_b128 v[224:227], v141 offset:36864
	ds_read_b128 v[194:197], v141 offset:37888
	ds_read_b128 v[202:205], v141 offset:38912
	ds_read_b128 v[206:209], v141 offset:39936
	global_load_lds_dwordx4 v[88:89], off
	v_lshl_add_u64 v[88:89], s[76:77], 0, v[130:131]
	s_mov_b32 m0, s41
	s_nop 0
	global_load_lds_dwordx4 v[88:89], off
	s_waitcnt vmcnt(8)
	s_waitcnt lgkmcnt(0)
	s_barrier
	s_waitcnt lgkmcnt(0)
	v_mfma_f32_16x16x32_bf16 v[64:67], v[8:11], v[24:27], v[64:67]
	v_mfma_f32_16x16x32_bf16 v[124:127], v[12:15], v[28:31], v[64:67]
	v_mfma_f32_16x16x32_bf16 v[64:67], v[16:19], v[24:27], v[68:71]
	v_mfma_f32_16x16x32_bf16 v[120:123], v[20:23], v[28:31], v[64:67]
	v_mfma_f32_16x16x32_bf16 v[64:67], v[8:11], v[60:63], v[72:75]
	v_mfma_f32_16x16x32_bf16 v[108:111], v[12:15], v[100:103], v[64:67]
	v_mfma_f32_16x16x32_bf16 v[64:67], v[16:19], v[60:63], v[76:79]
	v_mfma_f32_16x16x32_bf16 v[104:107], v[20:23], v[100:103], v[64:67]
	v_mfma_f32_16x16x32_bf16 v[64:67], v[8:11], v[224:227], v[80:83]
	v_mfma_f32_16x16x32_bf16 v[92:95], v[12:15], v[194:197], v[64:67]
	v_mfma_f32_16x16x32_bf16 v[64:67], v[16:19], v[224:227], v[84:87]
	v_mfma_f32_16x16x32_bf16 v[88:91], v[20:23], v[194:197], v[64:67]
	v_mfma_f32_16x16x32_bf16 v[64:67], v[8:11], v[202:205], v[236:239]
	v_mfma_f32_16x16x32_bf16 v[76:79], v[12:15], v[206:209], v[64:67]
	v_mfma_f32_16x16x32_bf16 v[64:67], v[16:19], v[202:205], v[240:243]
	v_mfma_f32_16x16x32_bf16 v[72:75], v[20:23], v[206:209], v[64:67]
	v_mfma_f32_16x16x32_bf16 v[64:67], v[166:169], v[24:27], v[96:99]
	v_mfma_f32_16x16x32_bf16 v[24:27], v[212:215], v[24:27], v[32:35]
	v_mfma_f32_16x16x32_bf16 v[116:119], v[248:251], v[28:31], v[24:27]
	v_mfma_f32_16x16x32_bf16 v[24:27], v[166:169], v[60:63], v[36:39]
	v_mfma_f32_16x16x32_bf16 v[96:99], v[186:189], v[100:103], v[24:27]
	v_mfma_f32_16x16x32_bf16 v[24:27], v[212:215], v[60:63], v[40:43]
	v_mfma_f32_16x16x32_bf16 v[100:103], v[248:251], v[100:103], v[24:27]
	v_mfma_f32_16x16x32_bf16 v[24:27], v[166:169], v[224:227], v[44:47]
	v_mfma_f32_16x16x32_bf16 v[80:83], v[186:189], v[194:197], v[24:27]
	v_mfma_f32_16x16x32_bf16 v[24:27], v[212:215], v[224:227], v[48:51]
	v_mfma_f32_16x16x32_bf16 v[84:87], v[248:251], v[194:197], v[24:27]
	v_mfma_f32_16x16x32_bf16 v[24:27], v[166:169], v[202:205], v[52:55]
	v_mfma_f32_16x16x32_bf16 v[60:63], v[186:189], v[206:209], v[24:27]
	v_mfma_f32_16x16x32_bf16 v[24:27], v[212:215], v[202:205], v[56:59]
	v_mfma_f32_16x16x32_bf16 v[112:115], v[186:189], v[28:31], v[64:67]
	v_mfma_f32_16x16x32_bf16 v[64:67], v[248:251], v[206:209], v[24:27]
	s_barrier
	s_mov_b32 m0, s74
	s_nop 2
	v_lshl_add_u64 v[24:25], v[138:139], 0, s[36:37]
	ds_read_b128 v[32:35], v141 offset:49152
	ds_read_b128 v[36:39], v141 offset:50176
	ds_read_b128 v[194:197], v141 offset:51200
	ds_read_b128 v[202:205], v141 offset:52224
	ds_read_b128 v[206:209], v141 offset:53248
	ds_read_b128 v[224:227], v141 offset:54272
	ds_read_b128 v[236:239], v141 offset:55296
	ds_read_b128 v[240:243], v141 offset:56320
	global_load_lds_dwordx4 v[24:25], off
	s_mov_b32 m0, s70
	s_add_u32 s70, s84, 0x10080
	v_lshl_add_u64 v[24:25], v[190:191], 0, s[36:37]
	s_addc_u32 s71, s85, 0
	global_load_lds_dwordx4 v[24:25], off
	v_lshl_add_u64 v[24:25], s[70:71], 0, v[192:193]
	s_mov_b32 m0, s72
	s_nop 0
	global_load_lds_dwordx4 v[24:25], off
	v_lshl_add_u64 v[24:25], s[70:71], 0, v[132:133]
	s_mov_b32 m0, s73
	s_nop 0
	global_load_lds_dwordx4 v[24:25], off
	v_lshl_add_u64 v[24:25], v[220:221], 0, s[36:37]
	s_mov_b32 m0, s46
	s_nop 0
	global_load_lds_dwordx4 v[24:25], off
	v_lshl_add_u64 v[24:25], v[230:231], 0, s[36:37]
	s_mov_b32 m0, s47
	s_nop 0
	global_load_lds_dwordx4 v[24:25], off
	s_waitcnt vmcnt(8)
	s_waitcnt lgkmcnt(0)
	s_barrier
	s_waitcnt lgkmcnt(0)
	v_mfma_f32_16x16x32_bf16 v[24:27], v[8:11], v[32:35], v[134:137]
	v_mfma_f32_16x16x32_bf16 v[68:71], v[12:15], v[36:39], v[24:27]
	v_mfma_f32_16x16x32_bf16 v[24:27], v[16:19], v[32:35], v[142:145]
	v_mfma_f32_16x16x32_bf16 v[56:59], v[20:23], v[36:39], v[24:27]
	v_mfma_f32_16x16x32_bf16 v[24:27], v[8:11], v[194:197], v[146:149]
	v_mfma_f32_16x16x32_bf16 v[44:47], v[12:15], v[202:205], v[24:27]
	v_mfma_f32_16x16x32_bf16 v[24:27], v[16:19], v[194:197], v[150:153]
	v_mfma_f32_16x16x32_bf16 v[40:43], v[20:23], v[202:205], v[24:27]
	v_mfma_f32_16x16x32_bf16 v[24:27], v[8:11], v[206:209], v[154:157]
	v_mfma_f32_16x16x32_bf16 v[0:3], v[8:11], v[236:239], v[0:3]
	v_mfma_f32_16x16x32_bf16 v[28:31], v[12:15], v[224:227], v[24:27]
	v_mfma_f32_16x16x32_bf16 v[24:27], v[16:19], v[206:209], v[158:161]
	v_mfma_f32_16x16x32_bf16 v[12:15], v[12:15], v[240:243], v[0:3]
	v_mfma_f32_16x16x32_bf16 v[0:3], v[16:19], v[236:239], v[4:7]
	v_mfma_f32_16x16x32_bf16 v[24:27], v[20:23], v[224:227], v[24:27]
	v_mfma_f32_16x16x32_bf16 v[8:11], v[20:23], v[240:243], v[0:3]
	v_mfma_f32_16x16x32_bf16 v[0:3], v[166:169], v[32:35], v[216:219]
	v_mfma_f32_16x16x32_bf16 v[48:51], v[186:189], v[36:39], v[0:3]
	v_mfma_f32_16x16x32_bf16 v[0:3], v[212:215], v[32:35], v[232:235]
	v_mfma_f32_16x16x32_bf16 v[52:55], v[248:251], v[36:39], v[0:3]
	v_mfma_f32_16x16x32_bf16 v[0:3], v[166:169], v[194:197], v[244:247]
	v_mfma_f32_16x16x32_bf16 v[32:35], v[186:189], v[202:205], v[0:3]
	v_mfma_f32_16x16x32_bf16 v[0:3], v[212:215], v[194:197], v[170:173]
	v_mfma_f32_16x16x32_bf16 v[36:39], v[248:251], v[202:205], v[0:3]
	v_mfma_f32_16x16x32_bf16 v[0:3], v[166:169], v[206:209], v[174:177]
	v_mfma_f32_16x16x32_bf16 v[16:19], v[186:189], v[224:227], v[0:3]
	v_mfma_f32_16x16x32_bf16 v[0:3], v[212:215], v[206:209], v[178:181]
	v_mfma_f32_16x16x32_bf16 v[20:23], v[248:251], v[224:227], v[0:3]
	v_mfma_f32_16x16x32_bf16 v[0:3], v[166:169], v[236:239], v[182:185]
	v_mfma_f32_16x16x32_bf16 v[4:7], v[212:215], v[236:239], v[162:165]
	v_mfma_f32_16x16x32_bf16 v[0:3], v[186:189], v[240:243], v[0:3]
	v_mfma_f32_16x16x32_bf16 v[4:7], v[248:251], v[240:243], v[4:7]
	s_barrier
	s_andn2_b64 vcc, exec, s[16:17]
	s_cbranch_vccnz .LBB0_63
	s_barrier

; #define PG8_STAGE(bufoff, gbase, voff) do { _Pragma("unroll") for (int _i = 0; _i < 2; ++_i) \
;         __builtin_amdgcn_global_load_lds((const unsigned*)((const char*)(gbase) + (voff)[_i]), (PG8_LAS unsigned*)(lds + (bufoff) + ldsw + _i * 8192), 16, 0, 0); } while (0)
; #define PG8_LDA(dst, b, h) do { _Pragma("unroll") for (int m = 0; m < 4; ++m) _Pragma("unroll") for (int k = 0; k < 2; ++k) dst[m][k] = *(const PG8_LAS bf16x8*)(lds + PG8_SA(b, h) + aoff + m * 2048 + k * 1024); } while (0)
; #define PG8_LDB(dst, b, h) do { _Pragma("unroll") for (int n = 0; n < 2; ++n) _Pragma("unroll") for (int k = 0; k < 2; ++k) dst[n][k] = *(const PG8_LAS bf16x8*)(lds + PG8_SB(b, h) + boff + n * 2048 + k * 1024); } while (0)
; #define PG8_MMA(ai, bj, At, Bt) do { __builtin_amdgcn_s_setprio(1); _Pragma("unroll") for (int m = 0; m < 4; ++m) _Pragma("unroll") for (int n = 0; n < 2; ++n) _Pragma("unroll") for (int k = 0; k < 2; ++k) \
;         acc[ai][bj][m][n] = __builtin_amdgcn_mfma_f32_16x16x32_bf16(Bt[n][k], At[m][k], acc[ai][bj][m][n], 0, 0, 0); __builtin_amdgcn_s_setprio(0); } while (0)
; #define PG8_WAIT_V(n) asm volatile("s_waitcnt vmcnt(" #n ")" ::: "memory")
; #define PG8_WAIT_L(n) asm volatile("s_waitcnt lgkmcnt(" #n ")" ::: "memory")
; #define PG8_BAR __builtin_amdgcn_s_barrier()
; #define PG8_SCHED __builtin_amdgcn_sched_barrier(0)
; template <class Epi, class Sched, bool ALIGN_EPI = false, bool SP2 = false>
; __device__ __forceinline__ void gemm_phase(PG8_LAS unsigned char* lds, const Gemm g, const Sched& S, const Epi& E, const int tid) {
;     ...
;             const bool last = (t == nt - 2);
;             const char* a1 = cA + (size_t)(t + 1) * kstep;
;             const char* a2 = last ? nA : cA + (size_t)(t + 2) * kstep; const char* b2 = last ? nB : cB + (size_t)(t + 2) * kstep;
;             const char* a3 = a2 + kstep; const char* b3 = b2 + kstep;
;             if (last && has_next) S.a_ready(nxt);
;             if constexpr (SP2) {
;             PG8_LDB(B0, 0, 0); PG8_LDB(B1, 0, 1); PG8_SCHED; PG8_LDA(At, 0, 0); PG8_STAGE(PG8_SA(1, 1), a1 + hstep, voffA);
;             PG8_WAIT_V(8); PG8_WAIT_L(0); PG8_BAR; PG8_MMA(0, 0, At, B0); PG8_MMA(0, 1, At, B1); PG8_BAR; PG8_SCHED;
;             PG8_LDA(At, 0, 1); PG8_STAGE(PG8_SB(0, 0), b2, voffB); PG8_STAGE(PG8_SB(0, 1), b2 + hstep, voffB); PG8_STAGE(PG8_SA(0, 0), a2, voffA);
.LBB0_99:
	s_add_u32 s20, s18, 0x100
	s_addc_u32 s21, s19, 0
	s_add_i32 s73, 0, 0x10000
	s_cmp_eq_u32 s72, 40
	s_cselect_b32 s45, s9, s21
	s_cselect_b32 s44, s8, s20
	s_cselect_b32 s23, s17, s71
	s_cselect_b32 s22, s16, s62
	s_add_i32 s74, 0, 0x14000
	v_add_u32_e32 v152, s73, v138
	v_add_u32_e32 v168, s74, v138
	ds_read_b128 v[140:143], v152
	ds_read_b128 v[144:147], v152 offset:1024
	ds_read_b128 v[148:151], v152 offset:2048
	ds_read_b128 v[152:155], v152 offset:3072
	ds_read_b128 v[156:159], v168
	ds_read_b128 v[160:163], v168 offset:1024
	ds_read_b128 v[164:167], v168 offset:2048
	ds_read_b128 v[168:171], v168 offset:3072
	v_lshl_add_u64 v[194:195], s[18:19], 0, v[134:135]
	s_add_i32 m0, s38, 0xc000
	ds_read_b128 v[172:175], v139
	ds_read_b128 v[176:179], v139 offset:1024
	ds_read_b128 v[180:183], v139 offset:2048
	ds_read_b128 v[184:187], v139 offset:3072
	ds_read_b128 v[188:191], v139 offset:4096
	ds_read_b128 v[212:215], v139 offset:5120
	ds_read_b128 v[216:219], v139 offset:6144
	ds_read_b128 v[232:235], v139 offset:7168
	global_load_lds_dwordx4 v[194:195], off
	v_lshl_add_u64 v[194:195], s[18:19], 0, v[136:137]
	s_add_i32 m0, s38, 0xe000
	s_nop 0
	global_load_lds_dwordx4 v[194:195], off
	s_waitcnt vmcnt(8)
	s_waitcnt lgkmcnt(0)
	s_barrier
	s_waitcnt lgkmcnt(0)
	v_mfma_f32_16x16x32_bf16 v[124:127], v[140:143], v[172:175], v[124:127]
	v_mfma_f32_16x16x32_bf16 v[120:123], v[148:151], v[172:175], v[120:123]
	v_mfma_f32_16x16x32_bf16 v[116:119], v[140:143], v[180:183], v[116:119]
	v_mfma_f32_16x16x32_bf16 v[112:115], v[148:151], v[180:183], v[112:115]
	v_mfma_f32_16x16x32_bf16 v[100:103], v[140:143], v[188:191], v[100:103]
	v_mfma_f32_16x16x32_bf16 v[96:99], v[148:151], v[188:191], v[96:99]
	v_mfma_f32_16x16x32_bf16 v[84:87], v[140:143], v[216:219], v[84:87]
	v_mfma_f32_16x16x32_bf16 v[80:83], v[148:151], v[216:219], v[80:83]
	v_mfma_f32_16x16x32_bf16 v[124:127], v[144:147], v[176:179], v[124:127]
	v_mfma_f32_16x16x32_bf16 v[120:123], v[152:155], v[176:179], v[120:123]
	v_mfma_f32_16x16x32_bf16 v[116:119], v[144:147], v[184:187], v[116:119]
	v_mfma_f32_16x16x32_bf16 v[112:115], v[152:155], v[184:187], v[112:115]
	v_mfma_f32_16x16x32_bf16 v[100:103], v[144:147], v[212:215], v[100:103]
	v_mfma_f32_16x16x32_bf16 v[96:99], v[152:155], v[212:215], v[96:99]
	v_mfma_f32_16x16x32_bf16 v[84:87], v[144:147], v[232:235], v[84:87]
	v_mfma_f32_16x16x32_bf16 v[80:83], v[152:155], v[232:235], v[80:83]
	v_mfma_f32_16x16x32_bf16 v[108:111], v[156:159], v[172:175], v[108:111]
	v_mfma_f32_16x16x32_bf16 v[104:107], v[164:167], v[172:175], v[104:107]
	v_mfma_f32_16x16x32_bf16 v[92:95], v[156:159], v[180:183], v[92:95]
	v_mfma_f32_16x16x32_bf16 v[88:91], v[164:167], v[180:183], v[88:91]
	v_mfma_f32_16x16x32_bf16 v[76:79], v[156:159], v[188:191], v[76:79]
	v_mfma_f32_16x16x32_bf16 v[72:75], v[164:167], v[188:191], v[72:75]
	v_mfma_f32_16x16x32_bf16 v[68:71], v[156:159], v[216:219], v[68:71]
	v_mfma_f32_16x16x32_bf16 v[64:67], v[164:167], v[216:219], v[64:67]
	v_mfma_f32_16x16x32_bf16 v[108:111], v[160:163], v[176:179], v[108:111]
	v_mfma_f32_16x16x32_bf16 v[104:107], v[168:171], v[176:179], v[104:107]
	v_mfma_f32_16x16x32_bf16 v[92:95], v[160:163], v[184:187], v[92:95]
	v_mfma_f32_16x16x32_bf16 v[88:91], v[168:171], v[184:187], v[88:91]
	v_mfma_f32_16x16x32_bf16 v[76:79], v[160:163], v[212:215], v[76:79]
	v_mfma_f32_16x16x32_bf16 v[72:75], v[168:171], v[212:215], v[72:75]
	v_mfma_f32_16x16x32_bf16 v[68:71], v[160:163], v[232:235], v[68:71]
	v_mfma_f32_16x16x32_bf16 v[64:67], v[168:171], v[232:235], v[64:67]
	s_barrier
	s_add_i32 s18, s73, s35
	v_lshl_add_u64 v[194:195], s[22:23], 0, v[192:193]
	s_mov_b32 m0, s18
	ds_read_b128 v[172:175], v139 offset:16384
	ds_read_b128 v[176:179], v139 offset:17408
	ds_read_b128 v[180:183], v139 offset:18432
	ds_read_b128 v[184:187], v139 offset:19456
	ds_read_b128 v[188:191], v139 offset:20480
	ds_read_b128 v[212:215], v139 offset:21504
	ds_read_b128 v[216:219], v139 offset:22528
	ds_read_b128 v[232:235], v139 offset:23552
	global_load_lds_dwordx4 v[194:195], off
	s_add_i32 m0, s18, 0x2000
	s_add_u32 s18, s22, 0xb0000
	v_lshl_add_u64 v[196:197], s[22:23], 0, v[132:133]
	s_addc_u32 s19, s23, 0
	s_add_i32 s73, s74, s35
	global_load_lds_dwordx4 v[196:197], off
	v_lshl_add_u64 v[202:203], s[18:19], 0, v[192:193]
	s_mov_b32 m0, s73
	v_lshl_add_u64 v[204:205], s[44:45], 0, v[130:131]
	global_load_lds_dwordx4 v[202:203], off
	v_lshl_add_u64 v[202:203], s[18:19], 0, v[132:133]
	s_add_i32 m0, s73, 0x2000
	s_nop 0
	global_load_lds_dwordx4 v[202:203], off
	v_lshl_add_u64 v[202:203], s[44:45], 0, v[128:129]
	s_mov_b32 m0, s38
	s_nop 0
	global_load_lds_dwordx4 v[202:203], off
	s_mov_b32 m0, s40
	s_nop 0
	global_load_lds_dwordx4 v[204:205], off
	s_waitcnt vmcnt(8)
	s_waitcnt lgkmcnt(0)
	s_barrier
; #define PG8_STAGE(bufoff, gbase, voff) do { _Pragma("unroll") for (int _i = 0; _i < 2; ++_i) \
;         __builtin_amdgcn_global_load_lds((const unsigned*)((const char*)(gbase) + (voff)[_i]), (PG8_LAS unsigned*)(lds + (bufoff) + ldsw + _i * 8192), 16, 0, 0); } while (0)
; #define PG8_LDA(dst, b, h) do { _Pragma("unroll") for (int m = 0; m < 4; ++m) _Pragma("unroll") for (int k = 0; k < 2; ++k) dst[m][k] = *(const PG8_LAS bf16x8*)(lds + PG8_SA(b, h) + aoff + m * 2048 + k * 1024); } while (0)
; #define PG8_LDB(dst, b, h) do { _Pragma("unroll") for (int n = 0; n < 2; ++n) _Pragma("unroll") for (int k = 0; k < 2; ++k) dst[n][k] = *(const PG8_LAS bf16x8*)(lds + PG8_SB(b, h) + boff + n * 2048 + k * 1024); } while (0)
; #define PG8_MMA(ai, bj, At, Bt) do { __builtin_amdgcn_s_setprio(1); _Pragma("unroll") for (int m = 0; m < 4; ++m) _Pragma("unroll") for (int n = 0; n < 2; ++n) _Pragma("unroll") for (int k = 0; k < 2; ++k) \
;         acc[ai][bj][m][n] = __builtin_amdgcn_mfma_f32_16x16x32_bf16(Bt[n][k], At[m][k], acc[ai][bj][m][n], 0, 0, 0); __builtin_amdgcn_s_setprio(0); } while (0)
; #define PG8_WAIT_V(n) asm volatile("s_waitcnt vmcnt(" #n ")" ::: "memory")
; #define PG8_WAIT_L(n) asm volatile("s_waitcnt lgkmcnt(" #n ")" ::: "memory")
; #define PG8_BAR __builtin_amdgcn_s_barrier()
; #define PG8_SCHED __builtin_amdgcn_sched_barrier(0)
; template <class Epi, class Sched, bool ALIGN_EPI = false, bool SP2 = false>
; __device__ __forceinline__ void gemm_phase(PG8_LAS unsigned char* lds, const Gemm g, const Sched& S, const Epi& E, const int tid) {
;     ...
;             PG8_WAIT_V(8); PG8_WAIT_L(0); PG8_BAR; PG8_MMA(1, 0, At, B0); PG8_MMA(1, 1, At, B1); PG8_BAR; PG8_SCHED;
;             PG8_LDB(B0, 1, 0); PG8_LDB(B1, 1, 1); PG8_SCHED; PG8_LDA(At, 1, 0); PG8_STAGE(PG8_SA(0, 1), a2 + hstep, voffA);
;             PG8_WAIT_V(8); PG8_WAIT_L(0); PG8_BAR; PG8_MMA(0, 0, At, B0); PG8_MMA(0, 1, At, B1); PG8_BAR; PG8_SCHED;
	s_waitcnt lgkmcnt(0)
	v_mfma_f32_16x16x32_bf16 v[60:63], v[140:143], v[172:175], v[60:63]
	v_mfma_f32_16x16x32_bf16 v[56:59], v[148:151], v[172:175], v[56:59]
	v_mfma_f32_16x16x32_bf16 v[52:55], v[140:143], v[180:183], v[52:55]
	v_mfma_f32_16x16x32_bf16 v[48:51], v[148:151], v[180:183], v[48:51]
	v_mfma_f32_16x16x32_bf16 v[36:39], v[140:143], v[188:191], v[36:39]
	v_mfma_f32_16x16x32_bf16 v[32:35], v[148:151], v[188:191], v[32:35]
	v_mfma_f32_16x16x32_bf16 v[20:23], v[140:143], v[216:219], v[20:23]
	v_mfma_f32_16x16x32_bf16 v[16:19], v[148:151], v[216:219], v[16:19]
	v_mfma_f32_16x16x32_bf16 v[60:63], v[144:147], v[176:179], v[60:63]
	v_mfma_f32_16x16x32_bf16 v[56:59], v[152:155], v[176:179], v[56:59]
	v_mfma_f32_16x16x32_bf16 v[52:55], v[144:147], v[184:187], v[52:55]
	v_mfma_f32_16x16x32_bf16 v[48:51], v[152:155], v[184:187], v[48:51]
	v_mfma_f32_16x16x32_bf16 v[36:39], v[144:147], v[212:215], v[36:39]
	v_mfma_f32_16x16x32_bf16 v[32:35], v[152:155], v[212:215], v[32:35]
	v_mfma_f32_16x16x32_bf16 v[20:23], v[144:147], v[232:235], v[20:23]
	v_mfma_f32_16x16x32_bf16 v[16:19], v[152:155], v[232:235], v[16:19]
	v_mfma_f32_16x16x32_bf16 v[44:47], v[156:159], v[172:175], v[44:47]
	v_mfma_f32_16x16x32_bf16 v[40:43], v[164:167], v[172:175], v[40:43]
	v_mfma_f32_16x16x32_bf16 v[28:31], v[156:159], v[180:183], v[28:31]
	v_mfma_f32_16x16x32_bf16 v[24:27], v[164:167], v[180:183], v[24:27]
	v_mfma_f32_16x16x32_bf16 v[12:15], v[156:159], v[188:191], v[12:15]
	v_mfma_f32_16x16x32_bf16 v[8:11], v[164:167], v[188:191], v[8:11]
	v_mfma_f32_16x16x32_bf16 v[4:7], v[156:159], v[216:219], v[4:7]
	v_mfma_f32_16x16x32_bf16 v[0:3], v[164:167], v[216:219], v[0:3]
	v_mfma_f32_16x16x32_bf16 v[44:47], v[160:163], v[176:179], v[44:47]
	v_mfma_f32_16x16x32_bf16 v[40:43], v[168:171], v[176:179], v[40:43]
	v_mfma_f32_16x16x32_bf16 v[28:31], v[160:163], v[184:187], v[28:31]
	v_mfma_f32_16x16x32_bf16 v[24:27], v[168:171], v[184:187], v[24:27]
	v_mfma_f32_16x16x32_bf16 v[12:15], v[160:163], v[212:215], v[12:15]
	v_mfma_f32_16x16x32_bf16 v[8:11], v[168:171], v[212:215], v[8:11]
	v_mfma_f32_16x16x32_bf16 v[4:7], v[160:163], v[232:235], v[4:7]
	v_mfma_f32_16x16x32_bf16 v[0:3], v[168:171], v[232:235], v[0:3]
	s_barrier
	s_add_i32 s73, 0, 0x18000
	s_add_i32 s74, 0, 0x1c000
	v_add_u32_e32 v152, s73, v138
	v_add_u32_e32 v168, s74, v138
	ds_read_b128 v[140:143], v152
	ds_read_b128 v[144:147], v152 offset:1024
	ds_read_b128 v[148:151], v152 offset:2048
	ds_read_b128 v[152:155], v152 offset:3072
	ds_read_b128 v[156:159], v168
	ds_read_b128 v[160:163], v168 offset:1024
	ds_read_b128 v[164:167], v168 offset:2048
	ds_read_b128 v[168:171], v168 offset:3072
	s_add_u32 s18, s44, 0xb0000
	s_addc_u32 s19, s45, 0
	s_mov_b32 m0, s41
	v_lshl_add_u64 v[206:207], s[18:19], 0, v[128:129]
	ds_read_b128 v[172:175], v139 offset:32768
	ds_read_b128 v[176:179], v139 offset:33792
	ds_read_b128 v[180:183], v139 offset:34816
	ds_read_b128 v[184:187], v139 offset:35840
	ds_read_b128 v[188:191], v139 offset:36864
	ds_read_b128 v[212:215], v139 offset:37888
	ds_read_b128 v[216:219], v139 offset:38912
	ds_read_b128 v[232:235], v139 offset:39936
	global_load_lds_dwordx4 v[206:207], off
	v_lshl_add_u64 v[206:207], s[18:19], 0, v[130:131]
	s_mov_b32 m0, s46
	s_nop 0
	global_load_lds_dwordx4 v[206:207], off
	s_waitcnt vmcnt(8)
	s_waitcnt lgkmcnt(0)
	s_barrier
	s_waitcnt lgkmcnt(0)
	v_mfma_f32_16x16x32_bf16 v[124:127], v[140:143], v[172:175], v[124:127]
	v_mfma_f32_16x16x32_bf16 v[120:123], v[148:151], v[172:175], v[120:123]
	v_mfma_f32_16x16x32_bf16 v[116:119], v[140:143], v[180:183], v[116:119]
	v_mfma_f32_16x16x32_bf16 v[112:115], v[148:151], v[180:183], v[112:115]
	v_mfma_f32_16x16x32_bf16 v[100:103], v[140:143], v[188:191], v[100:103]
	v_mfma_f32_16x16x32_bf16 v[96:99], v[148:151], v[188:191], v[96:99]
	v_mfma_f32_16x16x32_bf16 v[84:87], v[140:143], v[216:219], v[84:87]
	v_mfma_f32_16x16x32_bf16 v[80:83], v[148:151], v[216:219], v[80:83]
	v_mfma_f32_16x16x32_bf16 v[124:127], v[144:147], v[176:179], v[124:127]
	v_mfma_f32_16x16x32_bf16 v[120:123], v[152:155], v[176:179], v[120:123]
	v_mfma_f32_16x16x32_bf16 v[116:119], v[144:147], v[184:187], v[116:119]
	v_mfma_f32_16x16x32_bf16 v[112:115], v[152:155], v[184:187], v[112:115]
	v_mfma_f32_16x16x32_bf16 v[100:103], v[144:147], v[212:215], v[100:103]
	v_mfma_f32_16x16x32_bf16 v[96:99], v[152:155], v[212:215], v[96:99]
	v_mfma_f32_16x16x32_bf16 v[84:87], v[144:147], v[232:235], v[84:87]
	v_mfma_f32_16x16x32_bf16 v[80:83], v[152:155], v[232:235], v[80:83]
	v_mfma_f32_16x16x32_bf16 v[108:111], v[156:159], v[172:175], v[108:111]
	v_mfma_f32_16x16x32_bf16 v[104:107], v[164:167], v[172:175], v[104:107]
	v_mfma_f32_16x16x32_bf16 v[92:95], v[156:159], v[180:183], v[92:95]
	v_mfma_f32_16x16x32_bf16 v[88:91], v[164:167], v[180:183], v[88:91]
	v_mfma_f32_16x16x32_bf16 v[76:79], v[156:159], v[188:191], v[76:79]
	v_mfma_f32_16x16x32_bf16 v[72:75], v[164:167], v[188:191], v[72:75]
	v_mfma_f32_16x16x32_bf16 v[68:71], v[156:159], v[216:219], v[68:71]
	v_mfma_f32_16x16x32_bf16 v[64:67], v[164:167], v[216:219], v[64:67]
	v_mfma_f32_16x16x32_bf16 v[108:111], v[160:163], v[176:179], v[108:111]
	v_mfma_f32_16x16x32_bf16 v[104:107], v[168:171], v[176:179], v[104:107]
	v_mfma_f32_16x16x32_bf16 v[92:95], v[160:163], v[184:187], v[92:95]
	v_mfma_f32_16x16x32_bf16 v[88:91], v[168:171], v[184:187], v[88:91]
	v_mfma_f32_16x16x32_bf16 v[76:79], v[160:163], v[212:215], v[76:79]
	v_mfma_f32_16x16x32_bf16 v[72:75], v[168:171], v[212:215], v[72:75]
	v_mfma_f32_16x16x32_bf16 v[68:71], v[160:163], v[232:235], v[68:71]
	v_mfma_f32_16x16x32_bf16 v[64:67], v[168:171], v[232:235], v[64:67]
	s_barrier
; #define PG8_STAGE(bufoff, gbase, voff) do { _Pragma("unroll") for (int _i = 0; _i < 2; ++_i) \
;         __builtin_amdgcn_global_load_lds((const unsigned*)((const char*)(gbase) + (voff)[_i]), (PG8_LAS unsigned*)(lds + (bufoff) + ldsw + _i * 8192), 16, 0, 0); } while (0)
; #define PG8_LDA(dst, b, h) do { _Pragma("unroll") for (int m = 0; m < 4; ++m) _Pragma("unroll") for (int k = 0; k < 2; ++k) dst[m][k] = *(const PG8_LAS bf16x8*)(lds + PG8_SA(b, h) + aoff + m * 2048 + k * 1024); } while (0)
; #define PG8_MMA(ai, bj, At, Bt) do { __builtin_amdgcn_s_setprio(1); _Pragma("unroll") for (int m = 0; m < 4; ++m) _Pragma("unroll") for (int n = 0; n < 2; ++n) _Pragma("unroll") for (int k = 0; k < 2; ++k) \
;         acc[ai][bj][m][n] = __builtin_amdgcn_mfma_f32_16x16x32_bf16(Bt[n][k], At[m][k], acc[ai][bj][m][n], 0, 0, 0); __builtin_amdgcn_s_setprio(0); } while (0)
; #define PG8_WAIT_V(n) asm volatile("s_waitcnt vmcnt(" #n ")" ::: "memory")
; #define PG8_WAIT_L(n) asm volatile("s_waitcnt lgkmcnt(" #n ")" ::: "memory")
; #define PG8_BAR __builtin_amdgcn_s_barrier()
; #define PG8_SCHED __builtin_amdgcn_sched_barrier(0)
; template <class Epi, class Sched, bool ALIGN_EPI = false, bool SP2 = false>
; __device__ __forceinline__ void gemm_phase(PG8_LAS unsigned char* lds, const Gemm g, const Sched& S, const Epi& E, const int tid) {
;     ...
;             PG8_LDA(At, 1, 1); PG8_STAGE(PG8_SB(1, 0), b3, voffB); PG8_STAGE(PG8_SB(1, 1), b3 + hstep, voffB); PG8_STAGE(PG8_SA(1, 0), a3, voffA);
;             PG8_WAIT_V(8); PG8_WAIT_L(0); PG8_BAR; PG8_MMA(1, 0, At, B0); PG8_MMA(1, 1, At, B1); PG8_BAR; PG8_SCHED;
	s_add_i32 s18, s73, s35
	v_lshl_add_u64 v[194:195], v[194:195], 0, s[36:37]
	s_mov_b32 m0, s18
	ds_read_b128 v[172:175], v139 offset:49152
	ds_read_b128 v[176:179], v139 offset:50176
	ds_read_b128 v[180:183], v139 offset:51200
	ds_read_b128 v[184:187], v139 offset:52224
	ds_read_b128 v[188:191], v139 offset:53248
	ds_read_b128 v[212:215], v139 offset:54272
	ds_read_b128 v[216:219], v139 offset:55296
	ds_read_b128 v[232:235], v139 offset:56320
	global_load_lds_dwordx4 v[194:195], off
	s_add_i32 m0, s18, 0x2000
	s_add_u32 s18, s22, 0xb0080
	v_lshl_add_u64 v[194:195], v[196:197], 0, s[36:37]
	s_addc_u32 s19, s23, 0
	s_add_i32 s22, s74, s35
	global_load_lds_dwordx4 v[194:195], off
	v_lshl_add_u64 v[194:195], s[18:19], 0, v[192:193]
	s_mov_b32 m0, s22
	s_nop 0
	global_load_lds_dwordx4 v[194:195], off
	v_lshl_add_u64 v[194:195], s[18:19], 0, v[132:133]
	s_add_i32 m0, s22, 0x2000
	s_nop 0
	global_load_lds_dwordx4 v[194:195], off
	v_lshl_add_u64 v[194:195], v[202:203], 0, s[36:37]
	s_mov_b32 m0, s47
	s_nop 0
	global_load_lds_dwordx4 v[194:195], off
	v_lshl_add_u64 v[194:195], v[204:205], 0, s[36:37]
	s_mov_b32 m0, s53
	s_nop 0
	global_load_lds_dwordx4 v[194:195], off
	s_waitcnt vmcnt(8)
	s_waitcnt lgkmcnt(0)
	s_barrier
	s_waitcnt lgkmcnt(0)
	v_mfma_f32_16x16x32_bf16 v[60:63], v[140:143], v[172:175], v[60:63]
	v_mfma_f32_16x16x32_bf16 v[56:59], v[148:151], v[172:175], v[56:59]
	v_mfma_f32_16x16x32_bf16 v[52:55], v[140:143], v[180:183], v[52:55]
	v_mfma_f32_16x16x32_bf16 v[48:51], v[148:151], v[180:183], v[48:51]
	v_mfma_f32_16x16x32_bf16 v[36:39], v[140:143], v[188:191], v[36:39]
	v_mfma_f32_16x16x32_bf16 v[32:35], v[148:151], v[188:191], v[32:35]
	v_mfma_f32_16x16x32_bf16 v[20:23], v[140:143], v[216:219], v[20:23]
	v_mfma_f32_16x16x32_bf16 v[16:19], v[148:151], v[216:219], v[16:19]
	v_mfma_f32_16x16x32_bf16 v[60:63], v[144:147], v[176:179], v[60:63]
	v_mfma_f32_16x16x32_bf16 v[56:59], v[152:155], v[176:179], v[56:59]
	v_mfma_f32_16x16x32_bf16 v[52:55], v[144:147], v[184:187], v[52:55]
	v_mfma_f32_16x16x32_bf16 v[48:51], v[152:155], v[184:187], v[48:51]
	v_mfma_f32_16x16x32_bf16 v[36:39], v[144:147], v[212:215], v[36:39]
	v_mfma_f32_16x16x32_bf16 v[32:35], v[152:155], v[212:215], v[32:35]
	v_mfma_f32_16x16x32_bf16 v[20:23], v[144:147], v[232:235], v[20:23]
	v_mfma_f32_16x16x32_bf16 v[16:19], v[152:155], v[232:235], v[16:19]
	v_mfma_f32_16x16x32_bf16 v[44:47], v[156:159], v[172:175], v[44:47]
	v_mfma_f32_16x16x32_bf16 v[40:43], v[164:167], v[172:175], v[40:43]
	v_mfma_f32_16x16x32_bf16 v[28:31], v[156:159], v[180:183], v[28:31]
	v_mfma_f32_16x16x32_bf16 v[24:27], v[164:167], v[180:183], v[24:27]
	v_mfma_f32_16x16x32_bf16 v[12:15], v[156:159], v[188:191], v[12:15]
	v_mfma_f32_16x16x32_bf16 v[8:11], v[164:167], v[188:191], v[8:11]
	v_mfma_f32_16x16x32_bf16 v[4:7], v[156:159], v[216:219], v[4:7]
	v_mfma_f32_16x16x32_bf16 v[0:3], v[164:167], v[216:219], v[0:3]
	v_mfma_f32_16x16x32_bf16 v[44:47], v[160:163], v[176:179], v[44:47]
	v_mfma_f32_16x16x32_bf16 v[40:43], v[168:171], v[176:179], v[40:43]
	v_mfma_f32_16x16x32_bf16 v[28:31], v[160:163], v[184:187], v[28:31]
	v_mfma_f32_16x16x32_bf16 v[24:27], v[168:171], v[184:187], v[24:27]
	v_mfma_f32_16x16x32_bf16 v[12:15], v[160:163], v[212:215], v[12:15]
	v_mfma_f32_16x16x32_bf16 v[8:11], v[168:171], v[212:215], v[8:11]
	v_mfma_f32_16x16x32_bf16 v[4:7], v[160:163], v[232:235], v[4:7]
	v_mfma_f32_16x16x32_bf16 v[0:3], v[168:171], v[232:235], v[0:3]
	s_barrier
	s_add_i32 s72, s72, 2
	s_add_u32 s62, s62, 0x100
	s_addc_u32 s71, s71, 0
	s_cmp_gt_u32 s72, 41
	s_mov_b64 s[18:19], s[20:21]
	s_cbranch_scc0 .LBB0_99
	s_and_b64 vcc, exec, s[14:15]
	s_cbranch_vccz .LBB0_102
	s_barrier

; #define PG8_STAGE(bufoff, gbase, voff) do { _Pragma("unroll") for (int _i = 0; _i < 2; ++_i) \
;         __builtin_amdgcn_global_load_lds((const unsigned*)((const char*)(gbase) + (voff)[_i]), (PG8_LAS unsigned*)(lds + (bufoff) + ldsw + _i * 8192), 16, 0, 0); } while (0)
; #define PG8_LDA(dst, b, h) do { _Pragma("unroll") for (int m = 0; m < 4; ++m) _Pragma("unroll") for (int k = 0; k < 2; ++k) dst[m][k] = *(const PG8_LAS bf16x8*)(lds + PG8_SA(b, h) + aoff + m * 2048 + k * 1024); } while (0)
; #define PG8_LDB(dst, b, h) do { _Pragma("unroll") for (int n = 0; n < 2; ++n) _Pragma("unroll") for (int k = 0; k < 2; ++k) dst[n][k] = *(const PG8_LAS bf16x8*)(lds + PG8_SB(b, h) + boff + n * 2048 + k * 1024); } while (0)
; #define PG8_MMA(ai, bj, At, Bt) do { __builtin_amdgcn_s_setprio(1); _Pragma("unroll") for (int m = 0; m < 4; ++m) _Pragma("unroll") for (int n = 0; n < 2; ++n) _Pragma("unroll") for (int k = 0; k < 2; ++k) \
;         acc[ai][bj][m][n] = __builtin_amdgcn_mfma_f32_16x16x32_bf16(Bt[n][k], At[m][k], acc[ai][bj][m][n], 0, 0, 0); __builtin_amdgcn_s_setprio(0); } while (0)
; #define PG8_WAIT_V(n) asm volatile("s_waitcnt vmcnt(" #n ")" ::: "memory")
; #define PG8_WAIT_L(n) asm volatile("s_waitcnt lgkmcnt(" #n ")" ::: "memory")
; #define PG8_BAR __builtin_amdgcn_s_barrier()
; #define PG8_SCHED __builtin_amdgcn_sched_barrier(0)
; template <class Epi, class Sched, bool ALIGN_EPI = false, bool SP2 = false>
; __device__ __forceinline__ void gemm_phase(PG8_LAS unsigned char* lds, const Gemm g, const Sched& S, const Epi& E, const int tid) {
;     ...
;             const bool last = (t == nt - 2);
;             const char* a1 = cA + (size_t)(t + 1) * kstep;
;             const char* a2 = last ? nA : cA + (size_t)(t + 2) * kstep; const char* b2 = last ? nB : cB + (size_t)(t + 2) * kstep;
;             const char* a3 = a2 + kstep; const char* b3 = b2 + kstep;
;             if (last && has_next) S.a_ready(nxt);
;             if constexpr (SP2) {
;             PG8_LDB(B0, 0, 0); PG8_LDB(B1, 0, 1); PG8_SCHED; PG8_LDA(At, 0, 0); PG8_STAGE(PG8_SA(1, 1), a1 + hstep, voffA);
;             PG8_WAIT_V(8); PG8_WAIT_L(0); PG8_BAR; PG8_MMA(0, 0, At, B0); PG8_MMA(0, 1, At, B1); PG8_BAR; PG8_SCHED;
;             PG8_LDA(At, 0, 1); PG8_STAGE(PG8_SB(0, 0), b2, voffB); PG8_STAGE(PG8_SB(0, 1), b2 + hstep, voffB); PG8_STAGE(PG8_SA(0, 0), a2, voffA);
.LBB0_127:
	s_add_u32 s44, s16, s22
	s_addc_u32 s45, s17, s23
	s_add_u32 s44, s44, 0x100
	s_addc_u32 s45, s45, 0
	s_waitcnt lgkmcnt(0)
	s_add_u32 s75, s19, s22
	s_addc_u32 s76, s62, s23
	s_add_i32 s77, 0, 0x10000
	s_cmpk_eq_i32 s22, 0x1500
	s_cselect_b32 s59, s21, s45
	s_cselect_b32 s58, s20, s44
	s_cselect_b32 s45, s11, s76
	s_cselect_b32 s44, s10, s75
	s_add_i32 s75, 0, 0x14000
	v_add_u32_e32 v156, s77, v142
	v_add_u32_e32 v172, s75, v142
	ds_read_b128 v[144:147], v156
	ds_read_b128 v[148:151], v156 offset:1024
	ds_read_b128 v[152:155], v156 offset:2048
	ds_read_b128 v[156:159], v156 offset:3072
	ds_read_b128 v[160:163], v172
	ds_read_b128 v[164:167], v172 offset:1024
	ds_read_b128 v[168:171], v172 offset:2048
	ds_read_b128 v[172:175], v172 offset:3072
	v_lshl_add_u64 v[194:195], v[138:139], 0, s[22:23]
	s_add_i32 m0, s47, 0xc000
	ds_read_b128 v[176:179], v143
	ds_read_b128 v[180:183], v143 offset:1024
	ds_read_b128 v[184:187], v143 offset:2048
	ds_read_b128 v[188:191], v143 offset:3072
	ds_read_b128 v[212:215], v143 offset:4096
	ds_read_b128 v[216:219], v143 offset:5120
	ds_read_b128 v[232:235], v143 offset:6144
	ds_read_b128 v[236:239], v143 offset:7168
	global_load_lds_dwordx4 v[194:195], off
	v_lshl_add_u64 v[194:195], v[140:141], 0, s[22:23]
	s_add_i32 m0, s47, 0xe000
	s_nop 0
	global_load_lds_dwordx4 v[194:195], off
	s_waitcnt vmcnt(8)
	s_waitcnt lgkmcnt(0)
	s_barrier
	s_waitcnt lgkmcnt(0)
	v_mfma_f32_16x16x32_bf16 v[124:127], v[144:147], v[176:179], v[124:127]
	v_mfma_f32_16x16x32_bf16 v[120:123], v[152:155], v[176:179], v[120:123]
	v_mfma_f32_16x16x32_bf16 v[108:111], v[144:147], v[184:187], v[108:111]
	v_mfma_f32_16x16x32_bf16 v[104:107], v[152:155], v[184:187], v[104:107]
	v_mfma_f32_16x16x32_bf16 v[92:95], v[144:147], v[212:215], v[92:95]
	v_mfma_f32_16x16x32_bf16 v[88:91], v[152:155], v[212:215], v[88:91]
	v_mfma_f32_16x16x32_bf16 v[76:79], v[144:147], v[232:235], v[76:79]
	v_mfma_f32_16x16x32_bf16 v[72:75], v[152:155], v[232:235], v[72:75]
	v_mfma_f32_16x16x32_bf16 v[124:127], v[148:151], v[180:183], v[124:127]
	v_mfma_f32_16x16x32_bf16 v[120:123], v[156:159], v[180:183], v[120:123]
	v_mfma_f32_16x16x32_bf16 v[108:111], v[148:151], v[188:191], v[108:111]
	v_mfma_f32_16x16x32_bf16 v[104:107], v[156:159], v[188:191], v[104:107]
	v_mfma_f32_16x16x32_bf16 v[92:95], v[148:151], v[216:219], v[92:95]
	v_mfma_f32_16x16x32_bf16 v[88:91], v[156:159], v[216:219], v[88:91]
	v_mfma_f32_16x16x32_bf16 v[76:79], v[148:151], v[236:239], v[76:79]
	v_mfma_f32_16x16x32_bf16 v[72:75], v[156:159], v[236:239], v[72:75]
	v_mfma_f32_16x16x32_bf16 v[116:119], v[160:163], v[176:179], v[116:119]
	v_mfma_f32_16x16x32_bf16 v[112:115], v[168:171], v[176:179], v[112:115]
	v_mfma_f32_16x16x32_bf16 v[100:103], v[160:163], v[184:187], v[100:103]
	v_mfma_f32_16x16x32_bf16 v[96:99], v[168:171], v[184:187], v[96:99]
	v_mfma_f32_16x16x32_bf16 v[84:87], v[160:163], v[212:215], v[84:87]
	v_mfma_f32_16x16x32_bf16 v[80:83], v[168:171], v[212:215], v[80:83]
	v_mfma_f32_16x16x32_bf16 v[68:71], v[160:163], v[232:235], v[68:71]
	v_mfma_f32_16x16x32_bf16 v[64:67], v[168:171], v[232:235], v[64:67]
	v_mfma_f32_16x16x32_bf16 v[116:119], v[164:167], v[180:183], v[116:119]
	v_mfma_f32_16x16x32_bf16 v[112:115], v[172:175], v[180:183], v[112:115]
	v_mfma_f32_16x16x32_bf16 v[100:103], v[164:167], v[188:191], v[100:103]
	v_mfma_f32_16x16x32_bf16 v[96:99], v[172:175], v[188:191], v[96:99]
	v_mfma_f32_16x16x32_bf16 v[84:87], v[164:167], v[216:219], v[84:87]
	v_mfma_f32_16x16x32_bf16 v[80:83], v[172:175], v[216:219], v[80:83]
	v_mfma_f32_16x16x32_bf16 v[68:71], v[164:167], v[236:239], v[68:71]
	v_mfma_f32_16x16x32_bf16 v[64:67], v[172:175], v[236:239], v[64:67]
	s_barrier
	s_add_i32 s76, s77, s46
	v_lshl_add_u64 v[194:195], s[44:45], 0, v[192:193]
	s_mov_b32 m0, s76
	ds_read_b128 v[176:179], v143 offset:16384
	ds_read_b128 v[180:183], v143 offset:17408
	ds_read_b128 v[184:187], v143 offset:18432
	ds_read_b128 v[188:191], v143 offset:19456
	ds_read_b128 v[212:215], v143 offset:20480
	ds_read_b128 v[216:219], v143 offset:21504
	ds_read_b128 v[232:235], v143 offset:22528
	ds_read_b128 v[236:239], v143 offset:23552
	global_load_lds_dwordx4 v[194:195], off
	s_add_i32 m0, s76, 0x2000
	s_add_u32 s76, s44, 0xb0000
	v_lshl_add_u64 v[196:197], s[44:45], 0, v[132:133]
	s_addc_u32 s77, s45, 0
	s_add_i32 s75, s75, s46
	global_load_lds_dwordx4 v[196:197], off
	v_lshl_add_u64 v[202:203], s[76:77], 0, v[192:193]
	s_mov_b32 m0, s75
	v_lshl_add_u64 v[204:205], s[58:59], 0, v[130:131]
	global_load_lds_dwordx4 v[202:203], off
	v_lshl_add_u64 v[202:203], s[76:77], 0, v[132:133]
	s_add_i32 m0, s75, 0x2000
	s_nop 0
	global_load_lds_dwordx4 v[202:203], off
	v_lshl_add_u64 v[202:203], s[58:59], 0, v[128:129]
	s_mov_b32 m0, s47
	s_nop 0
	global_load_lds_dwordx4 v[202:203], off
	s_mov_b32 m0, s53
	s_nop 0
	global_load_lds_dwordx4 v[204:205], off
	s_waitcnt vmcnt(8)
	s_waitcnt lgkmcnt(0)
	s_barrier
; #define PG8_STAGE(bufoff, gbase, voff) do { _Pragma("unroll") for (int _i = 0; _i < 2; ++_i) \
;         __builtin_amdgcn_global_load_lds((const unsigned*)((const char*)(gbase) + (voff)[_i]), (PG8_LAS unsigned*)(lds + (bufoff) + ldsw + _i * 8192), 16, 0, 0); } while (0)
; #define PG8_LDA(dst, b, h) do { _Pragma("unroll") for (int m = 0; m < 4; ++m) _Pragma("unroll") for (int k = 0; k < 2; ++k) dst[m][k] = *(const PG8_LAS bf16x8*)(lds + PG8_SA(b, h) + aoff + m * 2048 + k * 1024); } while (0)
; #define PG8_LDB(dst, b, h) do { _Pragma("unroll") for (int n = 0; n < 2; ++n) _Pragma("unroll") for (int k = 0; k < 2; ++k) dst[n][k] = *(const PG8_LAS bf16x8*)(lds + PG8_SB(b, h) + boff + n * 2048 + k * 1024); } while (0)
; #define PG8_MMA(ai, bj, At, Bt) do { __builtin_amdgcn_s_setprio(1); _Pragma("unroll") for (int m = 0; m < 4; ++m) _Pragma("unroll") for (int n = 0; n < 2; ++n) _Pragma("unroll") for (int k = 0; k < 2; ++k) \
;         acc[ai][bj][m][n] = __builtin_amdgcn_mfma_f32_16x16x32_bf16(Bt[n][k], At[m][k], acc[ai][bj][m][n], 0, 0, 0); __builtin_amdgcn_s_setprio(0); } while (0)
; #define PG8_WAIT_V(n) asm volatile("s_waitcnt vmcnt(" #n ")" ::: "memory")
; #define PG8_WAIT_L(n) asm volatile("s_waitcnt lgkmcnt(" #n ")" ::: "memory")
; #define PG8_BAR __builtin_amdgcn_s_barrier()
; #define PG8_SCHED __builtin_amdgcn_sched_barrier(0)
; template <class Epi, class Sched, bool ALIGN_EPI = false, bool SP2 = false>
; __device__ __forceinline__ void gemm_phase(PG8_LAS unsigned char* lds, const Gemm g, const Sched& S, const Epi& E, const int tid) {
;     ...
;             PG8_WAIT_V(8); PG8_WAIT_L(0); PG8_BAR; PG8_MMA(1, 0, At, B0); PG8_MMA(1, 1, At, B1); PG8_BAR; PG8_SCHED;
;             PG8_LDB(B0, 1, 0); PG8_LDB(B1, 1, 1); PG8_SCHED; PG8_LDA(At, 1, 0); PG8_STAGE(PG8_SA(0, 1), a2 + hstep, voffA);
;             PG8_WAIT_V(8); PG8_WAIT_L(0); PG8_BAR; PG8_MMA(0, 0, At, B0); PG8_MMA(0, 1, At, B1); PG8_BAR; PG8_SCHED;
	s_waitcnt lgkmcnt(0)
	v_mfma_f32_16x16x32_bf16 v[60:63], v[144:147], v[176:179], v[60:63]
	v_mfma_f32_16x16x32_bf16 v[56:59], v[152:155], v[176:179], v[56:59]
	v_mfma_f32_16x16x32_bf16 v[44:47], v[144:147], v[184:187], v[44:47]
	v_mfma_f32_16x16x32_bf16 v[40:43], v[152:155], v[184:187], v[40:43]
	v_mfma_f32_16x16x32_bf16 v[28:31], v[144:147], v[212:215], v[28:31]
	v_mfma_f32_16x16x32_bf16 v[24:27], v[152:155], v[212:215], v[24:27]
	v_mfma_f32_16x16x32_bf16 v[12:15], v[144:147], v[232:235], v[12:15]
	v_mfma_f32_16x16x32_bf16 v[8:11], v[152:155], v[232:235], v[8:11]
	v_mfma_f32_16x16x32_bf16 v[60:63], v[148:151], v[180:183], v[60:63]
	v_mfma_f32_16x16x32_bf16 v[56:59], v[156:159], v[180:183], v[56:59]
	v_mfma_f32_16x16x32_bf16 v[44:47], v[148:151], v[188:191], v[44:47]
	v_mfma_f32_16x16x32_bf16 v[40:43], v[156:159], v[188:191], v[40:43]
	v_mfma_f32_16x16x32_bf16 v[28:31], v[148:151], v[216:219], v[28:31]
	v_mfma_f32_16x16x32_bf16 v[24:27], v[156:159], v[216:219], v[24:27]
	v_mfma_f32_16x16x32_bf16 v[12:15], v[148:151], v[236:239], v[12:15]
	v_mfma_f32_16x16x32_bf16 v[8:11], v[156:159], v[236:239], v[8:11]
	v_mfma_f32_16x16x32_bf16 v[52:55], v[160:163], v[176:179], v[52:55]
	v_mfma_f32_16x16x32_bf16 v[48:51], v[168:171], v[176:179], v[48:51]
	v_mfma_f32_16x16x32_bf16 v[36:39], v[160:163], v[184:187], v[36:39]
	v_mfma_f32_16x16x32_bf16 v[32:35], v[168:171], v[184:187], v[32:35]
	v_mfma_f32_16x16x32_bf16 v[20:23], v[160:163], v[212:215], v[20:23]
	v_mfma_f32_16x16x32_bf16 v[16:19], v[168:171], v[212:215], v[16:19]
	v_mfma_f32_16x16x32_bf16 v[4:7], v[160:163], v[232:235], v[4:7]
	v_mfma_f32_16x16x32_bf16 v[0:3], v[168:171], v[232:235], v[0:3]
	v_mfma_f32_16x16x32_bf16 v[52:55], v[164:167], v[180:183], v[52:55]
	v_mfma_f32_16x16x32_bf16 v[48:51], v[172:175], v[180:183], v[48:51]
	v_mfma_f32_16x16x32_bf16 v[36:39], v[164:167], v[188:191], v[36:39]
	v_mfma_f32_16x16x32_bf16 v[32:35], v[172:175], v[188:191], v[32:35]
	v_mfma_f32_16x16x32_bf16 v[20:23], v[164:167], v[216:219], v[20:23]
	v_mfma_f32_16x16x32_bf16 v[16:19], v[172:175], v[216:219], v[16:19]
	v_mfma_f32_16x16x32_bf16 v[4:7], v[164:167], v[236:239], v[4:7]
	v_mfma_f32_16x16x32_bf16 v[0:3], v[172:175], v[236:239], v[0:3]
	s_barrier
	s_add_i32 s75, 0, 0x18000
	s_add_i32 s76, 0, 0x1c000
	v_add_u32_e32 v156, s75, v142
	v_add_u32_e32 v172, s76, v142
	ds_read_b128 v[144:147], v156
	ds_read_b128 v[148:151], v156 offset:1024
	ds_read_b128 v[152:155], v156 offset:2048
	ds_read_b128 v[156:159], v156 offset:3072
	ds_read_b128 v[160:163], v172
	ds_read_b128 v[164:167], v172 offset:1024
	ds_read_b128 v[168:171], v172 offset:2048
	ds_read_b128 v[172:175], v172 offset:3072
	s_add_u32 s58, s58, 0xb0000
	s_addc_u32 s59, s59, 0
	s_mov_b32 m0, s54
	v_lshl_add_u64 v[206:207], s[58:59], 0, v[128:129]
	ds_read_b128 v[176:179], v143 offset:32768
	ds_read_b128 v[180:183], v143 offset:33792
	ds_read_b128 v[184:187], v143 offset:34816
	ds_read_b128 v[188:191], v143 offset:35840
	ds_read_b128 v[212:215], v143 offset:36864
	ds_read_b128 v[216:219], v143 offset:37888
	ds_read_b128 v[232:235], v143 offset:38912
	ds_read_b128 v[236:239], v143 offset:39936
	global_load_lds_dwordx4 v[206:207], off
	v_lshl_add_u64 v[206:207], s[58:59], 0, v[130:131]
	s_mov_b32 m0, s55
	s_nop 0
	global_load_lds_dwordx4 v[206:207], off
	s_waitcnt vmcnt(8)
	s_waitcnt lgkmcnt(0)
	s_barrier
	s_waitcnt lgkmcnt(0)
	v_mfma_f32_16x16x32_bf16 v[124:127], v[144:147], v[176:179], v[124:127]
	v_mfma_f32_16x16x32_bf16 v[120:123], v[152:155], v[176:179], v[120:123]
	v_mfma_f32_16x16x32_bf16 v[108:111], v[144:147], v[184:187], v[108:111]
	v_mfma_f32_16x16x32_bf16 v[104:107], v[152:155], v[184:187], v[104:107]
	v_mfma_f32_16x16x32_bf16 v[92:95], v[144:147], v[212:215], v[92:95]
	v_mfma_f32_16x16x32_bf16 v[88:91], v[152:155], v[212:215], v[88:91]
	v_mfma_f32_16x16x32_bf16 v[76:79], v[144:147], v[232:235], v[76:79]
	v_mfma_f32_16x16x32_bf16 v[72:75], v[152:155], v[232:235], v[72:75]
	v_mfma_f32_16x16x32_bf16 v[124:127], v[148:151], v[180:183], v[124:127]
	v_mfma_f32_16x16x32_bf16 v[120:123], v[156:159], v[180:183], v[120:123]
	v_mfma_f32_16x16x32_bf16 v[108:111], v[148:151], v[188:191], v[108:111]
	v_mfma_f32_16x16x32_bf16 v[104:107], v[156:159], v[188:191], v[104:107]
	v_mfma_f32_16x16x32_bf16 v[92:95], v[148:151], v[216:219], v[92:95]
	v_mfma_f32_16x16x32_bf16 v[88:91], v[156:159], v[216:219], v[88:91]
	v_mfma_f32_16x16x32_bf16 v[76:79], v[148:151], v[236:239], v[76:79]
	v_mfma_f32_16x16x32_bf16 v[72:75], v[156:159], v[236:239], v[72:75]
	v_mfma_f32_16x16x32_bf16 v[116:119], v[160:163], v[176:179], v[116:119]
	v_mfma_f32_16x16x32_bf16 v[112:115], v[168:171], v[176:179], v[112:115]
	v_mfma_f32_16x16x32_bf16 v[100:103], v[160:163], v[184:187], v[100:103]
	v_mfma_f32_16x16x32_bf16 v[96:99], v[168:171], v[184:187], v[96:99]
	v_mfma_f32_16x16x32_bf16 v[84:87], v[160:163], v[212:215], v[84:87]
	v_mfma_f32_16x16x32_bf16 v[80:83], v[168:171], v[212:215], v[80:83]
	v_mfma_f32_16x16x32_bf16 v[68:71], v[160:163], v[232:235], v[68:71]
	v_mfma_f32_16x16x32_bf16 v[64:67], v[168:171], v[232:235], v[64:67]
	v_mfma_f32_16x16x32_bf16 v[116:119], v[164:167], v[180:183], v[116:119]
	v_mfma_f32_16x16x32_bf16 v[112:115], v[172:175], v[180:183], v[112:115]
	v_mfma_f32_16x16x32_bf16 v[100:103], v[164:167], v[188:191], v[100:103]
	v_mfma_f32_16x16x32_bf16 v[96:99], v[172:175], v[188:191], v[96:99]
	v_mfma_f32_16x16x32_bf16 v[84:87], v[164:167], v[216:219], v[84:87]
	v_mfma_f32_16x16x32_bf16 v[80:83], v[172:175], v[216:219], v[80:83]
	v_mfma_f32_16x16x32_bf16 v[68:71], v[164:167], v[236:239], v[68:71]
	v_mfma_f32_16x16x32_bf16 v[64:67], v[172:175], v[236:239], v[64:67]
	s_barrier
; #define PG8_STAGE(bufoff, gbase, voff) do { _Pragma("unroll") for (int _i = 0; _i < 2; ++_i) \
;         __builtin_amdgcn_global_load_lds((const unsigned*)((const char*)(gbase) + (voff)[_i]), (PG8_LAS unsigned*)(lds + (bufoff) + ldsw + _i * 8192), 16, 0, 0); } while (0)
; #define PG8_LDA(dst, b, h) do { _Pragma("unroll") for (int m = 0; m < 4; ++m) _Pragma("unroll") for (int k = 0; k < 2; ++k) dst[m][k] = *(const PG8_LAS bf16x8*)(lds + PG8_SA(b, h) + aoff + m * 2048 + k * 1024); } while (0)
; #define PG8_MMA(ai, bj, At, Bt) do { __builtin_amdgcn_s_setprio(1); _Pragma("unroll") for (int m = 0; m < 4; ++m) _Pragma("unroll") for (int n = 0; n < 2; ++n) _Pragma("unroll") for (int k = 0; k < 2; ++k) \
;         acc[ai][bj][m][n] = __builtin_amdgcn_mfma_f32_16x16x32_bf16(Bt[n][k], At[m][k], acc[ai][bj][m][n], 0, 0, 0); __builtin_amdgcn_s_setprio(0); } while (0)
; #define PG8_WAIT_V(n) asm volatile("s_waitcnt vmcnt(" #n ")" ::: "memory")
; #define PG8_WAIT_L(n) asm volatile("s_waitcnt lgkmcnt(" #n ")" ::: "memory")
; #define PG8_BAR __builtin_amdgcn_s_barrier()
; #define PG8_SCHED __builtin_amdgcn_sched_barrier(0)
; template <class Epi, class Sched, bool ALIGN_EPI = false, bool SP2 = false>
; __device__ __forceinline__ void gemm_phase(PG8_LAS unsigned char* lds, const Gemm g, const Sched& S, const Epi& E, const int tid) {
;     ...
;             PG8_LDA(At, 1, 1); PG8_STAGE(PG8_SB(1, 0), b3, voffB); PG8_STAGE(PG8_SB(1, 1), b3 + hstep, voffB); PG8_STAGE(PG8_SA(1, 0), a3, voffA);
;             PG8_WAIT_V(8); PG8_WAIT_L(0); PG8_BAR; PG8_MMA(1, 0, At, B0); PG8_MMA(1, 1, At, B1); PG8_BAR; PG8_SCHED;
;     ...
;         if (!has_next) break;
; #pragma unroll
;         for (int a = 0; a < 2; ++a)
; #pragma unroll
;             for (int b = 0; b < 2; ++b)
; #pragma unroll
;                 for (int m = 0; m < 4; ++m)
; #pragma unroll
;                     for (int n = 0; n < 2; ++n) acc[a][b][m][n] = (f32x4){0.f, 0.f, 0.f, 0.f};
;         cur = nxt; cA = nA; cB = nB; ++ui;
	s_add_i32 s58, s75, s46
	v_lshl_add_u64 v[194:195], v[194:195], 0, s[36:37]
	s_mov_b32 m0, s58
	ds_read_b128 v[176:179], v143 offset:49152
	ds_read_b128 v[180:183], v143 offset:50176
	ds_read_b128 v[184:187], v143 offset:51200
	ds_read_b128 v[188:191], v143 offset:52224
	ds_read_b128 v[212:215], v143 offset:53248
	ds_read_b128 v[216:219], v143 offset:54272
	ds_read_b128 v[232:235], v143 offset:55296
	ds_read_b128 v[236:239], v143 offset:56320
	global_load_lds_dwordx4 v[194:195], off
	s_add_i32 m0, s58, 0x2000
	s_add_u32 s44, s44, 0xb0080
	v_lshl_add_u64 v[194:195], v[196:197], 0, s[36:37]
	s_addc_u32 s45, s45, 0
	s_add_i32 s58, s76, s46
	global_load_lds_dwordx4 v[194:195], off
	v_lshl_add_u64 v[194:195], s[44:45], 0, v[192:193]
	s_mov_b32 m0, s58
	s_nop 0
	global_load_lds_dwordx4 v[194:195], off
	v_lshl_add_u64 v[194:195], s[44:45], 0, v[132:133]
	s_add_i32 m0, s58, 0x2000
	s_nop 0
	global_load_lds_dwordx4 v[194:195], off
	v_lshl_add_u64 v[194:195], v[202:203], 0, s[36:37]
	s_mov_b32 m0, s60
	s_nop 0
	global_load_lds_dwordx4 v[194:195], off
	v_lshl_add_u64 v[194:195], v[204:205], 0, s[36:37]
	s_mov_b32 m0, s70
	s_nop 0
	global_load_lds_dwordx4 v[194:195], off
	s_waitcnt vmcnt(8)
	s_waitcnt lgkmcnt(0)
	s_barrier
	s_waitcnt lgkmcnt(0)
	v_mfma_f32_16x16x32_bf16 v[60:63], v[144:147], v[176:179], v[60:63]
	v_mfma_f32_16x16x32_bf16 v[56:59], v[152:155], v[176:179], v[56:59]
	v_mfma_f32_16x16x32_bf16 v[44:47], v[144:147], v[184:187], v[44:47]
	v_mfma_f32_16x16x32_bf16 v[40:43], v[152:155], v[184:187], v[40:43]
	v_mfma_f32_16x16x32_bf16 v[28:31], v[144:147], v[212:215], v[28:31]
	v_mfma_f32_16x16x32_bf16 v[24:27], v[152:155], v[212:215], v[24:27]
	v_mfma_f32_16x16x32_bf16 v[12:15], v[144:147], v[232:235], v[12:15]
	v_mfma_f32_16x16x32_bf16 v[8:11], v[152:155], v[232:235], v[8:11]
	v_mfma_f32_16x16x32_bf16 v[60:63], v[148:151], v[180:183], v[60:63]
	v_mfma_f32_16x16x32_bf16 v[56:59], v[156:159], v[180:183], v[56:59]
	v_mfma_f32_16x16x32_bf16 v[44:47], v[148:151], v[188:191], v[44:47]
	v_mfma_f32_16x16x32_bf16 v[40:43], v[156:159], v[188:191], v[40:43]
	v_mfma_f32_16x16x32_bf16 v[28:31], v[148:151], v[216:219], v[28:31]
	v_mfma_f32_16x16x32_bf16 v[24:27], v[156:159], v[216:219], v[24:27]
	v_mfma_f32_16x16x32_bf16 v[12:15], v[148:151], v[236:239], v[12:15]
	v_mfma_f32_16x16x32_bf16 v[8:11], v[156:159], v[236:239], v[8:11]
	v_mfma_f32_16x16x32_bf16 v[52:55], v[160:163], v[176:179], v[52:55]
	v_mfma_f32_16x16x32_bf16 v[48:51], v[168:171], v[176:179], v[48:51]
	v_mfma_f32_16x16x32_bf16 v[36:39], v[160:163], v[184:187], v[36:39]
	v_mfma_f32_16x16x32_bf16 v[32:35], v[168:171], v[184:187], v[32:35]
	v_mfma_f32_16x16x32_bf16 v[20:23], v[160:163], v[212:215], v[20:23]
	v_mfma_f32_16x16x32_bf16 v[16:19], v[168:171], v[212:215], v[16:19]
	v_mfma_f32_16x16x32_bf16 v[4:7], v[160:163], v[232:235], v[4:7]
	v_mfma_f32_16x16x32_bf16 v[0:3], v[168:171], v[232:235], v[0:3]
	v_mfma_f32_16x16x32_bf16 v[52:55], v[164:167], v[180:183], v[52:55]
	v_mfma_f32_16x16x32_bf16 v[48:51], v[172:175], v[180:183], v[48:51]
	v_mfma_f32_16x16x32_bf16 v[36:39], v[164:167], v[188:191], v[36:39]
	v_mfma_f32_16x16x32_bf16 v[32:35], v[172:175], v[188:191], v[32:35]
	v_mfma_f32_16x16x32_bf16 v[20:23], v[164:167], v[216:219], v[20:23]
	v_mfma_f32_16x16x32_bf16 v[16:19], v[172:175], v[216:219], v[16:19]
	v_mfma_f32_16x16x32_bf16 v[4:7], v[164:167], v[236:239], v[4:7]
	v_mfma_f32_16x16x32_bf16 v[0:3], v[172:175], v[236:239], v[0:3]
	s_barrier
	s_add_i32 s74, s74, 2
	s_add_u32 s22, s22, 0x100
	s_addc_u32 s23, s23, 0
	s_cmp_gt_u32 s74, 41
	s_cbranch_scc0 .LBB0_127
	s_add_u32 s22, s19, 0xffffff00
	s_addc_u32 s23, s62, -1
	s_and_b64 vcc, exec, s[8:9]
	s_cbranch_vccnz .LBB0_130
	v_mov_b32_e32 v0, 0
	s_mov_b32 s14, s72
	s_mov_b32 s1, s73
	s_mov_b64 s[16:17], s[20:21]
	s_mov_b32 s71, s18
	v_mov_b32_e32 v1, v0
	v_mov_b32_e32 v2, v0
	v_mov_b32_e32 v3, v0
	v_mov_b32_e32 v4, v0
	v_mov_b32_e32 v5, v0
	v_mov_b32_e32 v6, v0
	v_mov_b32_e32 v7, v0
	v_mov_b32_e32 v16, v0
	v_mov_b32_e32 v17, v0
	v_mov_b32_e32 v18, v0
	v_mov_b32_e32 v19, v0
	v_mov_b32_e32 v20, v0
	v_mov_b32_e32 v21, v0
	v_mov_b32_e32 v22, v0
	v_mov_b32_e32 v23, v0
	v_mov_b32_e32 v32, v0
	v_mov_b32_e32 v33, v0
	v_mov_b32_e32 v34, v0
	v_mov_b32_e32 v35, v0
	v_mov_b32_e32 v36, v0
	v_mov_b32_e32 v37, v0
	v_mov_b32_e32 v38, v0
	v_mov_b32_e32 v39, v0
	v_mov_b32_e32 v48, v0
	v_mov_b32_e32 v49, v0
	v_mov_b32_e32 v50, v0
	v_mov_b32_e32 v51, v0
	v_mov_b32_e32 v52, v0
	v_mov_b32_e32 v53, v0
	v_mov_b32_e32 v54, v0
	v_mov_b32_e32 v55, v0
	v_mov_b32_e32 v8, v0
	v_mov_b32_e32 v9, v0
	v_mov_b32_e32 v10, v0
	v_mov_b32_e32 v11, v0
	v_mov_b32_e32 v12, v0
	v_mov_b32_e32 v13, v0
	v_mov_b32_e32 v14, v0
	v_mov_b32_e32 v15, v0
	v_mov_b32_e32 v24, v0
	v_mov_b32_e32 v25, v0
	v_mov_b32_e32 v26, v0
	v_mov_b32_e32 v27, v0
	v_mov_b32_e32 v28, v0
	v_mov_b32_e32 v29, v0
	v_mov_b32_e32 v30, v0
	v_mov_b32_e32 v31, v0
	v_mov_b32_e32 v40, v0
	v_mov_b32_e32 v41, v0
	v_mov_b32_e32 v42, v0
	v_mov_b32_e32 v43, v0
	v_mov_b32_e32 v44, v0
	v_mov_b32_e32 v45, v0
	v_mov_b32_e32 v46, v0
	v_mov_b32_e32 v47, v0
	v_mov_b32_e32 v56, v0
	v_mov_b32_e32 v57, v0
	v_mov_b32_e32 v58, v0
	v_mov_b32_e32 v59, v0
	v_mov_b32_e32 v60, v0
	v_mov_b32_e32 v61, v0
	v_mov_b32_e32 v62, v0
	v_mov_b32_e32 v63, v0
	v_mov_b32_e32 v64, v0
	v_mov_b32_e32 v65, v0
	v_mov_b32_e32 v66, v0
	v_mov_b32_e32 v67, v0
	v_mov_b32_e32 v68, v0
	v_mov_b32_e32 v69, v0
	v_mov_b32_e32 v70, v0
	v_mov_b32_e32 v71, v0
	v_mov_b32_e32 v80, v0
	v_mov_b32_e32 v81, v0
	v_mov_b32_e32 v82, v0
	v_mov_b32_e32 v83, v0
	v_mov_b32_e32 v84, v0
	v_mov_b32_e32 v85, v0
	v_mov_b32_e32 v86, v0
	v_mov_b32_e32 v87, v0
	v_mov_b32_e32 v96, v0
	v_mov_b32_e32 v97, v0
	v_mov_b32_e32 v98, v0
	v_mov_b32_e32 v99, v0
	v_mov_b32_e32 v100, v0
	v_mov_b32_e32 v101, v0
	v_mov_b32_e32 v102, v0
	v_mov_b32_e32 v103, v0
	v_mov_b32_e32 v112, v0
	v_mov_b32_e32 v113, v0
	v_mov_b32_e32 v114, v0
	v_mov_b32_e32 v115, v0
	v_mov_b32_e32 v116, v0
	v_mov_b32_e32 v117, v0
	v_mov_b32_e32 v118, v0
	v_mov_b32_e32 v119, v0
	v_mov_b32_e32 v72, v0
	v_mov_b32_e32 v73, v0
	v_mov_b32_e32 v74, v0
	v_mov_b32_e32 v75, v0
	v_mov_b32_e32 v76, v0
	v_mov_b32_e32 v77, v0
	v_mov_b32_e32 v78, v0
	v_mov_b32_e32 v79, v0
	v_mov_b32_e32 v88, v0
	v_mov_b32_e32 v89, v0
	v_mov_b32_e32 v90, v0
	v_mov_b32_e32 v91, v0
	v_mov_b32_e32 v92, v0
	v_mov_b32_e32 v93, v0
	v_mov_b32_e32 v94, v0
	v_mov_b32_e32 v95, v0
	v_mov_b32_e32 v104, v0
	v_mov_b32_e32 v105, v0
	v_mov_b32_e32 v106, v0
	v_mov_b32_e32 v107, v0
	v_mov_b32_e32 v108, v0
	v_mov_b32_e32 v109, v0
	v_mov_b32_e32 v110, v0
	v_mov_b32_e32 v111, v0
	v_mov_b32_e32 v120, v0
	v_mov_b32_e32 v121, v0
	v_mov_b32_e32 v122, v0
	v_mov_b32_e32 v123, v0
	v_mov_b32_e32 v124, v0
	v_mov_b32_e32 v125, v0
	v_mov_b32_e32 v126, v0
	v_mov_b32_e32 v127, v0
	s_load_dword s75, s[96:97], 0x0
	s_andn2_b64 vcc, exec, s[6:7]
	s_cbranch_vccnz .LBB0_131
	s_branch .LBB0_189

; #define PG8_STAGE(bufoff, gbase, voff) do { _Pragma("unroll") for (int _i = 0; _i < 2; ++_i) \
;         __builtin_amdgcn_global_load_lds((const unsigned*)((const char*)(gbase) + (voff)[_i]), (PG8_LAS unsigned*)(lds + (bufoff) + ldsw + _i * 8192), 16, 0, 0); } while (0)
; #define PG8_LDA(dst, b, h) do { _Pragma("unroll") for (int m = 0; m < 4; ++m) _Pragma("unroll") for (int k = 0; k < 2; ++k) dst[m][k] = *(const PG8_LAS bf16x8*)(lds + PG8_SA(b, h) + aoff + m * 2048 + k * 1024); } while (0)
; #define PG8_LDB(dst, b, h) do { _Pragma("unroll") for (int n = 0; n < 2; ++n) _Pragma("unroll") for (int k = 0; k < 2; ++k) dst[n][k] = *(const PG8_LAS bf16x8*)(lds + PG8_SB(b, h) + boff + n * 2048 + k * 1024); } while (0)
; #define PG8_MMA(ai, bj, At, Bt) do { __builtin_amdgcn_s_setprio(1); _Pragma("unroll") for (int m = 0; m < 4; ++m) _Pragma("unroll") for (int n = 0; n < 2; ++n) _Pragma("unroll") for (int k = 0; k < 2; ++k) \
;         acc[ai][bj][m][n] = __builtin_amdgcn_mfma_f32_16x16x32_bf16(Bt[n][k], At[m][k], acc[ai][bj][m][n], 0, 0, 0); __builtin_amdgcn_s_setprio(0); } while (0)
; #define PG8_WAIT_V(n) asm volatile("s_waitcnt vmcnt(" #n ")" ::: "memory")
; #define PG8_WAIT_L(n) asm volatile("s_waitcnt lgkmcnt(" #n ")" ::: "memory")
; #define PG8_BAR __builtin_amdgcn_s_barrier()
; #define PG8_SCHED __builtin_amdgcn_sched_barrier(0)
; template <class Epi, class Sched, bool ALIGN_EPI = false, bool SP2 = false>
; __device__ __forceinline__ void gemm_phase(PG8_LAS unsigned char* lds, const Gemm g, const Sched& S, const Epi& E, const int tid) {
;     ...
;             const bool last = (t == nt - 2);
;             const char* a1 = cA + (size_t)(t + 1) * kstep;
;             const char* a2 = last ? nA : cA + (size_t)(t + 2) * kstep; const char* b2 = last ? nB : cB + (size_t)(t + 2) * kstep;
;             const char* a3 = a2 + kstep; const char* b3 = b2 + kstep;
;             if (last && has_next) S.a_ready(nxt);
;             if constexpr (SP2) {
;             PG8_LDB(B0, 0, 0); PG8_LDB(B1, 0, 1); PG8_SCHED; PG8_LDA(At, 0, 0); PG8_STAGE(PG8_SA(1, 1), a1 + hstep, voffA);
;             PG8_WAIT_V(8); PG8_WAIT_L(0); PG8_BAR; PG8_MMA(0, 0, At, B0); PG8_MMA(0, 1, At, B1); PG8_BAR; PG8_SCHED;
;             PG8_LDA(At, 0, 1); PG8_STAGE(PG8_SB(0, 0), b2, voffB); PG8_STAGE(PG8_SB(0, 1), b2 + hstep, voffB); PG8_STAGE(PG8_SA(0, 0), a2, voffA);
.LBB0_143:
	s_add_u32 s58, s44, 0xfffc0080
	s_addc_u32 s59, s45, -1
	s_add_i32 s72, 0, 0x10000
	s_cmp_eq_u32 s71, 12
	s_cselect_b32 s79, s17, s59
	s_cselect_b32 s78, s55, s58
	v_add_u32_e32 v138, s72, v140
	s_cselect_b32 s59, s15, s70
	s_cselect_b32 s58, s60, s62
	s_add_i32 s74, 0, 0x14000
	ds_read_b128 v[142:145], v138
	ds_read_b128 v[146:149], v138 offset:1024
	ds_read_b128 v[150:153], v138 offset:2048
	ds_read_b128 v[154:157], v138 offset:3072
	v_add_u32_e32 v138, s74, v140
	ds_read_b128 v[158:161], v138
	ds_read_b128 v[162:165], v138 offset:1024
	ds_read_b128 v[166:169], v138 offset:2048
	ds_read_b128 v[170:173], v138 offset:3072
	v_lshl_add_u64 v[138:139], s[44:45], 0, v[134:135]
	s_add_i32 m0, s38, 0xc000
	ds_read_b128 v[174:177], v141
	ds_read_b128 v[178:181], v141 offset:1024
	ds_read_b128 v[182:185], v141 offset:2048
	ds_read_b128 v[186:189], v141 offset:3072
	ds_read_b128 v[212:215], v141 offset:4096
	ds_read_b128 v[216:219], v141 offset:5120
	ds_read_b128 v[232:235], v141 offset:6144
	ds_read_b128 v[236:239], v141 offset:7168
	global_load_lds_dwordx4 v[138:139], off
	v_lshl_add_u64 v[138:139], s[44:45], 0, v[136:137]
	s_add_i32 m0, s38, 0xe000
	s_nop 0
	global_load_lds_dwordx4 v[138:139], off
	s_waitcnt vmcnt(8)
	s_waitcnt lgkmcnt(0)
	s_barrier
	s_waitcnt lgkmcnt(0)
	v_mfma_f32_16x16x32_bf16 v[124:127], v[142:145], v[174:177], v[124:127]
	v_mfma_f32_16x16x32_bf16 v[116:119], v[150:153], v[174:177], v[116:119]
	v_mfma_f32_16x16x32_bf16 v[108:111], v[142:145], v[182:185], v[108:111]
	v_mfma_f32_16x16x32_bf16 v[100:103], v[150:153], v[182:185], v[100:103]
	v_mfma_f32_16x16x32_bf16 v[92:95], v[142:145], v[212:215], v[92:95]
	v_mfma_f32_16x16x32_bf16 v[84:87], v[150:153], v[212:215], v[84:87]
	v_mfma_f32_16x16x32_bf16 v[76:79], v[142:145], v[232:235], v[76:79]
	v_mfma_f32_16x16x32_bf16 v[68:71], v[150:153], v[232:235], v[68:71]
	v_mfma_f32_16x16x32_bf16 v[124:127], v[146:149], v[178:181], v[124:127]
	v_mfma_f32_16x16x32_bf16 v[116:119], v[154:157], v[178:181], v[116:119]
	v_mfma_f32_16x16x32_bf16 v[108:111], v[146:149], v[186:189], v[108:111]
	v_mfma_f32_16x16x32_bf16 v[100:103], v[154:157], v[186:189], v[100:103]
	v_mfma_f32_16x16x32_bf16 v[92:95], v[146:149], v[216:219], v[92:95]
	v_mfma_f32_16x16x32_bf16 v[84:87], v[154:157], v[216:219], v[84:87]
	v_mfma_f32_16x16x32_bf16 v[76:79], v[146:149], v[236:239], v[76:79]
	v_mfma_f32_16x16x32_bf16 v[68:71], v[154:157], v[236:239], v[68:71]
	v_mfma_f32_16x16x32_bf16 v[120:123], v[158:161], v[174:177], v[120:123]
	v_mfma_f32_16x16x32_bf16 v[112:115], v[166:169], v[174:177], v[112:115]
	v_mfma_f32_16x16x32_bf16 v[104:107], v[158:161], v[182:185], v[104:107]
	v_mfma_f32_16x16x32_bf16 v[96:99], v[166:169], v[182:185], v[96:99]
	v_mfma_f32_16x16x32_bf16 v[88:91], v[158:161], v[212:215], v[88:91]
	v_mfma_f32_16x16x32_bf16 v[80:83], v[166:169], v[212:215], v[80:83]
	v_mfma_f32_16x16x32_bf16 v[72:75], v[158:161], v[232:235], v[72:75]
	v_mfma_f32_16x16x32_bf16 v[64:67], v[166:169], v[232:235], v[64:67]
	v_mfma_f32_16x16x32_bf16 v[120:123], v[162:165], v[178:181], v[120:123]
	v_mfma_f32_16x16x32_bf16 v[112:115], v[170:173], v[178:181], v[112:115]
	v_mfma_f32_16x16x32_bf16 v[104:107], v[162:165], v[186:189], v[104:107]
	v_mfma_f32_16x16x32_bf16 v[96:99], v[170:173], v[186:189], v[96:99]
	v_mfma_f32_16x16x32_bf16 v[88:91], v[162:165], v[216:219], v[88:91]
	v_mfma_f32_16x16x32_bf16 v[80:83], v[170:173], v[216:219], v[80:83]
	v_mfma_f32_16x16x32_bf16 v[72:75], v[162:165], v[236:239], v[72:75]
	v_mfma_f32_16x16x32_bf16 v[64:67], v[170:173], v[236:239], v[64:67]
	s_barrier
	s_add_i32 s72, s72, s34
	v_lshl_add_u64 v[138:139], s[58:59], 0, v[192:193]
	s_mov_b32 m0, s72
	ds_read_b128 v[174:177], v141 offset:16384
	ds_read_b128 v[178:181], v141 offset:17408
	ds_read_b128 v[182:185], v141 offset:18432
	ds_read_b128 v[186:189], v141 offset:19456
	ds_read_b128 v[212:215], v141 offset:20480
	ds_read_b128 v[216:219], v141 offset:21504
	ds_read_b128 v[232:235], v141 offset:22528
	ds_read_b128 v[236:239], v141 offset:23552
	global_load_lds_dwordx4 v[138:139], off
	s_add_i32 m0, s72, 0x2000
	s_add_u32 s72, s58, 0x40000
	v_lshl_add_u64 v[190:191], s[58:59], 0, v[128:129]
	s_addc_u32 s73, s59, 0
	s_add_i32 s74, s74, s34
	global_load_lds_dwordx4 v[190:191], off
	v_lshl_add_u64 v[194:195], s[72:73], 0, v[192:193]
	s_mov_b32 m0, s74
	v_lshl_add_u64 v[196:197], s[78:79], 0, v[130:131]
	global_load_lds_dwordx4 v[194:195], off
	v_lshl_add_u64 v[194:195], s[72:73], 0, v[128:129]
	s_add_i32 m0, s74, 0x2000
	s_nop 0
	global_load_lds_dwordx4 v[194:195], off
	v_lshl_add_u64 v[194:195], s[78:79], 0, v[132:133]
	s_mov_b32 m0, s38
	s_nop 0
	global_load_lds_dwordx4 v[194:195], off
	s_mov_b32 m0, s40
	s_nop 0
	global_load_lds_dwordx4 v[196:197], off
	s_waitcnt vmcnt(8)
	s_waitcnt lgkmcnt(0)
	s_barrier
; #define PG8_STAGE(bufoff, gbase, voff) do { _Pragma("unroll") for (int _i = 0; _i < 2; ++_i) \
;         __builtin_amdgcn_global_load_lds((const unsigned*)((const char*)(gbase) + (voff)[_i]), (PG8_LAS unsigned*)(lds + (bufoff) + ldsw + _i * 8192), 16, 0, 0); } while (0)
; #define PG8_LDA(dst, b, h) do { _Pragma("unroll") for (int m = 0; m < 4; ++m) _Pragma("unroll") for (int k = 0; k < 2; ++k) dst[m][k] = *(const PG8_LAS bf16x8*)(lds + PG8_SA(b, h) + aoff + m * 2048 + k * 1024); } while (0)
; #define PG8_LDB(dst, b, h) do { _Pragma("unroll") for (int n = 0; n < 2; ++n) _Pragma("unroll") for (int k = 0; k < 2; ++k) dst[n][k] = *(const PG8_LAS bf16x8*)(lds + PG8_SB(b, h) + boff + n * 2048 + k * 1024); } while (0)
; #define PG8_MMA(ai, bj, At, Bt) do { __builtin_amdgcn_s_setprio(1); _Pragma("unroll") for (int m = 0; m < 4; ++m) _Pragma("unroll") for (int n = 0; n < 2; ++n) _Pragma("unroll") for (int k = 0; k < 2; ++k) \
;         acc[ai][bj][m][n] = __builtin_amdgcn_mfma_f32_16x16x32_bf16(Bt[n][k], At[m][k], acc[ai][bj][m][n], 0, 0, 0); __builtin_amdgcn_s_setprio(0); } while (0)
; #define PG8_WAIT_V(n) asm volatile("s_waitcnt vmcnt(" #n ")" ::: "memory")
; #define PG8_WAIT_L(n) asm volatile("s_waitcnt lgkmcnt(" #n ")" ::: "memory")
; #define PG8_BAR __builtin_amdgcn_s_barrier()
; #define PG8_SCHED __builtin_amdgcn_sched_barrier(0)
; template <class Epi, class Sched, bool ALIGN_EPI = false, bool SP2 = false>
; __device__ __forceinline__ void gemm_phase(PG8_LAS unsigned char* lds, const Gemm g, const Sched& S, const Epi& E, const int tid) {
;     ...
;             PG8_WAIT_V(8); PG8_WAIT_L(0); PG8_BAR; PG8_MMA(1, 0, At, B0); PG8_MMA(1, 1, At, B1); PG8_BAR; PG8_SCHED;
;             PG8_LDB(B0, 1, 0); PG8_LDB(B1, 1, 1); PG8_SCHED; PG8_LDA(At, 1, 0); PG8_STAGE(PG8_SA(0, 1), a2 + hstep, voffA);
;             PG8_WAIT_V(8); PG8_WAIT_L(0); PG8_BAR; PG8_MMA(0, 0, At, B0); PG8_MMA(0, 1, At, B1); PG8_BAR; PG8_SCHED;
	s_waitcnt lgkmcnt(0)
	v_mfma_f32_16x16x32_bf16 v[60:63], v[142:145], v[174:177], v[60:63]
	v_mfma_f32_16x16x32_bf16 v[52:55], v[150:153], v[174:177], v[52:55]
	v_mfma_f32_16x16x32_bf16 v[44:47], v[142:145], v[182:185], v[44:47]
	v_mfma_f32_16x16x32_bf16 v[36:39], v[150:153], v[182:185], v[36:39]
	v_mfma_f32_16x16x32_bf16 v[28:31], v[142:145], v[212:215], v[28:31]
	v_mfma_f32_16x16x32_bf16 v[20:23], v[150:153], v[212:215], v[20:23]
	v_mfma_f32_16x16x32_bf16 v[12:15], v[142:145], v[232:235], v[12:15]
	v_mfma_f32_16x16x32_bf16 v[4:7], v[150:153], v[232:235], v[4:7]
	v_mfma_f32_16x16x32_bf16 v[60:63], v[146:149], v[178:181], v[60:63]
	v_mfma_f32_16x16x32_bf16 v[52:55], v[154:157], v[178:181], v[52:55]
	v_mfma_f32_16x16x32_bf16 v[44:47], v[146:149], v[186:189], v[44:47]
	v_mfma_f32_16x16x32_bf16 v[36:39], v[154:157], v[186:189], v[36:39]
	v_mfma_f32_16x16x32_bf16 v[28:31], v[146:149], v[216:219], v[28:31]
	v_mfma_f32_16x16x32_bf16 v[20:23], v[154:157], v[216:219], v[20:23]
	v_mfma_f32_16x16x32_bf16 v[12:15], v[146:149], v[236:239], v[12:15]
	v_mfma_f32_16x16x32_bf16 v[4:7], v[154:157], v[236:239], v[4:7]
	v_mfma_f32_16x16x32_bf16 v[56:59], v[158:161], v[174:177], v[56:59]
	v_mfma_f32_16x16x32_bf16 v[48:51], v[166:169], v[174:177], v[48:51]
	v_mfma_f32_16x16x32_bf16 v[40:43], v[158:161], v[182:185], v[40:43]
	v_mfma_f32_16x16x32_bf16 v[32:35], v[166:169], v[182:185], v[32:35]
	v_mfma_f32_16x16x32_bf16 v[24:27], v[158:161], v[212:215], v[24:27]
	v_mfma_f32_16x16x32_bf16 v[16:19], v[166:169], v[212:215], v[16:19]
	v_mfma_f32_16x16x32_bf16 v[8:11], v[158:161], v[232:235], v[8:11]
	v_mfma_f32_16x16x32_bf16 v[0:3], v[166:169], v[232:235], v[0:3]
	v_mfma_f32_16x16x32_bf16 v[56:59], v[162:165], v[178:181], v[56:59]
	v_mfma_f32_16x16x32_bf16 v[48:51], v[170:173], v[178:181], v[48:51]
	v_mfma_f32_16x16x32_bf16 v[40:43], v[162:165], v[186:189], v[40:43]
	v_mfma_f32_16x16x32_bf16 v[32:35], v[170:173], v[186:189], v[32:35]
	v_mfma_f32_16x16x32_bf16 v[24:27], v[162:165], v[216:219], v[24:27]
	v_mfma_f32_16x16x32_bf16 v[16:19], v[170:173], v[216:219], v[16:19]
	v_mfma_f32_16x16x32_bf16 v[8:11], v[162:165], v[236:239], v[8:11]
	v_mfma_f32_16x16x32_bf16 v[0:3], v[170:173], v[236:239], v[0:3]
	s_barrier
	s_add_i32 s74, 0, 0x18000
	s_add_i32 s75, 0, 0x1c000
	v_add_u32_e32 v154, s74, v140
	v_add_u32_e32 v170, s75, v140
	ds_read_b128 v[142:145], v154
	ds_read_b128 v[146:149], v154 offset:1024
	ds_read_b128 v[150:153], v154 offset:2048
	ds_read_b128 v[154:157], v154 offset:3072
	ds_read_b128 v[158:161], v170
	ds_read_b128 v[162:165], v170 offset:1024
	ds_read_b128 v[166:169], v170 offset:2048
	ds_read_b128 v[170:173], v170 offset:3072
	s_add_u32 s72, s78, 0x40000
	s_addc_u32 s73, s79, 0
	s_mov_b32 m0, s41
	v_lshl_add_u64 v[202:203], s[72:73], 0, v[132:133]
	ds_read_b128 v[174:177], v141 offset:32768
	ds_read_b128 v[178:181], v141 offset:33792
	ds_read_b128 v[182:185], v141 offset:34816
	ds_read_b128 v[186:189], v141 offset:35840
	ds_read_b128 v[212:215], v141 offset:36864
	ds_read_b128 v[216:219], v141 offset:37888
	ds_read_b128 v[232:235], v141 offset:38912
	ds_read_b128 v[236:239], v141 offset:39936
	global_load_lds_dwordx4 v[202:203], off
	v_lshl_add_u64 v[202:203], s[72:73], 0, v[130:131]
	s_mov_b32 m0, s46
	s_nop 0
	global_load_lds_dwordx4 v[202:203], off
	s_waitcnt vmcnt(8)
	s_waitcnt lgkmcnt(0)
	s_barrier
	s_waitcnt lgkmcnt(0)
	v_mfma_f32_16x16x32_bf16 v[124:127], v[142:145], v[174:177], v[124:127]
	v_mfma_f32_16x16x32_bf16 v[116:119], v[150:153], v[174:177], v[116:119]
	v_mfma_f32_16x16x32_bf16 v[108:111], v[142:145], v[182:185], v[108:111]
	v_mfma_f32_16x16x32_bf16 v[100:103], v[150:153], v[182:185], v[100:103]
	v_mfma_f32_16x16x32_bf16 v[92:95], v[142:145], v[212:215], v[92:95]
	v_mfma_f32_16x16x32_bf16 v[84:87], v[150:153], v[212:215], v[84:87]
	v_mfma_f32_16x16x32_bf16 v[76:79], v[142:145], v[232:235], v[76:79]
	v_mfma_f32_16x16x32_bf16 v[68:71], v[150:153], v[232:235], v[68:71]
	v_mfma_f32_16x16x32_bf16 v[124:127], v[146:149], v[178:181], v[124:127]
	v_mfma_f32_16x16x32_bf16 v[116:119], v[154:157], v[178:181], v[116:119]
	v_mfma_f32_16x16x32_bf16 v[108:111], v[146:149], v[186:189], v[108:111]
	v_mfma_f32_16x16x32_bf16 v[100:103], v[154:157], v[186:189], v[100:103]
	v_mfma_f32_16x16x32_bf16 v[92:95], v[146:149], v[216:219], v[92:95]
	v_mfma_f32_16x16x32_bf16 v[84:87], v[154:157], v[216:219], v[84:87]
	v_mfma_f32_16x16x32_bf16 v[76:79], v[146:149], v[236:239], v[76:79]
	v_mfma_f32_16x16x32_bf16 v[68:71], v[154:157], v[236:239], v[68:71]
	v_mfma_f32_16x16x32_bf16 v[120:123], v[158:161], v[174:177], v[120:123]
	v_mfma_f32_16x16x32_bf16 v[112:115], v[166:169], v[174:177], v[112:115]
	v_mfma_f32_16x16x32_bf16 v[104:107], v[158:161], v[182:185], v[104:107]
	v_mfma_f32_16x16x32_bf16 v[96:99], v[166:169], v[182:185], v[96:99]
	v_mfma_f32_16x16x32_bf16 v[88:91], v[158:161], v[212:215], v[88:91]
	v_mfma_f32_16x16x32_bf16 v[80:83], v[166:169], v[212:215], v[80:83]
	v_mfma_f32_16x16x32_bf16 v[72:75], v[158:161], v[232:235], v[72:75]
	v_mfma_f32_16x16x32_bf16 v[64:67], v[166:169], v[232:235], v[64:67]
	v_mfma_f32_16x16x32_bf16 v[120:123], v[162:165], v[178:181], v[120:123]
	v_mfma_f32_16x16x32_bf16 v[112:115], v[170:173], v[178:181], v[112:115]
	v_mfma_f32_16x16x32_bf16 v[104:107], v[162:165], v[186:189], v[104:107]
	v_mfma_f32_16x16x32_bf16 v[96:99], v[170:173], v[186:189], v[96:99]
	v_mfma_f32_16x16x32_bf16 v[88:91], v[162:165], v[216:219], v[88:91]
	v_mfma_f32_16x16x32_bf16 v[80:83], v[170:173], v[216:219], v[80:83]
	v_mfma_f32_16x16x32_bf16 v[72:75], v[162:165], v[236:239], v[72:75]
	v_mfma_f32_16x16x32_bf16 v[64:67], v[170:173], v[236:239], v[64:67]
	s_barrier
; #define PG8_STAGE(bufoff, gbase, voff) do { _Pragma("unroll") for (int _i = 0; _i < 2; ++_i) \
;         __builtin_amdgcn_global_load_lds((const unsigned*)((const char*)(gbase) + (voff)[_i]), (PG8_LAS unsigned*)(lds + (bufoff) + ldsw + _i * 8192), 16, 0, 0); } while (0)
; #define PG8_LDA(dst, b, h) do { _Pragma("unroll") for (int m = 0; m < 4; ++m) _Pragma("unroll") for (int k = 0; k < 2; ++k) dst[m][k] = *(const PG8_LAS bf16x8*)(lds + PG8_SA(b, h) + aoff + m * 2048 + k * 1024); } while (0)
; #define PG8_MMA(ai, bj, At, Bt) do { __builtin_amdgcn_s_setprio(1); _Pragma("unroll") for (int m = 0; m < 4; ++m) _Pragma("unroll") for (int n = 0; n < 2; ++n) _Pragma("unroll") for (int k = 0; k < 2; ++k) \
;         acc[ai][bj][m][n] = __builtin_amdgcn_mfma_f32_16x16x32_bf16(Bt[n][k], At[m][k], acc[ai][bj][m][n], 0, 0, 0); __builtin_amdgcn_s_setprio(0); } while (0)
; #define PG8_WAIT_V(n) asm volatile("s_waitcnt vmcnt(" #n ")" ::: "memory")
; #define PG8_WAIT_L(n) asm volatile("s_waitcnt lgkmcnt(" #n ")" ::: "memory")
; #define PG8_BAR __builtin_amdgcn_s_barrier()
; #define PG8_SCHED __builtin_amdgcn_sched_barrier(0)
; template <class Epi, class Sched, bool ALIGN_EPI = false, bool SP2 = false>
; __device__ __forceinline__ void gemm_phase(PG8_LAS unsigned char* lds, const Gemm g, const Sched& S, const Epi& E, const int tid) {
;     ...
;             PG8_LDA(At, 1, 1); PG8_STAGE(PG8_SB(1, 0), b3, voffB); PG8_STAGE(PG8_SB(1, 1), b3 + hstep, voffB); PG8_STAGE(PG8_SA(1, 0), a3, voffA);
;             PG8_WAIT_V(8); PG8_WAIT_L(0); PG8_BAR; PG8_MMA(1, 0, At, B0); PG8_MMA(1, 1, At, B1); PG8_BAR; PG8_SCHED;
	s_add_i32 s72, s74, s34
	v_lshl_add_u64 v[138:139], v[138:139], 0, s[36:37]
	s_mov_b32 m0, s72
	ds_read_b128 v[174:177], v141 offset:49152
	ds_read_b128 v[178:181], v141 offset:50176
	ds_read_b128 v[182:185], v141 offset:51200
	ds_read_b128 v[186:189], v141 offset:52224
	ds_read_b128 v[212:215], v141 offset:53248
	ds_read_b128 v[216:219], v141 offset:54272
	ds_read_b128 v[232:235], v141 offset:55296
	ds_read_b128 v[236:239], v141 offset:56320
	global_load_lds_dwordx4 v[138:139], off
	s_add_i32 m0, s72, 0x2000
	s_add_u32 s58, s58, 0x40080
	v_lshl_add_u64 v[138:139], v[190:191], 0, s[36:37]
	s_addc_u32 s59, s59, 0
	s_add_i32 s72, s75, s34
	global_load_lds_dwordx4 v[138:139], off
	v_lshl_add_u64 v[138:139], s[58:59], 0, v[192:193]
	s_mov_b32 m0, s72
	s_nop 0
	global_load_lds_dwordx4 v[138:139], off
	v_lshl_add_u64 v[138:139], s[58:59], 0, v[128:129]
	s_add_i32 m0, s72, 0x2000
	s_nop 0
	global_load_lds_dwordx4 v[138:139], off
	v_lshl_add_u64 v[138:139], v[194:195], 0, s[36:37]
	s_mov_b32 m0, s47
	s_nop 0
	global_load_lds_dwordx4 v[138:139], off
	v_lshl_add_u64 v[138:139], v[196:197], 0, s[36:37]
	s_mov_b32 m0, s52
	s_nop 0
	global_load_lds_dwordx4 v[138:139], off
	s_waitcnt vmcnt(8)
	s_waitcnt lgkmcnt(0)
	s_barrier
	s_waitcnt lgkmcnt(0)
	v_mfma_f32_16x16x32_bf16 v[60:63], v[142:145], v[174:177], v[60:63]
	v_mfma_f32_16x16x32_bf16 v[52:55], v[150:153], v[174:177], v[52:55]
	v_mfma_f32_16x16x32_bf16 v[44:47], v[142:145], v[182:185], v[44:47]
	v_mfma_f32_16x16x32_bf16 v[36:39], v[150:153], v[182:185], v[36:39]
	v_mfma_f32_16x16x32_bf16 v[28:31], v[142:145], v[212:215], v[28:31]
	v_mfma_f32_16x16x32_bf16 v[20:23], v[150:153], v[212:215], v[20:23]
	v_mfma_f32_16x16x32_bf16 v[12:15], v[142:145], v[232:235], v[12:15]
	v_mfma_f32_16x16x32_bf16 v[4:7], v[150:153], v[232:235], v[4:7]
	v_mfma_f32_16x16x32_bf16 v[60:63], v[146:149], v[178:181], v[60:63]
	v_mfma_f32_16x16x32_bf16 v[52:55], v[154:157], v[178:181], v[52:55]
	v_mfma_f32_16x16x32_bf16 v[44:47], v[146:149], v[186:189], v[44:47]
	v_mfma_f32_16x16x32_bf16 v[36:39], v[154:157], v[186:189], v[36:39]
	v_mfma_f32_16x16x32_bf16 v[28:31], v[146:149], v[216:219], v[28:31]
	v_mfma_f32_16x16x32_bf16 v[20:23], v[154:157], v[216:219], v[20:23]
	v_mfma_f32_16x16x32_bf16 v[12:15], v[146:149], v[236:239], v[12:15]
	v_mfma_f32_16x16x32_bf16 v[4:7], v[154:157], v[236:239], v[4:7]
	v_mfma_f32_16x16x32_bf16 v[56:59], v[158:161], v[174:177], v[56:59]
	v_mfma_f32_16x16x32_bf16 v[48:51], v[166:169], v[174:177], v[48:51]
	v_mfma_f32_16x16x32_bf16 v[40:43], v[158:161], v[182:185], v[40:43]
	v_mfma_f32_16x16x32_bf16 v[32:35], v[166:169], v[182:185], v[32:35]
	v_mfma_f32_16x16x32_bf16 v[24:27], v[158:161], v[212:215], v[24:27]
	v_mfma_f32_16x16x32_bf16 v[16:19], v[166:169], v[212:215], v[16:19]
	v_mfma_f32_16x16x32_bf16 v[8:11], v[158:161], v[232:235], v[8:11]
	v_mfma_f32_16x16x32_bf16 v[0:3], v[166:169], v[232:235], v[0:3]
	v_mfma_f32_16x16x32_bf16 v[56:59], v[162:165], v[178:181], v[56:59]
	v_mfma_f32_16x16x32_bf16 v[48:51], v[170:173], v[178:181], v[48:51]
	v_mfma_f32_16x16x32_bf16 v[40:43], v[162:165], v[186:189], v[40:43]
	v_mfma_f32_16x16x32_bf16 v[32:35], v[170:173], v[186:189], v[32:35]
	v_mfma_f32_16x16x32_bf16 v[24:27], v[162:165], v[216:219], v[24:27]
	v_mfma_f32_16x16x32_bf16 v[16:19], v[170:173], v[216:219], v[16:19]
	v_mfma_f32_16x16x32_bf16 v[8:11], v[162:165], v[236:239], v[8:11]
	v_mfma_f32_16x16x32_bf16 v[0:3], v[170:173], v[236:239], v[0:3]
	s_barrier
	s_add_i32 s71, s71, 2
	s_add_u32 s44, s44, 0x100
	s_addc_u32 s45, s45, 0
	s_add_u32 s62, s62, 0x100
	s_addc_u32 s70, s70, 0
	s_cmp_gt_u32 s71, 13
	s_cbranch_scc0 .LBB0_143
	s_and_b64 vcc, exec, s[10:11]
	s_cbranch_vccz .LBB0_146
	s_barrier

; #define PG8_STAGE(bufoff, gbase, voff) do { _Pragma("unroll") for (int _i = 0; _i < 2; ++_i) \
;         __builtin_amdgcn_global_load_lds((const unsigned*)((const char*)(gbase) + (voff)[_i]), (PG8_LAS unsigned*)(lds + (bufoff) + ldsw + _i * 8192), 16, 0, 0); } while (0)
; #define PG8_LDA(dst, b, h) do { _Pragma("unroll") for (int m = 0; m < 4; ++m) _Pragma("unroll") for (int k = 0; k < 2; ++k) dst[m][k] = *(const PG8_LAS bf16x8*)(lds + PG8_SA(b, h) + aoff + m * 2048 + k * 1024); } while (0)
; #define PG8_LDB(dst, b, h) do { _Pragma("unroll") for (int n = 0; n < 2; ++n) _Pragma("unroll") for (int k = 0; k < 2; ++k) dst[n][k] = *(const PG8_LAS bf16x8*)(lds + PG8_SB(b, h) + boff + n * 2048 + k * 1024); } while (0)
; #define PG8_MMA(ai, bj, At, Bt) do { __builtin_amdgcn_s_setprio(1); _Pragma("unroll") for (int m = 0; m < 4; ++m) _Pragma("unroll") for (int n = 0; n < 2; ++n) _Pragma("unroll") for (int k = 0; k < 2; ++k) \
;         acc[ai][bj][m][n] = __builtin_amdgcn_mfma_f32_16x16x32_bf16(Bt[n][k], At[m][k], acc[ai][bj][m][n], 0, 0, 0); __builtin_amdgcn_s_setprio(0); } while (0)
; #define PG8_WAIT_V(n) asm volatile("s_waitcnt vmcnt(" #n ")" ::: "memory")
; #define PG8_WAIT_L(n) asm volatile("s_waitcnt lgkmcnt(" #n ")" ::: "memory")
; #define PG8_BAR __builtin_amdgcn_s_barrier()
; #define PG8_SCHED __builtin_amdgcn_sched_barrier(0)
; template <class Epi, class Sched, bool ALIGN_EPI = false, bool SP2 = false>
; __device__ __forceinline__ void gemm_phase(PG8_LAS unsigned char* lds, const Gemm g, const Sched& S, const Epi& E, const int tid) {
;     ...
;             const bool last = (t == nt - 2);
;             const char* a1 = cA + (size_t)(t + 1) * kstep;
;             const char* a2 = last ? nA : cA + (size_t)(t + 2) * kstep; const char* b2 = last ? nB : cB + (size_t)(t + 2) * kstep;
;             const char* a3 = a2 + kstep; const char* b3 = b2 + kstep;
;             if (last && has_next) S.a_ready(nxt);
;             if constexpr (SP2) {
;             PG8_LDB(B0, 0, 0); PG8_LDB(B1, 0, 1); PG8_SCHED; PG8_LDA(At, 0, 0); PG8_STAGE(PG8_SA(1, 1), a1 + hstep, voffA);
;             PG8_WAIT_V(8); PG8_WAIT_L(0); PG8_BAR; PG8_MMA(0, 0, At, B0); PG8_MMA(0, 1, At, B1); PG8_BAR; PG8_SCHED;
;             PG8_LDA(At, 0, 1); PG8_STAGE(PG8_SB(0, 0), b2, voffB); PG8_STAGE(PG8_SB(0, 1), b2 + hstep, voffB); PG8_STAGE(PG8_SA(0, 0), a2, voffA);
.LBB0_183:
	s_add_u32 s28, s22, 0xfffc0080
	s_addc_u32 s29, s23, -1
	s_add_i32 s71, 0, 0x10000
	s_cmp_eq_u32 s70, 12
	s_cselect_b32 s45, s17, s29
	s_cselect_b32 s44, s58, s28
	s_cselect_b32 s29, s13, s62
	s_cselect_b32 s28, s59, s60
	s_add_i32 s74, 0, 0x14000
	v_add_u32_e32 v154, s71, v140
	v_add_u32_e32 v170, s74, v140
	ds_read_b128 v[142:145], v154
	ds_read_b128 v[146:149], v154 offset:1024
	ds_read_b128 v[150:153], v154 offset:2048
	ds_read_b128 v[154:157], v154 offset:3072
	ds_read_b128 v[158:161], v170
	ds_read_b128 v[162:165], v170 offset:1024
	ds_read_b128 v[166:169], v170 offset:2048
	ds_read_b128 v[170:173], v170 offset:3072
	v_lshl_add_u64 v[190:191], s[22:23], 0, v[136:137]
	s_add_i32 m0, s15, 0xc000
	ds_read_b128 v[174:177], v141
	ds_read_b128 v[178:181], v141 offset:1024
	ds_read_b128 v[182:185], v141 offset:2048
	ds_read_b128 v[186:189], v141 offset:3072
	ds_read_b128 v[212:215], v141 offset:4096
	ds_read_b128 v[216:219], v141 offset:5120
	ds_read_b128 v[232:235], v141 offset:6144
	ds_read_b128 v[236:239], v141 offset:7168
	global_load_lds_dwordx4 v[190:191], off
	v_lshl_add_u64 v[190:191], s[22:23], 0, v[138:139]
	s_add_i32 m0, s15, 0xe000
	s_nop 0
	global_load_lds_dwordx4 v[190:191], off
	s_waitcnt vmcnt(8)
	s_waitcnt lgkmcnt(0)
	s_barrier
	s_waitcnt lgkmcnt(0)
	v_mfma_f32_16x16x32_bf16 v[124:127], v[142:145], v[174:177], v[124:127]
	v_mfma_f32_16x16x32_bf16 v[120:123], v[150:153], v[174:177], v[120:123]
	v_mfma_f32_16x16x32_bf16 v[116:119], v[142:145], v[182:185], v[116:119]
	v_mfma_f32_16x16x32_bf16 v[112:115], v[150:153], v[182:185], v[112:115]
	v_mfma_f32_16x16x32_bf16 v[100:103], v[142:145], v[212:215], v[100:103]
	v_mfma_f32_16x16x32_bf16 v[96:99], v[150:153], v[212:215], v[96:99]
	v_mfma_f32_16x16x32_bf16 v[84:87], v[142:145], v[232:235], v[84:87]
	v_mfma_f32_16x16x32_bf16 v[80:83], v[150:153], v[232:235], v[80:83]
	v_mfma_f32_16x16x32_bf16 v[124:127], v[146:149], v[178:181], v[124:127]
	v_mfma_f32_16x16x32_bf16 v[120:123], v[154:157], v[178:181], v[120:123]
	v_mfma_f32_16x16x32_bf16 v[116:119], v[146:149], v[186:189], v[116:119]
	v_mfma_f32_16x16x32_bf16 v[112:115], v[154:157], v[186:189], v[112:115]
	v_mfma_f32_16x16x32_bf16 v[100:103], v[146:149], v[216:219], v[100:103]
	v_mfma_f32_16x16x32_bf16 v[96:99], v[154:157], v[216:219], v[96:99]
	v_mfma_f32_16x16x32_bf16 v[84:87], v[146:149], v[236:239], v[84:87]
	v_mfma_f32_16x16x32_bf16 v[80:83], v[154:157], v[236:239], v[80:83]
	v_mfma_f32_16x16x32_bf16 v[108:111], v[158:161], v[174:177], v[108:111]
	v_mfma_f32_16x16x32_bf16 v[104:107], v[166:169], v[174:177], v[104:107]
	v_mfma_f32_16x16x32_bf16 v[92:95], v[158:161], v[182:185], v[92:95]
	v_mfma_f32_16x16x32_bf16 v[88:91], v[166:169], v[182:185], v[88:91]
	v_mfma_f32_16x16x32_bf16 v[76:79], v[158:161], v[212:215], v[76:79]
	v_mfma_f32_16x16x32_bf16 v[72:75], v[166:169], v[212:215], v[72:75]
	v_mfma_f32_16x16x32_bf16 v[68:71], v[158:161], v[232:235], v[68:71]
	v_mfma_f32_16x16x32_bf16 v[64:67], v[166:169], v[232:235], v[64:67]
	v_mfma_f32_16x16x32_bf16 v[108:111], v[162:165], v[178:181], v[108:111]
	v_mfma_f32_16x16x32_bf16 v[104:107], v[170:173], v[178:181], v[104:107]
	v_mfma_f32_16x16x32_bf16 v[92:95], v[162:165], v[186:189], v[92:95]
	v_mfma_f32_16x16x32_bf16 v[88:91], v[170:173], v[186:189], v[88:91]
	v_mfma_f32_16x16x32_bf16 v[76:79], v[162:165], v[216:219], v[76:79]
	v_mfma_f32_16x16x32_bf16 v[72:75], v[170:173], v[216:219], v[72:75]
	v_mfma_f32_16x16x32_bf16 v[68:71], v[162:165], v[236:239], v[68:71]
	v_mfma_f32_16x16x32_bf16 v[64:67], v[170:173], v[236:239], v[64:67]
	s_barrier
	s_add_i32 s71, s71, s38
	v_lshl_add_u64 v[190:191], s[28:29], 0, v[192:193]
	s_mov_b32 m0, s71
	ds_read_b128 v[174:177], v141 offset:16384
	ds_read_b128 v[178:181], v141 offset:17408
	ds_read_b128 v[182:185], v141 offset:18432
	ds_read_b128 v[186:189], v141 offset:19456
	ds_read_b128 v[212:215], v141 offset:20480
	ds_read_b128 v[216:219], v141 offset:21504
	ds_read_b128 v[232:235], v141 offset:22528
	ds_read_b128 v[236:239], v141 offset:23552
	global_load_lds_dwordx4 v[190:191], off
	s_add_i32 m0, s71, 0x2000
	s_add_u32 s72, s28, 0x40000
	v_lshl_add_u64 v[194:195], s[28:29], 0, v[132:133]
	s_addc_u32 s73, s29, 0
	s_add_i32 s71, s74, s38
	global_load_lds_dwordx4 v[194:195], off
	v_lshl_add_u64 v[196:197], s[72:73], 0, v[192:193]
	s_mov_b32 m0, s71
	v_lshl_add_u64 v[202:203], s[44:45], 0, v[130:131]
	global_load_lds_dwordx4 v[196:197], off
	v_lshl_add_u64 v[196:197], s[72:73], 0, v[132:133]
	s_add_i32 m0, s71, 0x2000
	s_nop 0
	global_load_lds_dwordx4 v[196:197], off
	v_lshl_add_u64 v[196:197], s[44:45], 0, v[128:129]
	s_mov_b32 m0, s15
	s_nop 0
	global_load_lds_dwordx4 v[196:197], off
	s_mov_b32 m0, s40
	s_nop 0
	global_load_lds_dwordx4 v[202:203], off
	s_waitcnt vmcnt(8)
	s_waitcnt lgkmcnt(0)
	s_barrier
; #define PG8_STAGE(bufoff, gbase, voff) do { _Pragma("unroll") for (int _i = 0; _i < 2; ++_i) \
;         __builtin_amdgcn_global_load_lds((const unsigned*)((const char*)(gbase) + (voff)[_i]), (PG8_LAS unsigned*)(lds + (bufoff) + ldsw + _i * 8192), 16, 0, 0); } while (0)
; #define PG8_LDA(dst, b, h) do { _Pragma("unroll") for (int m = 0; m < 4; ++m) _Pragma("unroll") for (int k = 0; k < 2; ++k) dst[m][k] = *(const PG8_LAS bf16x8*)(lds + PG8_SA(b, h) + aoff + m * 2048 + k * 1024); } while (0)
; #define PG8_LDB(dst, b, h) do { _Pragma("unroll") for (int n = 0; n < 2; ++n) _Pragma("unroll") for (int k = 0; k < 2; ++k) dst[n][k] = *(const PG8_LAS bf16x8*)(lds + PG8_SB(b, h) + boff + n * 2048 + k * 1024); } while (0)
; #define PG8_MMA(ai, bj, At, Bt) do { __builtin_amdgcn_s_setprio(1); _Pragma("unroll") for (int m = 0; m < 4; ++m) _Pragma("unroll") for (int n = 0; n < 2; ++n) _Pragma("unroll") for (int k = 0; k < 2; ++k) \
;         acc[ai][bj][m][n] = __builtin_amdgcn_mfma_f32_16x16x32_bf16(Bt[n][k], At[m][k], acc[ai][bj][m][n], 0, 0, 0); __builtin_amdgcn_s_setprio(0); } while (0)
; #define PG8_WAIT_V(n) asm volatile("s_waitcnt vmcnt(" #n ")" ::: "memory")
; #define PG8_WAIT_L(n) asm volatile("s_waitcnt lgkmcnt(" #n ")" ::: "memory")
; #define PG8_BAR __builtin_amdgcn_s_barrier()
; #define PG8_SCHED __builtin_amdgcn_sched_barrier(0)
; template <class Epi, class Sched, bool ALIGN_EPI = false, bool SP2 = false>
; __device__ __forceinline__ void gemm_phase(PG8_LAS unsigned char* lds, const Gemm g, const Sched& S, const Epi& E, const int tid) {
;     ...
;             PG8_WAIT_V(8); PG8_WAIT_L(0); PG8_BAR; PG8_MMA(1, 0, At, B0); PG8_MMA(1, 1, At, B1); PG8_BAR; PG8_SCHED;
;             PG8_LDB(B0, 1, 0); PG8_LDB(B1, 1, 1); PG8_SCHED; PG8_LDA(At, 1, 0); PG8_STAGE(PG8_SA(0, 1), a2 + hstep, voffA);
;             PG8_WAIT_V(8); PG8_WAIT_L(0); PG8_BAR; PG8_MMA(0, 0, At, B0); PG8_MMA(0, 1, At, B1); PG8_BAR; PG8_SCHED;
	s_waitcnt lgkmcnt(0)
	v_mfma_f32_16x16x32_bf16 v[60:63], v[142:145], v[174:177], v[60:63]
	v_mfma_f32_16x16x32_bf16 v[56:59], v[150:153], v[174:177], v[56:59]
	v_mfma_f32_16x16x32_bf16 v[52:55], v[142:145], v[182:185], v[52:55]
	v_mfma_f32_16x16x32_bf16 v[48:51], v[150:153], v[182:185], v[48:51]
	v_mfma_f32_16x16x32_bf16 v[36:39], v[142:145], v[212:215], v[36:39]
	v_mfma_f32_16x16x32_bf16 v[32:35], v[150:153], v[212:215], v[32:35]
	v_mfma_f32_16x16x32_bf16 v[20:23], v[142:145], v[232:235], v[20:23]
	v_mfma_f32_16x16x32_bf16 v[16:19], v[150:153], v[232:235], v[16:19]
	v_mfma_f32_16x16x32_bf16 v[60:63], v[146:149], v[178:181], v[60:63]
	v_mfma_f32_16x16x32_bf16 v[56:59], v[154:157], v[178:181], v[56:59]
	v_mfma_f32_16x16x32_bf16 v[52:55], v[146:149], v[186:189], v[52:55]
	v_mfma_f32_16x16x32_bf16 v[48:51], v[154:157], v[186:189], v[48:51]
	v_mfma_f32_16x16x32_bf16 v[36:39], v[146:149], v[216:219], v[36:39]
	v_mfma_f32_16x16x32_bf16 v[32:35], v[154:157], v[216:219], v[32:35]
	v_mfma_f32_16x16x32_bf16 v[20:23], v[146:149], v[236:239], v[20:23]
	v_mfma_f32_16x16x32_bf16 v[16:19], v[154:157], v[236:239], v[16:19]
	v_mfma_f32_16x16x32_bf16 v[44:47], v[158:161], v[174:177], v[44:47]
	v_mfma_f32_16x16x32_bf16 v[40:43], v[166:169], v[174:177], v[40:43]
	v_mfma_f32_16x16x32_bf16 v[28:31], v[158:161], v[182:185], v[28:31]
	v_mfma_f32_16x16x32_bf16 v[24:27], v[166:169], v[182:185], v[24:27]
	v_mfma_f32_16x16x32_bf16 v[12:15], v[158:161], v[212:215], v[12:15]
	v_mfma_f32_16x16x32_bf16 v[8:11], v[166:169], v[212:215], v[8:11]
	v_mfma_f32_16x16x32_bf16 v[4:7], v[158:161], v[232:235], v[4:7]
	v_mfma_f32_16x16x32_bf16 v[0:3], v[166:169], v[232:235], v[0:3]
	v_mfma_f32_16x16x32_bf16 v[44:47], v[162:165], v[178:181], v[44:47]
	v_mfma_f32_16x16x32_bf16 v[40:43], v[170:173], v[178:181], v[40:43]
	v_mfma_f32_16x16x32_bf16 v[28:31], v[162:165], v[186:189], v[28:31]
	v_mfma_f32_16x16x32_bf16 v[24:27], v[170:173], v[186:189], v[24:27]
	v_mfma_f32_16x16x32_bf16 v[12:15], v[162:165], v[216:219], v[12:15]
	v_mfma_f32_16x16x32_bf16 v[8:11], v[170:173], v[216:219], v[8:11]
	v_mfma_f32_16x16x32_bf16 v[4:7], v[162:165], v[236:239], v[4:7]
	v_mfma_f32_16x16x32_bf16 v[0:3], v[170:173], v[236:239], v[0:3]
	s_barrier
	s_add_i32 s71, 0, 0x18000
	s_add_i32 s72, 0, 0x1c000
	v_add_u32_e32 v154, s71, v140
	v_add_u32_e32 v170, s72, v140
	ds_read_b128 v[142:145], v154
	ds_read_b128 v[146:149], v154 offset:1024
	ds_read_b128 v[150:153], v154 offset:2048
	ds_read_b128 v[154:157], v154 offset:3072
	ds_read_b128 v[158:161], v170
	ds_read_b128 v[162:165], v170 offset:1024
	ds_read_b128 v[166:169], v170 offset:2048
	ds_read_b128 v[170:173], v170 offset:3072
	s_add_u32 s44, s44, 0x40000
	s_addc_u32 s45, s45, 0
	s_mov_b32 m0, s41
	v_lshl_add_u64 v[204:205], s[44:45], 0, v[128:129]
	ds_read_b128 v[174:177], v141 offset:32768
	ds_read_b128 v[178:181], v141 offset:33792
	ds_read_b128 v[182:185], v141 offset:34816
	ds_read_b128 v[186:189], v141 offset:35840
	ds_read_b128 v[212:215], v141 offset:36864
	ds_read_b128 v[216:219], v141 offset:37888
	ds_read_b128 v[232:235], v141 offset:38912
	ds_read_b128 v[236:239], v141 offset:39936
	global_load_lds_dwordx4 v[204:205], off
	v_lshl_add_u64 v[204:205], s[44:45], 0, v[130:131]
	s_mov_b32 m0, s46
	s_nop 0
	global_load_lds_dwordx4 v[204:205], off
	s_waitcnt vmcnt(8)
	s_waitcnt lgkmcnt(0)
	s_barrier
	s_waitcnt lgkmcnt(0)
	v_mfma_f32_16x16x32_bf16 v[124:127], v[142:145], v[174:177], v[124:127]
	v_mfma_f32_16x16x32_bf16 v[120:123], v[150:153], v[174:177], v[120:123]
	v_mfma_f32_16x16x32_bf16 v[116:119], v[142:145], v[182:185], v[116:119]
	v_mfma_f32_16x16x32_bf16 v[112:115], v[150:153], v[182:185], v[112:115]
	v_mfma_f32_16x16x32_bf16 v[100:103], v[142:145], v[212:215], v[100:103]
	v_mfma_f32_16x16x32_bf16 v[96:99], v[150:153], v[212:215], v[96:99]
	v_mfma_f32_16x16x32_bf16 v[84:87], v[142:145], v[232:235], v[84:87]
	v_mfma_f32_16x16x32_bf16 v[80:83], v[150:153], v[232:235], v[80:83]
	v_mfma_f32_16x16x32_bf16 v[124:127], v[146:149], v[178:181], v[124:127]
	v_mfma_f32_16x16x32_bf16 v[120:123], v[154:157], v[178:181], v[120:123]
	v_mfma_f32_16x16x32_bf16 v[116:119], v[146:149], v[186:189], v[116:119]
	v_mfma_f32_16x16x32_bf16 v[112:115], v[154:157], v[186:189], v[112:115]
	v_mfma_f32_16x16x32_bf16 v[100:103], v[146:149], v[216:219], v[100:103]
	v_mfma_f32_16x16x32_bf16 v[96:99], v[154:157], v[216:219], v[96:99]
	v_mfma_f32_16x16x32_bf16 v[84:87], v[146:149], v[236:239], v[84:87]
	v_mfma_f32_16x16x32_bf16 v[80:83], v[154:157], v[236:239], v[80:83]
	v_mfma_f32_16x16x32_bf16 v[108:111], v[158:161], v[174:177], v[108:111]
	v_mfma_f32_16x16x32_bf16 v[104:107], v[166:169], v[174:177], v[104:107]
	v_mfma_f32_16x16x32_bf16 v[92:95], v[158:161], v[182:185], v[92:95]
	v_mfma_f32_16x16x32_bf16 v[88:91], v[166:169], v[182:185], v[88:91]
	v_mfma_f32_16x16x32_bf16 v[76:79], v[158:161], v[212:215], v[76:79]
	v_mfma_f32_16x16x32_bf16 v[72:75], v[166:169], v[212:215], v[72:75]
	v_mfma_f32_16x16x32_bf16 v[68:71], v[158:161], v[232:235], v[68:71]
	v_mfma_f32_16x16x32_bf16 v[64:67], v[166:169], v[232:235], v[64:67]
	v_mfma_f32_16x16x32_bf16 v[108:111], v[162:165], v[178:181], v[108:111]
	v_mfma_f32_16x16x32_bf16 v[104:107], v[170:173], v[178:181], v[104:107]
	v_mfma_f32_16x16x32_bf16 v[92:95], v[162:165], v[186:189], v[92:95]
	v_mfma_f32_16x16x32_bf16 v[88:91], v[170:173], v[186:189], v[88:91]
	v_mfma_f32_16x16x32_bf16 v[76:79], v[162:165], v[216:219], v[76:79]
	v_mfma_f32_16x16x32_bf16 v[72:75], v[170:173], v[216:219], v[72:75]
	v_mfma_f32_16x16x32_bf16 v[68:71], v[162:165], v[236:239], v[68:71]
	v_mfma_f32_16x16x32_bf16 v[64:67], v[170:173], v[236:239], v[64:67]
	s_barrier
; #define PG8_STAGE(bufoff, gbase, voff) do { _Pragma("unroll") for (int _i = 0; _i < 2; ++_i) \
;         __builtin_amdgcn_global_load_lds((const unsigned*)((const char*)(gbase) + (voff)[_i]), (PG8_LAS unsigned*)(lds + (bufoff) + ldsw + _i * 8192), 16, 0, 0); } while (0)
; #define PG8_LDA(dst, b, h) do { _Pragma("unroll") for (int m = 0; m < 4; ++m) _Pragma("unroll") for (int k = 0; k < 2; ++k) dst[m][k] = *(const PG8_LAS bf16x8*)(lds + PG8_SA(b, h) + aoff + m * 2048 + k * 1024); } while (0)
; #define PG8_MMA(ai, bj, At, Bt) do { __builtin_amdgcn_s_setprio(1); _Pragma("unroll") for (int m = 0; m < 4; ++m) _Pragma("unroll") for (int n = 0; n < 2; ++n) _Pragma("unroll") for (int k = 0; k < 2; ++k) \
;         acc[ai][bj][m][n] = __builtin_amdgcn_mfma_f32_16x16x32_bf16(Bt[n][k], At[m][k], acc[ai][bj][m][n], 0, 0, 0); __builtin_amdgcn_s_setprio(0); } while (0)
; #define PG8_WAIT_V(n) asm volatile("s_waitcnt vmcnt(" #n ")" ::: "memory")
; #define PG8_WAIT_L(n) asm volatile("s_waitcnt lgkmcnt(" #n ")" ::: "memory")
; #define PG8_BAR __builtin_amdgcn_s_barrier()
; #define PG8_SCHED __builtin_amdgcn_sched_barrier(0)
; template <class Epi, class Sched, bool ALIGN_EPI = false, bool SP2 = false>
; __device__ __forceinline__ void gemm_phase(PG8_LAS unsigned char* lds, const Gemm g, const Sched& S, const Epi& E, const int tid) {
;     ...
;             PG8_LDA(At, 1, 1); PG8_STAGE(PG8_SB(1, 0), b3, voffB); PG8_STAGE(PG8_SB(1, 1), b3 + hstep, voffB); PG8_STAGE(PG8_SA(1, 0), a3, voffA);
;             PG8_WAIT_V(8); PG8_WAIT_L(0); PG8_BAR; PG8_MMA(1, 0, At, B0); PG8_MMA(1, 1, At, B1); PG8_BAR; PG8_SCHED;
	s_add_i32 s44, s71, s38
	v_lshl_add_u64 v[190:191], v[190:191], 0, s[36:37]
	s_mov_b32 m0, s44
	ds_read_b128 v[174:177], v141 offset:49152
	ds_read_b128 v[178:181], v141 offset:50176
	ds_read_b128 v[182:185], v141 offset:51200
	ds_read_b128 v[186:189], v141 offset:52224
	ds_read_b128 v[212:215], v141 offset:53248
	ds_read_b128 v[216:219], v141 offset:54272
	ds_read_b128 v[232:235], v141 offset:55296
	ds_read_b128 v[236:239], v141 offset:56320
	global_load_lds_dwordx4 v[190:191], off
	s_add_i32 m0, s44, 0x2000
	s_add_u32 s28, s28, 0x40080
	v_lshl_add_u64 v[190:191], v[194:195], 0, s[36:37]
	s_addc_u32 s29, s29, 0
	s_add_i32 s44, s72, s38
	global_load_lds_dwordx4 v[190:191], off
	v_lshl_add_u64 v[190:191], s[28:29], 0, v[192:193]
	s_mov_b32 m0, s44
	s_nop 0
	global_load_lds_dwordx4 v[190:191], off
	v_lshl_add_u64 v[190:191], s[28:29], 0, v[132:133]
	s_add_i32 m0, s44, 0x2000
	s_nop 0
	global_load_lds_dwordx4 v[190:191], off
	v_lshl_add_u64 v[190:191], v[196:197], 0, s[36:37]
	s_mov_b32 m0, s47
	s_nop 0
	global_load_lds_dwordx4 v[190:191], off
	v_lshl_add_u64 v[190:191], v[202:203], 0, s[36:37]
	s_mov_b32 m0, s52
	s_nop 0
	global_load_lds_dwordx4 v[190:191], off
	s_waitcnt vmcnt(8)
	s_waitcnt lgkmcnt(0)
	s_barrier
	s_waitcnt lgkmcnt(0)
	v_mfma_f32_16x16x32_bf16 v[60:63], v[142:145], v[174:177], v[60:63]
	v_mfma_f32_16x16x32_bf16 v[56:59], v[150:153], v[174:177], v[56:59]
	v_mfma_f32_16x16x32_bf16 v[52:55], v[142:145], v[182:185], v[52:55]
	v_mfma_f32_16x16x32_bf16 v[48:51], v[150:153], v[182:185], v[48:51]
	v_mfma_f32_16x16x32_bf16 v[36:39], v[142:145], v[212:215], v[36:39]
	v_mfma_f32_16x16x32_bf16 v[32:35], v[150:153], v[212:215], v[32:35]
	v_mfma_f32_16x16x32_bf16 v[20:23], v[142:145], v[232:235], v[20:23]
	v_mfma_f32_16x16x32_bf16 v[16:19], v[150:153], v[232:235], v[16:19]
	v_mfma_f32_16x16x32_bf16 v[60:63], v[146:149], v[178:181], v[60:63]
	v_mfma_f32_16x16x32_bf16 v[56:59], v[154:157], v[178:181], v[56:59]
	v_mfma_f32_16x16x32_bf16 v[52:55], v[146:149], v[186:189], v[52:55]
	v_mfma_f32_16x16x32_bf16 v[48:51], v[154:157], v[186:189], v[48:51]
	v_mfma_f32_16x16x32_bf16 v[36:39], v[146:149], v[216:219], v[36:39]
	v_mfma_f32_16x16x32_bf16 v[32:35], v[154:157], v[216:219], v[32:35]
	v_mfma_f32_16x16x32_bf16 v[20:23], v[146:149], v[236:239], v[20:23]
	v_mfma_f32_16x16x32_bf16 v[16:19], v[154:157], v[236:239], v[16:19]
	v_mfma_f32_16x16x32_bf16 v[44:47], v[158:161], v[174:177], v[44:47]
	v_mfma_f32_16x16x32_bf16 v[40:43], v[166:169], v[174:177], v[40:43]
	v_mfma_f32_16x16x32_bf16 v[28:31], v[158:161], v[182:185], v[28:31]
	v_mfma_f32_16x16x32_bf16 v[24:27], v[166:169], v[182:185], v[24:27]
	v_mfma_f32_16x16x32_bf16 v[12:15], v[158:161], v[212:215], v[12:15]
	v_mfma_f32_16x16x32_bf16 v[8:11], v[166:169], v[212:215], v[8:11]
	v_mfma_f32_16x16x32_bf16 v[4:7], v[158:161], v[232:235], v[4:7]
	v_mfma_f32_16x16x32_bf16 v[0:3], v[166:169], v[232:235], v[0:3]
	v_mfma_f32_16x16x32_bf16 v[44:47], v[162:165], v[178:181], v[44:47]
	v_mfma_f32_16x16x32_bf16 v[40:43], v[170:173], v[178:181], v[40:43]
	v_mfma_f32_16x16x32_bf16 v[28:31], v[162:165], v[186:189], v[28:31]
	v_mfma_f32_16x16x32_bf16 v[24:27], v[170:173], v[186:189], v[24:27]
	v_mfma_f32_16x16x32_bf16 v[12:15], v[162:165], v[216:219], v[12:15]
	v_mfma_f32_16x16x32_bf16 v[8:11], v[170:173], v[216:219], v[8:11]
	v_mfma_f32_16x16x32_bf16 v[4:7], v[162:165], v[236:239], v[4:7]
	v_mfma_f32_16x16x32_bf16 v[0:3], v[170:173], v[236:239], v[0:3]
	s_barrier
	s_add_i32 s70, s70, 2
	s_add_u32 s22, s22, 0x100
	s_addc_u32 s23, s23, 0
	s_add_u32 s60, s60, 0x100
	s_addc_u32 s62, s62, 0
	s_cmp_gt_u32 s70, 13
	s_cbranch_scc0 .LBB0_183
	s_and_b64 vcc, exec, s[10:11]
	s_cbranch_vccz .LBB0_186
	s_barrier

; #define PG8_STAGE(bufoff, gbase, voff) do { _Pragma("unroll") for (int _i = 0; _i < 2; ++_i) \
;         __builtin_amdgcn_global_load_lds((const unsigned*)((const char*)(gbase) + (voff)[_i]), (PG8_LAS unsigned*)(lds + (bufoff) + ldsw + _i * 8192), 16, 0, 0); } while (0)
; #define PG8_LDA(dst, b, h) do { _Pragma("unroll") for (int m = 0; m < 4; ++m) _Pragma("unroll") for (int k = 0; k < 2; ++k) dst[m][k] = *(const PG8_LAS bf16x8*)(lds + PG8_SA(b, h) + aoff + m * 2048 + k * 1024); } while (0)
; #define PG8_LDB(dst, b, h) do { _Pragma("unroll") for (int n = 0; n < 2; ++n) _Pragma("unroll") for (int k = 0; k < 2; ++k) dst[n][k] = *(const PG8_LAS bf16x8*)(lds + PG8_SB(b, h) + boff + n * 2048 + k * 1024); } while (0)
; #define PG8_MMA(ai, bj, At, Bt) do { __builtin_amdgcn_s_setprio(1); _Pragma("unroll") for (int m = 0; m < 4; ++m) _Pragma("unroll") for (int n = 0; n < 2; ++n) _Pragma("unroll") for (int k = 0; k < 2; ++k) \
;         acc[ai][bj][m][n] = __builtin_amdgcn_mfma_f32_16x16x32_bf16(Bt[n][k], At[m][k], acc[ai][bj][m][n], 0, 0, 0); __builtin_amdgcn_s_setprio(0); } while (0)
; #define PG8_WAIT_V(n) asm volatile("s_waitcnt vmcnt(" #n ")" ::: "memory")
; #define PG8_WAIT_L(n) asm volatile("s_waitcnt lgkmcnt(" #n ")" ::: "memory")
; #define PG8_BAR __builtin_amdgcn_s_barrier()
; #define PG8_SCHED __builtin_amdgcn_sched_barrier(0)
; template <class Epi, class Sched, bool ALIGN_EPI = false, bool SP2 = false>
; __device__ __forceinline__ void gemm_phase(PG8_LAS unsigned char* lds, const Gemm g, const Sched& S, const Epi& E, const int tid) {
;     ...
;             const bool last = (t == nt - 2);
;             const char* a1 = cA + (size_t)(t + 1) * kstep;
;             const char* a2 = last ? nA : cA + (size_t)(t + 2) * kstep; const char* b2 = last ? nB : cB + (size_t)(t + 2) * kstep;
;             const char* a3 = a2 + kstep; const char* b3 = b2 + kstep;
;             if (last && has_next) S.a_ready(nxt);
;             if constexpr (SP2) {
;             PG8_LDB(B0, 0, 0); PG8_LDB(B1, 0, 1); PG8_SCHED; PG8_LDA(At, 0, 0); PG8_STAGE(PG8_SA(1, 1), a1 + hstep, voffA);
;             PG8_WAIT_V(8); PG8_WAIT_L(0); PG8_BAR; PG8_MMA(0, 0, At, B0); PG8_MMA(0, 1, At, B1); PG8_BAR; PG8_SCHED;
;             PG8_LDA(At, 0, 1); PG8_STAGE(PG8_SB(0, 0), b2, voffB); PG8_STAGE(PG8_SB(0, 1), b2 + hstep, voffB); PG8_STAGE(PG8_SA(0, 0), a2, voffA);
.LBB0_239:
	s_add_u32 s58, s10, s44
	s_addc_u32 s59, s11, s45
	s_add_u32 s58, s58, 0x100
	s_addc_u32 s59, s59, 0
	s_add_u32 s73, s19, s44
	s_addc_u32 s74, s62, s45
	s_waitcnt lgkmcnt(0)
	s_add_i32 s75, 0, 0x10000
	s_cmpk_eq_i32 s44, 0x700
	s_cselect_b32 s79, s15, s59
	s_cselect_b32 s78, s70, s58
	s_cselect_b32 s59, s13, s74
	s_cselect_b32 s58, s71, s73
	s_add_i32 s73, 0, 0x14000
	v_add_u32_e32 v156, s75, v142
	v_add_u32_e32 v172, s73, v142
	ds_read_b128 v[144:147], v156
	ds_read_b128 v[148:151], v156 offset:1024
	ds_read_b128 v[152:155], v156 offset:2048
	ds_read_b128 v[156:159], v156 offset:3072
	ds_read_b128 v[160:163], v172
	ds_read_b128 v[164:167], v172 offset:1024
	ds_read_b128 v[168:171], v172 offset:2048
	ds_read_b128 v[172:175], v172 offset:3072
	v_lshl_add_u64 v[194:195], v[138:139], 0, s[44:45]
	s_add_i32 m0, s46, 0xc000
	ds_read_b128 v[176:179], v143
	ds_read_b128 v[180:183], v143 offset:1024
	ds_read_b128 v[184:187], v143 offset:2048
	ds_read_b128 v[188:191], v143 offset:3072
	ds_read_b128 v[212:215], v143 offset:4096
	ds_read_b128 v[216:219], v143 offset:5120
	ds_read_b128 v[234:237], v143 offset:6144
	ds_read_b128 v[238:241], v143 offset:7168
	global_load_lds_dwordx4 v[194:195], off
	v_lshl_add_u64 v[194:195], v[140:141], 0, s[44:45]
	s_add_i32 m0, s46, 0xe000
	s_nop 0
	global_load_lds_dwordx4 v[194:195], off
	s_waitcnt vmcnt(8)
	s_waitcnt lgkmcnt(0)
	s_barrier
	s_waitcnt lgkmcnt(0)
	v_mfma_f32_16x16x32_bf16 v[76:79], v[144:147], v[176:179], v[76:79]
	v_mfma_f32_16x16x32_bf16 v[72:75], v[152:155], v[176:179], v[72:75]
	v_mfma_f32_16x16x32_bf16 v[100:103], v[144:147], v[184:187], v[100:103]
	v_mfma_f32_16x16x32_bf16 v[96:99], v[152:155], v[184:187], v[96:99]
	v_mfma_f32_16x16x32_bf16 v[124:127], v[144:147], v[212:215], v[124:127]
	v_mfma_f32_16x16x32_bf16 v[120:123], v[152:155], v[212:215], v[120:123]
	v_mfma_f32_16x16x32_bf16 v[92:95], v[144:147], v[234:237], v[92:95]
	v_mfma_f32_16x16x32_bf16 v[84:87], v[152:155], v[234:237], v[84:87]
	v_mfma_f32_16x16x32_bf16 v[76:79], v[148:151], v[180:183], v[76:79]
	v_mfma_f32_16x16x32_bf16 v[72:75], v[156:159], v[180:183], v[72:75]
	v_mfma_f32_16x16x32_bf16 v[100:103], v[148:151], v[188:191], v[100:103]
	v_mfma_f32_16x16x32_bf16 v[96:99], v[156:159], v[188:191], v[96:99]
	v_mfma_f32_16x16x32_bf16 v[124:127], v[148:151], v[216:219], v[124:127]
	v_mfma_f32_16x16x32_bf16 v[120:123], v[156:159], v[216:219], v[120:123]
	v_mfma_f32_16x16x32_bf16 v[92:95], v[148:151], v[238:241], v[92:95]
	v_mfma_f32_16x16x32_bf16 v[84:87], v[156:159], v[238:241], v[84:87]
	v_mfma_f32_16x16x32_bf16 v[80:83], v[160:163], v[176:179], v[80:83]
	v_mfma_f32_16x16x32_bf16 v[88:91], v[168:171], v[176:179], v[88:91]
	v_mfma_f32_16x16x32_bf16 v[108:111], v[160:163], v[184:187], v[108:111]
	v_mfma_f32_16x16x32_bf16 v[116:119], v[168:171], v[184:187], v[116:119]
	v_mfma_f32_16x16x32_bf16 v[112:115], v[160:163], v[212:215], v[112:115]
	v_mfma_f32_16x16x32_bf16 v[104:107], v[168:171], v[212:215], v[104:107]
	v_mfma_f32_16x16x32_bf16 v[68:71], v[160:163], v[234:237], v[68:71]
	v_mfma_f32_16x16x32_bf16 v[64:67], v[168:171], v[234:237], v[64:67]
	v_mfma_f32_16x16x32_bf16 v[80:83], v[164:167], v[180:183], v[80:83]
	v_mfma_f32_16x16x32_bf16 v[88:91], v[172:175], v[180:183], v[88:91]
	v_mfma_f32_16x16x32_bf16 v[108:111], v[164:167], v[188:191], v[108:111]
	v_mfma_f32_16x16x32_bf16 v[116:119], v[172:175], v[188:191], v[116:119]
	v_mfma_f32_16x16x32_bf16 v[112:115], v[164:167], v[216:219], v[112:115]
	v_mfma_f32_16x16x32_bf16 v[104:107], v[172:175], v[216:219], v[104:107]
	v_mfma_f32_16x16x32_bf16 v[68:71], v[164:167], v[238:241], v[68:71]
	v_mfma_f32_16x16x32_bf16 v[64:67], v[172:175], v[238:241], v[64:67]
	s_barrier
	s_add_i32 s74, s75, s41
	v_lshl_add_u64 v[194:195], s[58:59], 0, v[192:193]
	s_mov_b32 m0, s74
	ds_read_b128 v[176:179], v143 offset:16384
	ds_read_b128 v[180:183], v143 offset:17408
	ds_read_b128 v[184:187], v143 offset:18432
	ds_read_b128 v[188:191], v143 offset:19456
	ds_read_b128 v[212:215], v143 offset:20480
	ds_read_b128 v[216:219], v143 offset:21504
	ds_read_b128 v[234:237], v143 offset:22528
	ds_read_b128 v[238:241], v143 offset:23552
	global_load_lds_dwordx4 v[194:195], off
	s_add_i32 m0, s74, 0x2000
	s_add_u32 s74, s58, 0x40000
	v_lshl_add_u64 v[196:197], s[58:59], 0, v[132:133]
	s_addc_u32 s75, s59, 0
	s_add_i32 s73, s73, s41
	global_load_lds_dwordx4 v[196:197], off
	v_lshl_add_u64 v[202:203], s[74:75], 0, v[192:193]
	s_mov_b32 m0, s73
	v_lshl_add_u64 v[204:205], s[78:79], 0, v[130:131]
	global_load_lds_dwordx4 v[202:203], off
	v_lshl_add_u64 v[202:203], s[74:75], 0, v[132:133]
	s_add_i32 m0, s73, 0x2000
	s_nop 0
	global_load_lds_dwordx4 v[202:203], off
	v_lshl_add_u64 v[202:203], s[78:79], 0, v[128:129]
	s_mov_b32 m0, s46
	s_nop 0
	global_load_lds_dwordx4 v[202:203], off
	s_mov_b32 m0, s47
	s_nop 0
	global_load_lds_dwordx4 v[204:205], off
	s_waitcnt vmcnt(8)
	s_waitcnt lgkmcnt(0)
	s_barrier
; #define PG8_STAGE(bufoff, gbase, voff) do { _Pragma("unroll") for (int _i = 0; _i < 2; ++_i) \
;         __builtin_amdgcn_global_load_lds((const unsigned*)((const char*)(gbase) + (voff)[_i]), (PG8_LAS unsigned*)(lds + (bufoff) + ldsw + _i * 8192), 16, 0, 0); } while (0)
; #define PG8_LDA(dst, b, h) do { _Pragma("unroll") for (int m = 0; m < 4; ++m) _Pragma("unroll") for (int k = 0; k < 2; ++k) dst[m][k] = *(const PG8_LAS bf16x8*)(lds + PG8_SA(b, h) + aoff + m * 2048 + k * 1024); } while (0)
; #define PG8_LDB(dst, b, h) do { _Pragma("unroll") for (int n = 0; n < 2; ++n) _Pragma("unroll") for (int k = 0; k < 2; ++k) dst[n][k] = *(const PG8_LAS bf16x8*)(lds + PG8_SB(b, h) + boff + n * 2048 + k * 1024); } while (0)
; #define PG8_MMA(ai, bj, At, Bt) do { __builtin_amdgcn_s_setprio(1); _Pragma("unroll") for (int m = 0; m < 4; ++m) _Pragma("unroll") for (int n = 0; n < 2; ++n) _Pragma("unroll") for (int k = 0; k < 2; ++k) \
;         acc[ai][bj][m][n] = __builtin_amdgcn_mfma_f32_16x16x32_bf16(Bt[n][k], At[m][k], acc[ai][bj][m][n], 0, 0, 0); __builtin_amdgcn_s_setprio(0); } while (0)
; #define PG8_WAIT_V(n) asm volatile("s_waitcnt vmcnt(" #n ")" ::: "memory")
; #define PG8_WAIT_L(n) asm volatile("s_waitcnt lgkmcnt(" #n ")" ::: "memory")
; #define PG8_BAR __builtin_amdgcn_s_barrier()
; #define PG8_SCHED __builtin_amdgcn_sched_barrier(0)
; template <class Epi, class Sched, bool ALIGN_EPI = false, bool SP2 = false>
; __device__ __forceinline__ void gemm_phase(PG8_LAS unsigned char* lds, const Gemm g, const Sched& S, const Epi& E, const int tid) {
;     ...
;             PG8_WAIT_V(8); PG8_WAIT_L(0); PG8_BAR; PG8_MMA(1, 0, At, B0); PG8_MMA(1, 1, At, B1); PG8_BAR; PG8_SCHED;
;             PG8_LDB(B0, 1, 0); PG8_LDB(B1, 1, 1); PG8_SCHED; PG8_LDA(At, 1, 0); PG8_STAGE(PG8_SA(0, 1), a2 + hstep, voffA);
;             PG8_WAIT_V(8); PG8_WAIT_L(0); PG8_BAR; PG8_MMA(0, 0, At, B0); PG8_MMA(0, 1, At, B1); PG8_BAR; PG8_SCHED;
	s_waitcnt lgkmcnt(0)
	v_mfma_f32_16x16x32_bf16 v[60:63], v[144:147], v[176:179], v[60:63]
	v_mfma_f32_16x16x32_bf16 v[56:59], v[152:155], v[176:179], v[56:59]
	v_mfma_f32_16x16x32_bf16 v[44:47], v[144:147], v[184:187], v[44:47]
	v_mfma_f32_16x16x32_bf16 v[40:43], v[152:155], v[184:187], v[40:43]
	v_mfma_f32_16x16x32_bf16 v[28:31], v[144:147], v[212:215], v[28:31]
	v_mfma_f32_16x16x32_bf16 v[24:27], v[152:155], v[212:215], v[24:27]
	v_mfma_f32_16x16x32_bf16 v[12:15], v[144:147], v[234:237], v[12:15]
	v_mfma_f32_16x16x32_bf16 v[8:11], v[152:155], v[234:237], v[8:11]
	v_mfma_f32_16x16x32_bf16 v[60:63], v[148:151], v[180:183], v[60:63]
	v_mfma_f32_16x16x32_bf16 v[56:59], v[156:159], v[180:183], v[56:59]
	v_mfma_f32_16x16x32_bf16 v[44:47], v[148:151], v[188:191], v[44:47]
	v_mfma_f32_16x16x32_bf16 v[40:43], v[156:159], v[188:191], v[40:43]
	v_mfma_f32_16x16x32_bf16 v[28:31], v[148:151], v[216:219], v[28:31]
	v_mfma_f32_16x16x32_bf16 v[24:27], v[156:159], v[216:219], v[24:27]
	v_mfma_f32_16x16x32_bf16 v[12:15], v[148:151], v[238:241], v[12:15]
	v_mfma_f32_16x16x32_bf16 v[8:11], v[156:159], v[238:241], v[8:11]
	v_mfma_f32_16x16x32_bf16 v[52:55], v[160:163], v[176:179], v[52:55]
	v_mfma_f32_16x16x32_bf16 v[48:51], v[168:171], v[176:179], v[48:51]
	v_mfma_f32_16x16x32_bf16 v[36:39], v[160:163], v[184:187], v[36:39]
	v_mfma_f32_16x16x32_bf16 v[32:35], v[168:171], v[184:187], v[32:35]
	v_mfma_f32_16x16x32_bf16 v[20:23], v[160:163], v[212:215], v[20:23]
	v_mfma_f32_16x16x32_bf16 v[16:19], v[168:171], v[212:215], v[16:19]
	v_mfma_f32_16x16x32_bf16 v[4:7], v[160:163], v[234:237], v[4:7]
	v_mfma_f32_16x16x32_bf16 v[0:3], v[168:171], v[234:237], v[0:3]
	v_mfma_f32_16x16x32_bf16 v[52:55], v[164:167], v[180:183], v[52:55]
	v_mfma_f32_16x16x32_bf16 v[48:51], v[172:175], v[180:183], v[48:51]
	v_mfma_f32_16x16x32_bf16 v[36:39], v[164:167], v[188:191], v[36:39]
	v_mfma_f32_16x16x32_bf16 v[32:35], v[172:175], v[188:191], v[32:35]
	v_mfma_f32_16x16x32_bf16 v[20:23], v[164:167], v[216:219], v[20:23]
	v_mfma_f32_16x16x32_bf16 v[16:19], v[172:175], v[216:219], v[16:19]
	v_mfma_f32_16x16x32_bf16 v[4:7], v[164:167], v[238:241], v[4:7]
	v_mfma_f32_16x16x32_bf16 v[0:3], v[172:175], v[238:241], v[0:3]
	s_barrier
	s_add_i32 s73, 0, 0x18000
	s_add_i32 s76, 0, 0x1c000
	v_add_u32_e32 v156, s73, v142
	v_add_u32_e32 v172, s76, v142
	ds_read_b128 v[144:147], v156
	ds_read_b128 v[148:151], v156 offset:1024
	ds_read_b128 v[152:155], v156 offset:2048
	ds_read_b128 v[156:159], v156 offset:3072
	ds_read_b128 v[160:163], v172
	ds_read_b128 v[164:167], v172 offset:1024
	ds_read_b128 v[168:171], v172 offset:2048
	ds_read_b128 v[172:175], v172 offset:3072
	s_add_u32 s74, s78, 0x40000
	s_addc_u32 s75, s79, 0
	s_mov_b32 m0, s52
	v_lshl_add_u64 v[206:207], s[74:75], 0, v[128:129]
	ds_read_b128 v[176:179], v143 offset:32768
	ds_read_b128 v[180:183], v143 offset:33792
	ds_read_b128 v[184:187], v143 offset:34816
	ds_read_b128 v[188:191], v143 offset:35840
	ds_read_b128 v[212:215], v143 offset:36864
	ds_read_b128 v[216:219], v143 offset:37888
	ds_read_b128 v[234:237], v143 offset:38912
	ds_read_b128 v[238:241], v143 offset:39936
	global_load_lds_dwordx4 v[206:207], off
	v_lshl_add_u64 v[206:207], s[74:75], 0, v[130:131]
	s_mov_b32 m0, s53
	s_nop 0
	global_load_lds_dwordx4 v[206:207], off
	s_waitcnt vmcnt(8)
	s_waitcnt lgkmcnt(0)
	s_barrier
	s_waitcnt lgkmcnt(0)
	v_mfma_f32_16x16x32_bf16 v[76:79], v[144:147], v[176:179], v[76:79]
	v_mfma_f32_16x16x32_bf16 v[72:75], v[152:155], v[176:179], v[72:75]
	v_mfma_f32_16x16x32_bf16 v[100:103], v[144:147], v[184:187], v[100:103]
	v_mfma_f32_16x16x32_bf16 v[96:99], v[152:155], v[184:187], v[96:99]
	v_mfma_f32_16x16x32_bf16 v[124:127], v[144:147], v[212:215], v[124:127]
	v_mfma_f32_16x16x32_bf16 v[120:123], v[152:155], v[212:215], v[120:123]
	v_mfma_f32_16x16x32_bf16 v[92:95], v[144:147], v[234:237], v[92:95]
	v_mfma_f32_16x16x32_bf16 v[84:87], v[152:155], v[234:237], v[84:87]
	v_mfma_f32_16x16x32_bf16 v[76:79], v[148:151], v[180:183], v[76:79]
	v_mfma_f32_16x16x32_bf16 v[72:75], v[156:159], v[180:183], v[72:75]
	v_mfma_f32_16x16x32_bf16 v[100:103], v[148:151], v[188:191], v[100:103]
	v_mfma_f32_16x16x32_bf16 v[96:99], v[156:159], v[188:191], v[96:99]
	v_mfma_f32_16x16x32_bf16 v[124:127], v[148:151], v[216:219], v[124:127]
	v_mfma_f32_16x16x32_bf16 v[120:123], v[156:159], v[216:219], v[120:123]
	v_mfma_f32_16x16x32_bf16 v[92:95], v[148:151], v[238:241], v[92:95]
	v_mfma_f32_16x16x32_bf16 v[84:87], v[156:159], v[238:241], v[84:87]
	v_mfma_f32_16x16x32_bf16 v[80:83], v[160:163], v[176:179], v[80:83]
	v_mfma_f32_16x16x32_bf16 v[88:91], v[168:171], v[176:179], v[88:91]
	v_mfma_f32_16x16x32_bf16 v[108:111], v[160:163], v[184:187], v[108:111]
	v_mfma_f32_16x16x32_bf16 v[116:119], v[168:171], v[184:187], v[116:119]
	v_mfma_f32_16x16x32_bf16 v[112:115], v[160:163], v[212:215], v[112:115]
	v_mfma_f32_16x16x32_bf16 v[104:107], v[168:171], v[212:215], v[104:107]
	v_mfma_f32_16x16x32_bf16 v[68:71], v[160:163], v[234:237], v[68:71]
	v_mfma_f32_16x16x32_bf16 v[64:67], v[168:171], v[234:237], v[64:67]
	v_mfma_f32_16x16x32_bf16 v[80:83], v[164:167], v[180:183], v[80:83]
	v_mfma_f32_16x16x32_bf16 v[88:91], v[172:175], v[180:183], v[88:91]
	v_mfma_f32_16x16x32_bf16 v[108:111], v[164:167], v[188:191], v[108:111]
	v_mfma_f32_16x16x32_bf16 v[116:119], v[172:175], v[188:191], v[116:119]
	v_mfma_f32_16x16x32_bf16 v[112:115], v[164:167], v[216:219], v[112:115]
	v_mfma_f32_16x16x32_bf16 v[104:107], v[172:175], v[216:219], v[104:107]
	v_mfma_f32_16x16x32_bf16 v[68:71], v[164:167], v[238:241], v[68:71]
	v_mfma_f32_16x16x32_bf16 v[64:67], v[172:175], v[238:241], v[64:67]
	s_barrier
; #define PG8_STAGE(bufoff, gbase, voff) do { _Pragma("unroll") for (int _i = 0; _i < 2; ++_i) \
;         __builtin_amdgcn_global_load_lds((const unsigned*)((const char*)(gbase) + (voff)[_i]), (PG8_LAS unsigned*)(lds + (bufoff) + ldsw + _i * 8192), 16, 0, 0); } while (0)
; #define PG8_LDA(dst, b, h) do { _Pragma("unroll") for (int m = 0; m < 4; ++m) _Pragma("unroll") for (int k = 0; k < 2; ++k) dst[m][k] = *(const PG8_LAS bf16x8*)(lds + PG8_SA(b, h) + aoff + m * 2048 + k * 1024); } while (0)
; #define PG8_MMA(ai, bj, At, Bt) do { __builtin_amdgcn_s_setprio(1); _Pragma("unroll") for (int m = 0; m < 4; ++m) _Pragma("unroll") for (int n = 0; n < 2; ++n) _Pragma("unroll") for (int k = 0; k < 2; ++k) \
;         acc[ai][bj][m][n] = __builtin_amdgcn_mfma_f32_16x16x32_bf16(Bt[n][k], At[m][k], acc[ai][bj][m][n], 0, 0, 0); __builtin_amdgcn_s_setprio(0); } while (0)
; #define PG8_WAIT_V(n) asm volatile("s_waitcnt vmcnt(" #n ")" ::: "memory")
; #define PG8_WAIT_L(n) asm volatile("s_waitcnt lgkmcnt(" #n ")" ::: "memory")
; #define PG8_BAR __builtin_amdgcn_s_barrier()
; #define PG8_SCHED __builtin_amdgcn_sched_barrier(0)
; template <class Epi, class Sched, bool ALIGN_EPI = false, bool SP2 = false>
; __device__ __forceinline__ void gemm_phase(PG8_LAS unsigned char* lds, const Gemm g, const Sched& S, const Epi& E, const int tid) {
;     ...
;             PG8_LDA(At, 1, 1); PG8_STAGE(PG8_SB(1, 0), b3, voffB); PG8_STAGE(PG8_SB(1, 1), b3 + hstep, voffB); PG8_STAGE(PG8_SA(1, 0), a3, voffA);
;             PG8_WAIT_V(8); PG8_WAIT_L(0); PG8_BAR; PG8_MMA(1, 0, At, B0); PG8_MMA(1, 1, At, B1); PG8_BAR; PG8_SCHED;
;     ...
;         if (!has_next) break;
; #pragma unroll
;         for (int a = 0; a < 2; ++a)
; #pragma unroll
;             for (int b = 0; b < 2; ++b)
; #pragma unroll
;                 for (int m = 0; m < 4; ++m)
; #pragma unroll
;                     for (int n = 0; n < 2; ++n) acc[a][b][m][n] = (f32x4){0.f, 0.f, 0.f, 0.f};
;         cur = nxt; cA = nA; cB = nB; ++ui;
	s_add_i32 s73, s73, s41
	v_lshl_add_u64 v[194:195], v[194:195], 0, s[36:37]
	s_mov_b32 m0, s73
	ds_read_b128 v[176:179], v143 offset:49152
	ds_read_b128 v[180:183], v143 offset:50176
	ds_read_b128 v[184:187], v143 offset:51200
	ds_read_b128 v[188:191], v143 offset:52224
	ds_read_b128 v[212:215], v143 offset:53248
	ds_read_b128 v[216:219], v143 offset:54272
	ds_read_b128 v[234:237], v143 offset:55296
	ds_read_b128 v[238:241], v143 offset:56320
	global_load_lds_dwordx4 v[194:195], off
	s_add_i32 m0, s73, 0x2000
	s_add_u32 s58, s58, 0x40080
	v_lshl_add_u64 v[194:195], v[196:197], 0, s[36:37]
	s_addc_u32 s59, s59, 0
	s_add_i32 s73, s76, s41
	global_load_lds_dwordx4 v[194:195], off
	v_lshl_add_u64 v[194:195], s[58:59], 0, v[192:193]
	s_mov_b32 m0, s73
	s_nop 0
	global_load_lds_dwordx4 v[194:195], off
	v_lshl_add_u64 v[194:195], s[58:59], 0, v[132:133]
	s_add_i32 m0, s73, 0x2000
	s_nop 0
	global_load_lds_dwordx4 v[194:195], off
	v_lshl_add_u64 v[194:195], v[202:203], 0, s[36:37]
	s_mov_b32 m0, s54
	s_nop 0
	global_load_lds_dwordx4 v[194:195], off
	v_lshl_add_u64 v[194:195], v[204:205], 0, s[36:37]
	s_mov_b32 m0, s55
	s_nop 0
	global_load_lds_dwordx4 v[194:195], off
	s_waitcnt vmcnt(8)
	s_waitcnt lgkmcnt(0)
	s_barrier
	s_waitcnt lgkmcnt(0)
	v_mfma_f32_16x16x32_bf16 v[60:63], v[144:147], v[176:179], v[60:63]
	v_mfma_f32_16x16x32_bf16 v[56:59], v[152:155], v[176:179], v[56:59]
	v_mfma_f32_16x16x32_bf16 v[44:47], v[144:147], v[184:187], v[44:47]
	v_mfma_f32_16x16x32_bf16 v[40:43], v[152:155], v[184:187], v[40:43]
	v_mfma_f32_16x16x32_bf16 v[28:31], v[144:147], v[212:215], v[28:31]
	v_mfma_f32_16x16x32_bf16 v[24:27], v[152:155], v[212:215], v[24:27]
	v_mfma_f32_16x16x32_bf16 v[12:15], v[144:147], v[234:237], v[12:15]
	v_mfma_f32_16x16x32_bf16 v[8:11], v[152:155], v[234:237], v[8:11]
	v_mfma_f32_16x16x32_bf16 v[60:63], v[148:151], v[180:183], v[60:63]
	v_mfma_f32_16x16x32_bf16 v[56:59], v[156:159], v[180:183], v[56:59]
	v_mfma_f32_16x16x32_bf16 v[44:47], v[148:151], v[188:191], v[44:47]
	v_mfma_f32_16x16x32_bf16 v[40:43], v[156:159], v[188:191], v[40:43]
	v_mfma_f32_16x16x32_bf16 v[28:31], v[148:151], v[216:219], v[28:31]
	v_mfma_f32_16x16x32_bf16 v[24:27], v[156:159], v[216:219], v[24:27]
	v_mfma_f32_16x16x32_bf16 v[12:15], v[148:151], v[238:241], v[12:15]
	v_mfma_f32_16x16x32_bf16 v[8:11], v[156:159], v[238:241], v[8:11]
	v_mfma_f32_16x16x32_bf16 v[52:55], v[160:163], v[176:179], v[52:55]
	v_mfma_f32_16x16x32_bf16 v[48:51], v[168:171], v[176:179], v[48:51]
	v_mfma_f32_16x16x32_bf16 v[36:39], v[160:163], v[184:187], v[36:39]
	v_mfma_f32_16x16x32_bf16 v[32:35], v[168:171], v[184:187], v[32:35]
	v_mfma_f32_16x16x32_bf16 v[20:23], v[160:163], v[212:215], v[20:23]
	v_mfma_f32_16x16x32_bf16 v[16:19], v[168:171], v[212:215], v[16:19]
	v_mfma_f32_16x16x32_bf16 v[4:7], v[160:163], v[234:237], v[4:7]
	v_mfma_f32_16x16x32_bf16 v[0:3], v[168:171], v[234:237], v[0:3]
	v_mfma_f32_16x16x32_bf16 v[52:55], v[164:167], v[180:183], v[52:55]
	v_mfma_f32_16x16x32_bf16 v[48:51], v[172:175], v[180:183], v[48:51]
	v_mfma_f32_16x16x32_bf16 v[36:39], v[164:167], v[188:191], v[36:39]
	v_mfma_f32_16x16x32_bf16 v[32:35], v[172:175], v[188:191], v[32:35]
	v_mfma_f32_16x16x32_bf16 v[20:23], v[164:167], v[216:219], v[20:23]
	v_mfma_f32_16x16x32_bf16 v[16:19], v[172:175], v[216:219], v[16:19]
	v_mfma_f32_16x16x32_bf16 v[4:7], v[164:167], v[238:241], v[4:7]
	v_mfma_f32_16x16x32_bf16 v[0:3], v[172:175], v[238:241], v[0:3]
	s_barrier
	s_add_i32 s72, s72, 2
	s_add_u32 s44, s44, 0x100
	s_addc_u32 s45, s45, 0
	s_cmp_gt_u32 s72, 13
	s_cbranch_scc0 .LBB0_239
	s_add_u32 s44, s19, 0xffffff00
	s_addc_u32 s45, s62, -1
	s_andn2_b64 vcc, exec, s[8:9]
	s_cbranch_vccnz .LBB0_242
	v_mov_b32_e32 v0, 0
	s_mov_b32 s22, s12
	s_mov_b32 s20, s14
	s_mov_b64 s[10:11], s[28:29]
	s_mov_b32 s60, s18
	v_mov_b32_e32 v1, v0
	v_mov_b32_e32 v2, v0
	v_mov_b32_e32 v3, v0
	v_mov_b32_e32 v4, v0
	v_mov_b32_e32 v5, v0
	v_mov_b32_e32 v6, v0
	v_mov_b32_e32 v7, v0
	v_mov_b32_e32 v16, v0
	v_mov_b32_e32 v17, v0
	v_mov_b32_e32 v18, v0
	v_mov_b32_e32 v19, v0
	v_mov_b32_e32 v20, v0
	v_mov_b32_e32 v21, v0
	v_mov_b32_e32 v22, v0
	v_mov_b32_e32 v23, v0
	v_mov_b32_e32 v32, v0
	v_mov_b32_e32 v33, v0
	v_mov_b32_e32 v34, v0
	v_mov_b32_e32 v35, v0
	v_mov_b32_e32 v36, v0
	v_mov_b32_e32 v37, v0
	v_mov_b32_e32 v38, v0
	v_mov_b32_e32 v39, v0
	v_mov_b32_e32 v48, v0
	v_mov_b32_e32 v49, v0
	v_mov_b32_e32 v50, v0
	v_mov_b32_e32 v51, v0
	v_mov_b32_e32 v52, v0
	v_mov_b32_e32 v53, v0
	v_mov_b32_e32 v54, v0
	v_mov_b32_e32 v55, v0
	v_mov_b32_e32 v8, v0
	v_mov_b32_e32 v9, v0
	v_mov_b32_e32 v10, v0
	v_mov_b32_e32 v11, v0
	v_mov_b32_e32 v12, v0
	v_mov_b32_e32 v13, v0
	v_mov_b32_e32 v14, v0
	v_mov_b32_e32 v15, v0
	v_mov_b32_e32 v24, v0
	v_mov_b32_e32 v25, v0
	v_mov_b32_e32 v26, v0
	v_mov_b32_e32 v27, v0
	v_mov_b32_e32 v28, v0
	v_mov_b32_e32 v29, v0
	v_mov_b32_e32 v30, v0
	v_mov_b32_e32 v31, v0
	v_mov_b32_e32 v40, v0
	v_mov_b32_e32 v41, v0
	v_mov_b32_e32 v42, v0
	v_mov_b32_e32 v43, v0
	v_mov_b32_e32 v44, v0
	v_mov_b32_e32 v45, v0
	v_mov_b32_e32 v46, v0
	v_mov_b32_e32 v47, v0
	v_mov_b32_e32 v56, v0
	v_mov_b32_e32 v57, v0
	v_mov_b32_e32 v58, v0
	v_mov_b32_e32 v59, v0
	v_mov_b32_e32 v60, v0
	v_mov_b32_e32 v61, v0
	v_mov_b32_e32 v62, v0
	v_mov_b32_e32 v63, v0
	v_mov_b32_e32 v64, v0
	v_mov_b32_e32 v65, v0
	v_mov_b32_e32 v66, v0
	v_mov_b32_e32 v67, v0
	v_mov_b32_e32 v68, v0
	v_mov_b32_e32 v69, v0
	v_mov_b32_e32 v70, v0
	v_mov_b32_e32 v71, v0
	v_mov_b32_e32 v104, v0
	v_mov_b32_e32 v105, v0
	v_mov_b32_e32 v106, v0
	v_mov_b32_e32 v107, v0
	v_mov_b32_e32 v112, v0
	v_mov_b32_e32 v113, v0
	v_mov_b32_e32 v114, v0
	v_mov_b32_e32 v115, v0
	v_mov_b32_e32 v116, v0
	v_mov_b32_e32 v117, v0
	v_mov_b32_e32 v118, v0
	v_mov_b32_e32 v119, v0
	v_mov_b32_e32 v108, v0
	v_mov_b32_e32 v109, v0
	v_mov_b32_e32 v110, v0
	v_mov_b32_e32 v111, v0
	v_mov_b32_e32 v88, v0
	v_mov_b32_e32 v89, v0
	v_mov_b32_e32 v90, v0
	v_mov_b32_e32 v91, v0
	v_mov_b32_e32 v80, v0
	v_mov_b32_e32 v81, v0
	v_mov_b32_e32 v82, v0
	v_mov_b32_e32 v83, v0
	v_mov_b32_e32 v84, v0
	v_mov_b32_e32 v85, v0
	v_mov_b32_e32 v86, v0
	v_mov_b32_e32 v87, v0
	v_mov_b32_e32 v92, v0
	v_mov_b32_e32 v93, v0
	v_mov_b32_e32 v94, v0
	v_mov_b32_e32 v95, v0
	v_mov_b32_e32 v120, v0
	v_mov_b32_e32 v121, v0
	v_mov_b32_e32 v122, v0
	v_mov_b32_e32 v123, v0
	v_mov_b32_e32 v124, v0
	v_mov_b32_e32 v125, v0
	v_mov_b32_e32 v126, v0
	v_mov_b32_e32 v127, v0
	v_mov_b32_e32 v96, v0
	v_mov_b32_e32 v97, v0
	v_mov_b32_e32 v98, v0
	v_mov_b32_e32 v99, v0
	v_mov_b32_e32 v100, v0
	v_mov_b32_e32 v101, v0
	v_mov_b32_e32 v102, v0
	v_mov_b32_e32 v103, v0
	v_mov_b32_e32 v72, v0
	v_mov_b32_e32 v73, v0
	v_mov_b32_e32 v74, v0
	v_mov_b32_e32 v75, v0
	v_mov_b32_e32 v76, v0
	v_mov_b32_e32 v77, v0
	v_mov_b32_e32 v78, v0
	v_mov_b32_e32 v79, v0
	s_load_dword s75, s[96:97], 0x0
	s_mov_b64 s[72:73], 0x20000
	s_andn2_b64 vcc, exec, s[6:7]
	s_cbranch_vccnz .LBB0_243
	s_branch .LBB0_244

; #define PG8_STAGE(bufoff, gbase, voff) do { _Pragma("unroll") for (int _i = 0; _i < 2; ++_i) \
;         __builtin_amdgcn_global_load_lds((const unsigned*)((const char*)(gbase) + (voff)[_i]), (PG8_LAS unsigned*)(lds + (bufoff) + ldsw + _i * 8192), 16, 0, 0); } while (0)
; #define PG8_LDA(dst, b, h) do { _Pragma("unroll") for (int m = 0; m < 4; ++m) _Pragma("unroll") for (int k = 0; k < 2; ++k) dst[m][k] = *(const PG8_LAS bf16x8*)(lds + PG8_SA(b, h) + aoff + m * 2048 + k * 1024); } while (0)
; #define PG8_LDB(dst, b, h) do { _Pragma("unroll") for (int n = 0; n < 2; ++n) _Pragma("unroll") for (int k = 0; k < 2; ++k) dst[n][k] = *(const PG8_LAS bf16x8*)(lds + PG8_SB(b, h) + boff + n * 2048 + k * 1024); } while (0)
; #define PG8_MMA(ai, bj, At, Bt) do { __builtin_amdgcn_s_setprio(1); _Pragma("unroll") for (int m = 0; m < 4; ++m) _Pragma("unroll") for (int n = 0; n < 2; ++n) _Pragma("unroll") for (int k = 0; k < 2; ++k) \
;         acc[ai][bj][m][n] = __builtin_amdgcn_mfma_f32_16x16x32_bf16(Bt[n][k], At[m][k], acc[ai][bj][m][n], 0, 0, 0); __builtin_amdgcn_s_setprio(0); } while (0)
; #define PG8_WAIT_V(n) asm volatile("s_waitcnt vmcnt(" #n ")" ::: "memory")
; #define PG8_WAIT_L(n) asm volatile("s_waitcnt lgkmcnt(" #n ")" ::: "memory")
; #define PG8_BAR __builtin_amdgcn_s_barrier()
; #define PG8_SCHED __builtin_amdgcn_sched_barrier(0)
; template <class Epi, class Sched, bool ALIGN_EPI = false, bool SP2 = false>
; __device__ __forceinline__ void gemm_phase(PG8_LAS unsigned char* lds, const Gemm g, const Sched& S, const Epi& E, const int tid) {
;     ...
;             const bool last = (t == nt - 2);
;             const char* a1 = cA + (size_t)(t + 1) * kstep;
;             const char* a2 = last ? nA : cA + (size_t)(t + 2) * kstep; const char* b2 = last ? nB : cB + (size_t)(t + 2) * kstep;
;             const char* a3 = a2 + kstep; const char* b3 = b2 + kstep;
;             if (last && has_next) S.a_ready(nxt);
;             if constexpr (SP2) {
;             PG8_LDB(B0, 0, 0); PG8_LDB(B1, 0, 1); PG8_SCHED; PG8_LDA(At, 0, 0); PG8_STAGE(PG8_SA(1, 1), a1 + hstep, voffA);
;             PG8_WAIT_V(8); PG8_WAIT_L(0); PG8_BAR; PG8_MMA(0, 0, At, B0); PG8_MMA(0, 1, At, B1); PG8_BAR; PG8_SCHED;
;             PG8_LDA(At, 0, 1); PG8_STAGE(PG8_SB(0, 0), b2, voffB); PG8_STAGE(PG8_SB(0, 1), b2 + hstep, voffB); PG8_STAGE(PG8_SA(0, 0), a2, voffA);
.LBB0_324:
	s_add_u32 s28, s22, 0xfffc0080
	s_addc_u32 s29, s23, -1
	s_add_i32 s35, 0, 0x10000
	s_cmp_eq_u32 s34, 12
	s_cselect_b32 s45, s1, s29
	s_cselect_b32 s44, s2, s28
	s_cselect_b32 s29, s13, s26
	s_cselect_b32 s28, s15, s21
	s_add_i32 s38, 0, 0x14000
	v_add_u32_e32 v152, s35, v142
	v_add_u32_e32 v168, s38, v142
	ds_read_b128 v[138:141], v152
	ds_read_b128 v[144:147], v152 offset:1024
	ds_read_b128 v[148:151], v152 offset:2048
	ds_read_b128 v[152:155], v152 offset:3072
	ds_read_b128 v[156:159], v168
	ds_read_b128 v[160:163], v168 offset:1024
	ds_read_b128 v[164:167], v168 offset:2048
	ds_read_b128 v[168:171], v168 offset:3072
	v_lshl_add_u64 v[194:195], s[22:23], 0, v[134:135]
	s_add_i32 m0, s80, 0xc000
	ds_read_b128 v[172:175], v143
	ds_read_b128 v[176:179], v143 offset:1024
	ds_read_b128 v[180:183], v143 offset:2048
	ds_read_b128 v[184:187], v143 offset:3072
	ds_read_b128 v[188:191], v143 offset:4096
	ds_read_b128 v[212:215], v143 offset:5120
	ds_read_b128 v[216:219], v143 offset:6144
	ds_read_b128 v[232:235], v143 offset:7168
	global_load_lds_dwordx4 v[194:195], off
	v_lshl_add_u64 v[194:195], s[22:23], 0, v[136:137]
	s_add_i32 m0, s80, 0xe000
	s_nop 0
	global_load_lds_dwordx4 v[194:195], off
	s_waitcnt vmcnt(8)
	s_waitcnt lgkmcnt(0)
	s_barrier
	s_waitcnt lgkmcnt(0)
	v_mfma_f32_16x16x32_bf16 v[124:127], v[138:141], v[172:175], v[124:127]
	v_mfma_f32_16x16x32_bf16 v[120:123], v[148:151], v[172:175], v[120:123]
	v_mfma_f32_16x16x32_bf16 v[108:111], v[138:141], v[180:183], v[108:111]
	v_mfma_f32_16x16x32_bf16 v[104:107], v[148:151], v[180:183], v[104:107]
	v_mfma_f32_16x16x32_bf16 v[92:95], v[138:141], v[188:191], v[92:95]
	v_mfma_f32_16x16x32_bf16 v[88:91], v[148:151], v[188:191], v[88:91]
	v_mfma_f32_16x16x32_bf16 v[76:79], v[138:141], v[216:219], v[76:79]
	v_mfma_f32_16x16x32_bf16 v[72:75], v[148:151], v[216:219], v[72:75]
	v_mfma_f32_16x16x32_bf16 v[124:127], v[144:147], v[176:179], v[124:127]
	v_mfma_f32_16x16x32_bf16 v[120:123], v[152:155], v[176:179], v[120:123]
	v_mfma_f32_16x16x32_bf16 v[108:111], v[144:147], v[184:187], v[108:111]
	v_mfma_f32_16x16x32_bf16 v[104:107], v[152:155], v[184:187], v[104:107]
	v_mfma_f32_16x16x32_bf16 v[92:95], v[144:147], v[212:215], v[92:95]
	v_mfma_f32_16x16x32_bf16 v[88:91], v[152:155], v[212:215], v[88:91]
	v_mfma_f32_16x16x32_bf16 v[76:79], v[144:147], v[232:235], v[76:79]
	v_mfma_f32_16x16x32_bf16 v[72:75], v[152:155], v[232:235], v[72:75]
	v_mfma_f32_16x16x32_bf16 v[116:119], v[156:159], v[172:175], v[116:119]
	v_mfma_f32_16x16x32_bf16 v[112:115], v[164:167], v[172:175], v[112:115]
	v_mfma_f32_16x16x32_bf16 v[100:103], v[156:159], v[180:183], v[100:103]
	v_mfma_f32_16x16x32_bf16 v[96:99], v[164:167], v[180:183], v[96:99]
	v_mfma_f32_16x16x32_bf16 v[84:87], v[156:159], v[188:191], v[84:87]
	v_mfma_f32_16x16x32_bf16 v[80:83], v[164:167], v[188:191], v[80:83]
	v_mfma_f32_16x16x32_bf16 v[68:71], v[156:159], v[216:219], v[68:71]
	v_mfma_f32_16x16x32_bf16 v[64:67], v[164:167], v[216:219], v[64:67]
	v_mfma_f32_16x16x32_bf16 v[116:119], v[160:163], v[176:179], v[116:119]
	v_mfma_f32_16x16x32_bf16 v[112:115], v[168:171], v[176:179], v[112:115]
	v_mfma_f32_16x16x32_bf16 v[100:103], v[160:163], v[184:187], v[100:103]
	v_mfma_f32_16x16x32_bf16 v[96:99], v[168:171], v[184:187], v[96:99]
	v_mfma_f32_16x16x32_bf16 v[84:87], v[160:163], v[212:215], v[84:87]
	v_mfma_f32_16x16x32_bf16 v[80:83], v[168:171], v[212:215], v[80:83]
	v_mfma_f32_16x16x32_bf16 v[68:71], v[160:163], v[232:235], v[68:71]
	v_mfma_f32_16x16x32_bf16 v[64:67], v[168:171], v[232:235], v[64:67]
	s_barrier
	s_add_i32 s35, s35, s79
	v_lshl_add_u64 v[194:195], s[28:29], 0, v[192:193]
	s_mov_b32 m0, s35
	ds_read_b128 v[172:175], v143 offset:16384
	ds_read_b128 v[176:179], v143 offset:17408
	ds_read_b128 v[180:183], v143 offset:18432
	ds_read_b128 v[184:187], v143 offset:19456
	ds_read_b128 v[188:191], v143 offset:20480
	ds_read_b128 v[212:215], v143 offset:21504
	ds_read_b128 v[216:219], v143 offset:22528
	ds_read_b128 v[232:235], v143 offset:23552
	global_load_lds_dwordx4 v[194:195], off
	s_add_i32 m0, s35, 0x2000
	s_add_u32 s40, s28, 0x40000
	v_lshl_add_u64 v[196:197], s[28:29], 0, v[132:133]
	s_addc_u32 s41, s29, 0
	s_add_i32 s35, s38, s79
	global_load_lds_dwordx4 v[196:197], off
	v_lshl_add_u64 v[202:203], s[40:41], 0, v[192:193]
	s_mov_b32 m0, s35
	v_lshl_add_u64 v[204:205], s[44:45], 0, v[130:131]
	global_load_lds_dwordx4 v[202:203], off
	v_lshl_add_u64 v[202:203], s[40:41], 0, v[132:133]
	s_add_i32 m0, s35, 0x2000
	s_nop 0
	global_load_lds_dwordx4 v[202:203], off
	v_lshl_add_u64 v[202:203], s[44:45], 0, v[128:129]
	s_mov_b32 m0, s80
	s_nop 0
	global_load_lds_dwordx4 v[202:203], off
	s_mov_b32 m0, s81
	s_nop 0
	global_load_lds_dwordx4 v[204:205], off
	s_waitcnt vmcnt(8)
	s_waitcnt lgkmcnt(0)
	s_barrier
; #define PG8_STAGE(bufoff, gbase, voff) do { _Pragma("unroll") for (int _i = 0; _i < 2; ++_i) \
;         __builtin_amdgcn_global_load_lds((const unsigned*)((const char*)(gbase) + (voff)[_i]), (PG8_LAS unsigned*)(lds + (bufoff) + ldsw + _i * 8192), 16, 0, 0); } while (0)
; #define PG8_LDA(dst, b, h) do { _Pragma("unroll") for (int m = 0; m < 4; ++m) _Pragma("unroll") for (int k = 0; k < 2; ++k) dst[m][k] = *(const PG8_LAS bf16x8*)(lds + PG8_SA(b, h) + aoff + m * 2048 + k * 1024); } while (0)
; #define PG8_LDB(dst, b, h) do { _Pragma("unroll") for (int n = 0; n < 2; ++n) _Pragma("unroll") for (int k = 0; k < 2; ++k) dst[n][k] = *(const PG8_LAS bf16x8*)(lds + PG8_SB(b, h) + boff + n * 2048 + k * 1024); } while (0)
; #define PG8_MMA(ai, bj, At, Bt) do { __builtin_amdgcn_s_setprio(1); _Pragma("unroll") for (int m = 0; m < 4; ++m) _Pragma("unroll") for (int n = 0; n < 2; ++n) _Pragma("unroll") for (int k = 0; k < 2; ++k) \
;         acc[ai][bj][m][n] = __builtin_amdgcn_mfma_f32_16x16x32_bf16(Bt[n][k], At[m][k], acc[ai][bj][m][n], 0, 0, 0); __builtin_amdgcn_s_setprio(0); } while (0)
; #define PG8_WAIT_V(n) asm volatile("s_waitcnt vmcnt(" #n ")" ::: "memory")
; #define PG8_WAIT_L(n) asm volatile("s_waitcnt lgkmcnt(" #n ")" ::: "memory")
; #define PG8_BAR __builtin_amdgcn_s_barrier()
; #define PG8_SCHED __builtin_amdgcn_sched_barrier(0)
; template <class Epi, class Sched, bool ALIGN_EPI = false, bool SP2 = false>
; __device__ __forceinline__ void gemm_phase(PG8_LAS unsigned char* lds, const Gemm g, const Sched& S, const Epi& E, const int tid) {
;     ...
;             PG8_WAIT_V(8); PG8_WAIT_L(0); PG8_BAR; PG8_MMA(1, 0, At, B0); PG8_MMA(1, 1, At, B1); PG8_BAR; PG8_SCHED;
;             PG8_LDB(B0, 1, 0); PG8_LDB(B1, 1, 1); PG8_SCHED; PG8_LDA(At, 1, 0); PG8_STAGE(PG8_SA(0, 1), a2 + hstep, voffA);
;             PG8_WAIT_V(8); PG8_WAIT_L(0); PG8_BAR; PG8_MMA(0, 0, At, B0); PG8_MMA(0, 1, At, B1); PG8_BAR; PG8_SCHED;
	s_waitcnt lgkmcnt(0)
	v_mfma_f32_16x16x32_bf16 v[60:63], v[138:141], v[172:175], v[60:63]
	v_mfma_f32_16x16x32_bf16 v[56:59], v[148:151], v[172:175], v[56:59]
	v_mfma_f32_16x16x32_bf16 v[44:47], v[138:141], v[180:183], v[44:47]
	v_mfma_f32_16x16x32_bf16 v[40:43], v[148:151], v[180:183], v[40:43]
	v_mfma_f32_16x16x32_bf16 v[28:31], v[138:141], v[188:191], v[28:31]
	v_mfma_f32_16x16x32_bf16 v[24:27], v[148:151], v[188:191], v[24:27]
	v_mfma_f32_16x16x32_bf16 v[12:15], v[138:141], v[216:219], v[12:15]
	v_mfma_f32_16x16x32_bf16 v[8:11], v[148:151], v[216:219], v[8:11]
	v_mfma_f32_16x16x32_bf16 v[60:63], v[144:147], v[176:179], v[60:63]
	v_mfma_f32_16x16x32_bf16 v[56:59], v[152:155], v[176:179], v[56:59]
	v_mfma_f32_16x16x32_bf16 v[44:47], v[144:147], v[184:187], v[44:47]
	v_mfma_f32_16x16x32_bf16 v[40:43], v[152:155], v[184:187], v[40:43]
	v_mfma_f32_16x16x32_bf16 v[28:31], v[144:147], v[212:215], v[28:31]
	v_mfma_f32_16x16x32_bf16 v[24:27], v[152:155], v[212:215], v[24:27]
	v_mfma_f32_16x16x32_bf16 v[12:15], v[144:147], v[232:235], v[12:15]
	v_mfma_f32_16x16x32_bf16 v[8:11], v[152:155], v[232:235], v[8:11]
	v_mfma_f32_16x16x32_bf16 v[52:55], v[156:159], v[172:175], v[52:55]
	v_mfma_f32_16x16x32_bf16 v[48:51], v[164:167], v[172:175], v[48:51]
	v_mfma_f32_16x16x32_bf16 v[36:39], v[156:159], v[180:183], v[36:39]
	v_mfma_f32_16x16x32_bf16 v[32:35], v[164:167], v[180:183], v[32:35]
	v_mfma_f32_16x16x32_bf16 v[20:23], v[156:159], v[188:191], v[20:23]
	v_mfma_f32_16x16x32_bf16 v[16:19], v[164:167], v[188:191], v[16:19]
	v_mfma_f32_16x16x32_bf16 v[4:7], v[156:159], v[216:219], v[4:7]
	v_mfma_f32_16x16x32_bf16 v[0:3], v[164:167], v[216:219], v[0:3]
	v_mfma_f32_16x16x32_bf16 v[52:55], v[160:163], v[176:179], v[52:55]
	v_mfma_f32_16x16x32_bf16 v[48:51], v[168:171], v[176:179], v[48:51]
	v_mfma_f32_16x16x32_bf16 v[36:39], v[160:163], v[184:187], v[36:39]
	v_mfma_f32_16x16x32_bf16 v[32:35], v[168:171], v[184:187], v[32:35]
	v_mfma_f32_16x16x32_bf16 v[20:23], v[160:163], v[212:215], v[20:23]
	v_mfma_f32_16x16x32_bf16 v[16:19], v[168:171], v[212:215], v[16:19]
	v_mfma_f32_16x16x32_bf16 v[4:7], v[160:163], v[232:235], v[4:7]
	v_mfma_f32_16x16x32_bf16 v[0:3], v[168:171], v[232:235], v[0:3]
	s_barrier
	s_add_i32 s35, 0, 0x18000
	s_add_i32 s38, 0, 0x1c000
	v_add_u32_e32 v152, s35, v142
	v_add_u32_e32 v168, s38, v142
	ds_read_b128 v[138:141], v152
	ds_read_b128 v[144:147], v152 offset:1024
	ds_read_b128 v[148:151], v152 offset:2048
	ds_read_b128 v[152:155], v152 offset:3072
	ds_read_b128 v[156:159], v168
	ds_read_b128 v[160:163], v168 offset:1024
	ds_read_b128 v[164:167], v168 offset:2048
	ds_read_b128 v[168:171], v168 offset:3072
	s_add_u32 s40, s44, 0x40000
	s_addc_u32 s41, s45, 0
	s_mov_b32 m0, s82
	v_lshl_add_u64 v[206:207], s[40:41], 0, v[128:129]
	ds_read_b128 v[172:175], v143 offset:32768
	ds_read_b128 v[176:179], v143 offset:33792
	ds_read_b128 v[180:183], v143 offset:34816
	ds_read_b128 v[184:187], v143 offset:35840
	ds_read_b128 v[188:191], v143 offset:36864
	ds_read_b128 v[212:215], v143 offset:37888
	ds_read_b128 v[216:219], v143 offset:38912
	ds_read_b128 v[232:235], v143 offset:39936
	global_load_lds_dwordx4 v[206:207], off
	v_lshl_add_u64 v[206:207], s[40:41], 0, v[130:131]
	s_mov_b32 m0, s83
	s_nop 0
	global_load_lds_dwordx4 v[206:207], off
	s_waitcnt vmcnt(8)
	s_waitcnt lgkmcnt(0)
	s_barrier
	s_waitcnt lgkmcnt(0)
	v_mfma_f32_16x16x32_bf16 v[124:127], v[138:141], v[172:175], v[124:127]
	v_mfma_f32_16x16x32_bf16 v[120:123], v[148:151], v[172:175], v[120:123]
	v_mfma_f32_16x16x32_bf16 v[108:111], v[138:141], v[180:183], v[108:111]
	v_mfma_f32_16x16x32_bf16 v[104:107], v[148:151], v[180:183], v[104:107]
	v_mfma_f32_16x16x32_bf16 v[92:95], v[138:141], v[188:191], v[92:95]
	v_mfma_f32_16x16x32_bf16 v[88:91], v[148:151], v[188:191], v[88:91]
	v_mfma_f32_16x16x32_bf16 v[76:79], v[138:141], v[216:219], v[76:79]
	v_mfma_f32_16x16x32_bf16 v[72:75], v[148:151], v[216:219], v[72:75]
	v_mfma_f32_16x16x32_bf16 v[124:127], v[144:147], v[176:179], v[124:127]
	v_mfma_f32_16x16x32_bf16 v[120:123], v[152:155], v[176:179], v[120:123]
	v_mfma_f32_16x16x32_bf16 v[108:111], v[144:147], v[184:187], v[108:111]
	v_mfma_f32_16x16x32_bf16 v[104:107], v[152:155], v[184:187], v[104:107]
	v_mfma_f32_16x16x32_bf16 v[92:95], v[144:147], v[212:215], v[92:95]
	v_mfma_f32_16x16x32_bf16 v[88:91], v[152:155], v[212:215], v[88:91]
	v_mfma_f32_16x16x32_bf16 v[76:79], v[144:147], v[232:235], v[76:79]
	v_mfma_f32_16x16x32_bf16 v[72:75], v[152:155], v[232:235], v[72:75]
	v_mfma_f32_16x16x32_bf16 v[116:119], v[156:159], v[172:175], v[116:119]
	v_mfma_f32_16x16x32_bf16 v[112:115], v[164:167], v[172:175], v[112:115]
	v_mfma_f32_16x16x32_bf16 v[100:103], v[156:159], v[180:183], v[100:103]
	v_mfma_f32_16x16x32_bf16 v[96:99], v[164:167], v[180:183], v[96:99]
	v_mfma_f32_16x16x32_bf16 v[84:87], v[156:159], v[188:191], v[84:87]
	v_mfma_f32_16x16x32_bf16 v[80:83], v[164:167], v[188:191], v[80:83]
	v_mfma_f32_16x16x32_bf16 v[68:71], v[156:159], v[216:219], v[68:71]
	v_mfma_f32_16x16x32_bf16 v[64:67], v[164:167], v[216:219], v[64:67]
	v_mfma_f32_16x16x32_bf16 v[116:119], v[160:163], v[176:179], v[116:119]
	v_mfma_f32_16x16x32_bf16 v[112:115], v[168:171], v[176:179], v[112:115]
	v_mfma_f32_16x16x32_bf16 v[100:103], v[160:163], v[184:187], v[100:103]
	v_mfma_f32_16x16x32_bf16 v[96:99], v[168:171], v[184:187], v[96:99]
	v_mfma_f32_16x16x32_bf16 v[84:87], v[160:163], v[212:215], v[84:87]
	v_mfma_f32_16x16x32_bf16 v[80:83], v[168:171], v[212:215], v[80:83]
	v_mfma_f32_16x16x32_bf16 v[68:71], v[160:163], v[232:235], v[68:71]
	v_mfma_f32_16x16x32_bf16 v[64:67], v[168:171], v[232:235], v[64:67]
	s_barrier
; #define PG8_STAGE(bufoff, gbase, voff) do { _Pragma("unroll") for (int _i = 0; _i < 2; ++_i) \
;         __builtin_amdgcn_global_load_lds((const unsigned*)((const char*)(gbase) + (voff)[_i]), (PG8_LAS unsigned*)(lds + (bufoff) + ldsw + _i * 8192), 16, 0, 0); } while (0)
; #define PG8_LDA(dst, b, h) do { _Pragma("unroll") for (int m = 0; m < 4; ++m) _Pragma("unroll") for (int k = 0; k < 2; ++k) dst[m][k] = *(const PG8_LAS bf16x8*)(lds + PG8_SA(b, h) + aoff + m * 2048 + k * 1024); } while (0)
; #define PG8_MMA(ai, bj, At, Bt) do { __builtin_amdgcn_s_setprio(1); _Pragma("unroll") for (int m = 0; m < 4; ++m) _Pragma("unroll") for (int n = 0; n < 2; ++n) _Pragma("unroll") for (int k = 0; k < 2; ++k) \
;         acc[ai][bj][m][n] = __builtin_amdgcn_mfma_f32_16x16x32_bf16(Bt[n][k], At[m][k], acc[ai][bj][m][n], 0, 0, 0); __builtin_amdgcn_s_setprio(0); } while (0)
; #define PG8_WAIT_V(n) asm volatile("s_waitcnt vmcnt(" #n ")" ::: "memory")
; #define PG8_WAIT_L(n) asm volatile("s_waitcnt lgkmcnt(" #n ")" ::: "memory")
; #define PG8_BAR __builtin_amdgcn_s_barrier()
; #define PG8_SCHED __builtin_amdgcn_sched_barrier(0)
; template <class Epi, class Sched, bool ALIGN_EPI = false, bool SP2 = false>
; __device__ __forceinline__ void gemm_phase(PG8_LAS unsigned char* lds, const Gemm g, const Sched& S, const Epi& E, const int tid) {
;     ...
;         for (int t = 0; t < nt; t += 2) {
;     ...
;             PG8_LDA(At, 1, 1); PG8_STAGE(PG8_SB(1, 0), b3, voffB); PG8_STAGE(PG8_SB(1, 1), b3 + hstep, voffB); PG8_STAGE(PG8_SA(1, 0), a3, voffA);
;             PG8_WAIT_V(8); PG8_WAIT_L(0); PG8_BAR; PG8_MMA(1, 0, At, B0); PG8_MMA(1, 1, At, B1); PG8_BAR; PG8_SCHED;
	s_add_i32 s35, s35, s79
	v_lshl_add_u64 v[194:195], v[194:195], 0, s[36:37]
	s_mov_b32 m0, s35
	ds_read_b128 v[172:175], v143 offset:49152
	ds_read_b128 v[176:179], v143 offset:50176
	ds_read_b128 v[180:183], v143 offset:51200
	ds_read_b128 v[184:187], v143 offset:52224
	ds_read_b128 v[188:191], v143 offset:53248
	ds_read_b128 v[212:215], v143 offset:54272
	ds_read_b128 v[216:219], v143 offset:55296
	ds_read_b128 v[232:235], v143 offset:56320
	global_load_lds_dwordx4 v[194:195], off
	s_add_i32 m0, s35, 0x2000
	s_add_u32 s28, s28, 0x40080
	v_lshl_add_u64 v[194:195], v[196:197], 0, s[36:37]
	s_addc_u32 s29, s29, 0
	s_add_i32 s35, s38, s79
	global_load_lds_dwordx4 v[194:195], off
	v_lshl_add_u64 v[194:195], s[28:29], 0, v[192:193]
	s_mov_b32 m0, s35
	s_nop 0
	global_load_lds_dwordx4 v[194:195], off
	v_lshl_add_u64 v[194:195], s[28:29], 0, v[132:133]
	s_add_i32 m0, s35, 0x2000
	s_nop 0
	global_load_lds_dwordx4 v[194:195], off
	v_lshl_add_u64 v[194:195], v[202:203], 0, s[36:37]
	s_mov_b32 m0, s84
	s_nop 0
	global_load_lds_dwordx4 v[194:195], off
	v_lshl_add_u64 v[194:195], v[204:205], 0, s[36:37]
	s_mov_b32 m0, s85
	s_nop 0
	global_load_lds_dwordx4 v[194:195], off
	s_waitcnt vmcnt(8)
	s_waitcnt lgkmcnt(0)
	s_barrier
	s_waitcnt lgkmcnt(0)
	v_mfma_f32_16x16x32_bf16 v[60:63], v[138:141], v[172:175], v[60:63]
	v_mfma_f32_16x16x32_bf16 v[56:59], v[148:151], v[172:175], v[56:59]
	v_mfma_f32_16x16x32_bf16 v[44:47], v[138:141], v[180:183], v[44:47]
	v_mfma_f32_16x16x32_bf16 v[40:43], v[148:151], v[180:183], v[40:43]
	v_mfma_f32_16x16x32_bf16 v[28:31], v[138:141], v[188:191], v[28:31]
	v_mfma_f32_16x16x32_bf16 v[24:27], v[148:151], v[188:191], v[24:27]
	v_mfma_f32_16x16x32_bf16 v[12:15], v[138:141], v[216:219], v[12:15]
	v_mfma_f32_16x16x32_bf16 v[8:11], v[148:151], v[216:219], v[8:11]
	v_mfma_f32_16x16x32_bf16 v[60:63], v[144:147], v[176:179], v[60:63]
	v_mfma_f32_16x16x32_bf16 v[56:59], v[152:155], v[176:179], v[56:59]
	v_mfma_f32_16x16x32_bf16 v[44:47], v[144:147], v[184:187], v[44:47]
	v_mfma_f32_16x16x32_bf16 v[40:43], v[152:155], v[184:187], v[40:43]
	v_mfma_f32_16x16x32_bf16 v[28:31], v[144:147], v[212:215], v[28:31]
	v_mfma_f32_16x16x32_bf16 v[24:27], v[152:155], v[212:215], v[24:27]
	v_mfma_f32_16x16x32_bf16 v[12:15], v[144:147], v[232:235], v[12:15]
	v_mfma_f32_16x16x32_bf16 v[8:11], v[152:155], v[232:235], v[8:11]
	v_mfma_f32_16x16x32_bf16 v[52:55], v[156:159], v[172:175], v[52:55]
	v_mfma_f32_16x16x32_bf16 v[48:51], v[164:167], v[172:175], v[48:51]
	v_mfma_f32_16x16x32_bf16 v[36:39], v[156:159], v[180:183], v[36:39]
	v_mfma_f32_16x16x32_bf16 v[32:35], v[164:167], v[180:183], v[32:35]
	v_mfma_f32_16x16x32_bf16 v[20:23], v[156:159], v[188:191], v[20:23]
	v_mfma_f32_16x16x32_bf16 v[16:19], v[164:167], v[188:191], v[16:19]
	v_mfma_f32_16x16x32_bf16 v[4:7], v[156:159], v[216:219], v[4:7]
	v_mfma_f32_16x16x32_bf16 v[0:3], v[164:167], v[216:219], v[0:3]
	v_mfma_f32_16x16x32_bf16 v[52:55], v[160:163], v[176:179], v[52:55]
	v_mfma_f32_16x16x32_bf16 v[48:51], v[168:171], v[176:179], v[48:51]
	v_mfma_f32_16x16x32_bf16 v[36:39], v[160:163], v[184:187], v[36:39]
	v_mfma_f32_16x16x32_bf16 v[32:35], v[168:171], v[184:187], v[32:35]
	v_mfma_f32_16x16x32_bf16 v[20:23], v[160:163], v[212:215], v[20:23]
	v_mfma_f32_16x16x32_bf16 v[16:19], v[168:171], v[212:215], v[16:19]
	v_mfma_f32_16x16x32_bf16 v[4:7], v[160:163], v[232:235], v[4:7]
	v_mfma_f32_16x16x32_bf16 v[0:3], v[168:171], v[232:235], v[0:3]
	s_barrier
	s_add_i32 s34, s34, 2
	s_add_u32 s22, s22, 0x100
	s_addc_u32 s23, s23, 0
	s_add_u32 s21, s21, 0x100
	s_addc_u32 s26, s26, 0
	s_cmp_gt_u32 s34, 13
	s_cbranch_scc0 .LBB0_324
	s_and_b64 vcc, exec, s[10:11]
	s_cbranch_vccz .LBB0_327
	s_barrier

; #define PG8_STAGE(bufoff, gbase, voff) do { _Pragma("unroll") for (int _i = 0; _i < 2; ++_i) \
;         __builtin_amdgcn_global_load_lds((const unsigned*)((const char*)(gbase) + (voff)[_i]), (PG8_LAS unsigned*)(lds + (bufoff) + ldsw + _i * 8192), 16, 0, 0); } while (0)
; #define PG8_LDA(dst, b, h) do { _Pragma("unroll") for (int m = 0; m < 4; ++m) _Pragma("unroll") for (int k = 0; k < 2; ++k) dst[m][k] = *(const PG8_LAS bf16x8*)(lds + PG8_SA(b, h) + aoff + m * 2048 + k * 1024); } while (0)
; #define PG8_LDB(dst, b, h) do { _Pragma("unroll") for (int n = 0; n < 2; ++n) _Pragma("unroll") for (int k = 0; k < 2; ++k) dst[n][k] = *(const PG8_LAS bf16x8*)(lds + PG8_SB(b, h) + boff + n * 2048 + k * 1024); } while (0)
; #define PG8_MMA(ai, bj, At, Bt) do { __builtin_amdgcn_s_setprio(1); _Pragma("unroll") for (int m = 0; m < 4; ++m) _Pragma("unroll") for (int n = 0; n < 2; ++n) _Pragma("unroll") for (int k = 0; k < 2; ++k) \
;         acc[ai][bj][m][n] = __builtin_amdgcn_mfma_f32_16x16x32_bf16(Bt[n][k], At[m][k], acc[ai][bj][m][n], 0, 0, 0); __builtin_amdgcn_s_setprio(0); } while (0)
; #define PG8_WAIT_V(n) asm volatile("s_waitcnt vmcnt(" #n ")" ::: "memory")
; #define PG8_WAIT_L(n) asm volatile("s_waitcnt lgkmcnt(" #n ")" ::: "memory")
; #define PG8_BAR __builtin_amdgcn_s_barrier()
; #define PG8_SCHED __builtin_amdgcn_sched_barrier(0)
; template <class Epi, class Sched, bool ALIGN_EPI = false, bool SP2 = false>
; __device__ __forceinline__ void gemm_phase(PG8_LAS unsigned char* lds, const Gemm g, const Sched& S, const Epi& E, const int tid) {
;     ...
;             const bool last = (t == nt - 2);
;             const char* a1 = cA + (size_t)(t + 1) * kstep;
;             const char* a2 = last ? nA : cA + (size_t)(t + 2) * kstep; const char* b2 = last ? nB : cB + (size_t)(t + 2) * kstep;
;             const char* a3 = a2 + kstep; const char* b3 = b2 + kstep;
;             if (last && has_next) S.a_ready(nxt);
;             if constexpr (SP2) {
;             PG8_LDB(B0, 0, 0); PG8_LDB(B1, 0, 1); PG8_SCHED; PG8_LDA(At, 0, 0); PG8_STAGE(PG8_SA(1, 1), a1 + hstep, voffA);
;             PG8_WAIT_V(8); PG8_WAIT_L(0); PG8_BAR; PG8_MMA(0, 0, At, B0); PG8_MMA(0, 1, At, B1); PG8_BAR; PG8_SCHED;
;             PG8_LDA(At, 0, 1); PG8_STAGE(PG8_SB(0, 0), b2, voffB); PG8_STAGE(PG8_SB(0, 1), b2 + hstep, voffB); PG8_STAGE(PG8_SA(0, 0), a2, voffA);
.LBB0_348:
	s_add_u32 s35, s28, 0xfffe0080
	s_addc_u32 s38, s29, -1
	s_add_i32 s40, 0, 0x10000
	s_cmp_eq_u32 s34, 4
	s_cselect_b32 s59, s1, s38
	s_cselect_b32 s58, s2, s35
	s_cselect_b32 s45, s15, s26
	s_cselect_b32 s44, s17, s23
	s_add_i32 s35, 0, 0x14000
	v_add_u32_e32 v152, s40, v142
	v_add_u32_e32 v168, s35, v142
	ds_read_b128 v[138:141], v152
	ds_read_b128 v[144:147], v152 offset:1024
	ds_read_b128 v[148:151], v152 offset:2048
	ds_read_b128 v[152:155], v152 offset:3072
	ds_read_b128 v[156:159], v168
	ds_read_b128 v[160:163], v168 offset:1024
	ds_read_b128 v[164:167], v168 offset:2048
	ds_read_b128 v[168:171], v168 offset:3072
	v_lshl_add_u64 v[194:195], s[28:29], 0, v[134:135]
	s_add_i32 m0, s83, 0xc000
	ds_read_b128 v[172:175], v143
	ds_read_b128 v[176:179], v143 offset:1024
	ds_read_b128 v[180:183], v143 offset:2048
	ds_read_b128 v[184:187], v143 offset:3072
	ds_read_b128 v[188:191], v143 offset:4096
	ds_read_b128 v[212:215], v143 offset:5120
	ds_read_b128 v[216:219], v143 offset:6144
	ds_read_b128 v[232:235], v143 offset:7168
	global_load_lds_dwordx4 v[194:195], off
	v_lshl_add_u64 v[194:195], s[28:29], 0, v[136:137]
	s_add_i32 m0, s83, 0xe000
	s_nop 0
	global_load_lds_dwordx4 v[194:195], off
	s_waitcnt vmcnt(8)
	s_waitcnt lgkmcnt(0)
	s_barrier
	s_waitcnt lgkmcnt(0)
	v_mfma_f32_16x16x32_bf16 v[124:127], v[138:141], v[172:175], v[124:127]
	v_mfma_f32_16x16x32_bf16 v[120:123], v[148:151], v[172:175], v[120:123]
	v_mfma_f32_16x16x32_bf16 v[108:111], v[138:141], v[180:183], v[108:111]
	v_mfma_f32_16x16x32_bf16 v[104:107], v[148:151], v[180:183], v[104:107]
	v_mfma_f32_16x16x32_bf16 v[92:95], v[138:141], v[188:191], v[92:95]
	v_mfma_f32_16x16x32_bf16 v[88:91], v[148:151], v[188:191], v[88:91]
	v_mfma_f32_16x16x32_bf16 v[76:79], v[138:141], v[216:219], v[76:79]
	v_mfma_f32_16x16x32_bf16 v[72:75], v[148:151], v[216:219], v[72:75]
	v_mfma_f32_16x16x32_bf16 v[124:127], v[144:147], v[176:179], v[124:127]
	v_mfma_f32_16x16x32_bf16 v[120:123], v[152:155], v[176:179], v[120:123]
	v_mfma_f32_16x16x32_bf16 v[108:111], v[144:147], v[184:187], v[108:111]
	v_mfma_f32_16x16x32_bf16 v[104:107], v[152:155], v[184:187], v[104:107]
	v_mfma_f32_16x16x32_bf16 v[92:95], v[144:147], v[212:215], v[92:95]
	v_mfma_f32_16x16x32_bf16 v[88:91], v[152:155], v[212:215], v[88:91]
	v_mfma_f32_16x16x32_bf16 v[76:79], v[144:147], v[232:235], v[76:79]
	v_mfma_f32_16x16x32_bf16 v[72:75], v[152:155], v[232:235], v[72:75]
	v_mfma_f32_16x16x32_bf16 v[116:119], v[156:159], v[172:175], v[116:119]
	v_mfma_f32_16x16x32_bf16 v[112:115], v[164:167], v[172:175], v[112:115]
	v_mfma_f32_16x16x32_bf16 v[100:103], v[156:159], v[180:183], v[100:103]
	v_mfma_f32_16x16x32_bf16 v[96:99], v[164:167], v[180:183], v[96:99]
	v_mfma_f32_16x16x32_bf16 v[84:87], v[156:159], v[188:191], v[84:87]
	v_mfma_f32_16x16x32_bf16 v[80:83], v[164:167], v[188:191], v[80:83]
	v_mfma_f32_16x16x32_bf16 v[68:71], v[156:159], v[216:219], v[68:71]
	v_mfma_f32_16x16x32_bf16 v[64:67], v[164:167], v[216:219], v[64:67]
	v_mfma_f32_16x16x32_bf16 v[116:119], v[160:163], v[176:179], v[116:119]
	v_mfma_f32_16x16x32_bf16 v[112:115], v[168:171], v[176:179], v[112:115]
	v_mfma_f32_16x16x32_bf16 v[100:103], v[160:163], v[184:187], v[100:103]
	v_mfma_f32_16x16x32_bf16 v[96:99], v[168:171], v[184:187], v[96:99]
	v_mfma_f32_16x16x32_bf16 v[84:87], v[160:163], v[212:215], v[84:87]
	v_mfma_f32_16x16x32_bf16 v[80:83], v[168:171], v[212:215], v[80:83]
	v_mfma_f32_16x16x32_bf16 v[68:71], v[160:163], v[232:235], v[68:71]
	v_mfma_f32_16x16x32_bf16 v[64:67], v[168:171], v[232:235], v[64:67]
	s_barrier
	s_add_i32 s38, s40, s82
	v_lshl_add_u64 v[194:195], s[44:45], 0, v[192:193]
	s_mov_b32 m0, s38
	ds_read_b128 v[172:175], v143 offset:16384
	ds_read_b128 v[176:179], v143 offset:17408
	ds_read_b128 v[180:183], v143 offset:18432
	ds_read_b128 v[184:187], v143 offset:19456
	ds_read_b128 v[188:191], v143 offset:20480
	ds_read_b128 v[212:215], v143 offset:21504
	ds_read_b128 v[216:219], v143 offset:22528
	ds_read_b128 v[232:235], v143 offset:23552
	global_load_lds_dwordx4 v[194:195], off
	s_add_i32 m0, s38, 0x2000
	s_add_u32 s40, s44, 0x20000
	v_lshl_add_u64 v[196:197], s[44:45], 0, v[132:133]
	s_addc_u32 s41, s45, 0
	s_add_i32 s35, s35, s82
	global_load_lds_dwordx4 v[196:197], off
	v_lshl_add_u64 v[202:203], s[40:41], 0, v[192:193]
	s_mov_b32 m0, s35
	v_lshl_add_u64 v[204:205], s[58:59], 0, v[130:131]
	global_load_lds_dwordx4 v[202:203], off
	v_lshl_add_u64 v[202:203], s[40:41], 0, v[132:133]
	s_add_i32 m0, s35, 0x2000
	s_nop 0
	global_load_lds_dwordx4 v[202:203], off
	v_lshl_add_u64 v[202:203], s[58:59], 0, v[128:129]
	s_mov_b32 m0, s83
	s_nop 0
	global_load_lds_dwordx4 v[202:203], off
	s_mov_b32 m0, s84
	s_nop 0
	global_load_lds_dwordx4 v[204:205], off
	s_waitcnt vmcnt(8)
	s_waitcnt lgkmcnt(0)
	s_barrier
; #define PG8_STAGE(bufoff, gbase, voff) do { _Pragma("unroll") for (int _i = 0; _i < 2; ++_i) \
;         __builtin_amdgcn_global_load_lds((const unsigned*)((const char*)(gbase) + (voff)[_i]), (PG8_LAS unsigned*)(lds + (bufoff) + ldsw + _i * 8192), 16, 0, 0); } while (0)
; #define PG8_LDA(dst, b, h) do { _Pragma("unroll") for (int m = 0; m < 4; ++m) _Pragma("unroll") for (int k = 0; k < 2; ++k) dst[m][k] = *(const PG8_LAS bf16x8*)(lds + PG8_SA(b, h) + aoff + m * 2048 + k * 1024); } while (0)
; #define PG8_LDB(dst, b, h) do { _Pragma("unroll") for (int n = 0; n < 2; ++n) _Pragma("unroll") for (int k = 0; k < 2; ++k) dst[n][k] = *(const PG8_LAS bf16x8*)(lds + PG8_SB(b, h) + boff + n * 2048 + k * 1024); } while (0)
; #define PG8_MMA(ai, bj, At, Bt) do { __builtin_amdgcn_s_setprio(1); _Pragma("unroll") for (int m = 0; m < 4; ++m) _Pragma("unroll") for (int n = 0; n < 2; ++n) _Pragma("unroll") for (int k = 0; k < 2; ++k) \
;         acc[ai][bj][m][n] = __builtin_amdgcn_mfma_f32_16x16x32_bf16(Bt[n][k], At[m][k], acc[ai][bj][m][n], 0, 0, 0); __builtin_amdgcn_s_setprio(0); } while (0)
; #define PG8_WAIT_V(n) asm volatile("s_waitcnt vmcnt(" #n ")" ::: "memory")
; #define PG8_WAIT_L(n) asm volatile("s_waitcnt lgkmcnt(" #n ")" ::: "memory")
; #define PG8_BAR __builtin_amdgcn_s_barrier()
; #define PG8_SCHED __builtin_amdgcn_sched_barrier(0)
; template <class Epi, class Sched, bool ALIGN_EPI = false, bool SP2 = false>
; __device__ __forceinline__ void gemm_phase(PG8_LAS unsigned char* lds, const Gemm g, const Sched& S, const Epi& E, const int tid) {
;     ...
;             PG8_WAIT_V(8); PG8_WAIT_L(0); PG8_BAR; PG8_MMA(1, 0, At, B0); PG8_MMA(1, 1, At, B1); PG8_BAR; PG8_SCHED;
;             PG8_LDB(B0, 1, 0); PG8_LDB(B1, 1, 1); PG8_SCHED; PG8_LDA(At, 1, 0); PG8_STAGE(PG8_SA(0, 1), a2 + hstep, voffA);
;             PG8_WAIT_V(8); PG8_WAIT_L(0); PG8_BAR; PG8_MMA(0, 0, At, B0); PG8_MMA(0, 1, At, B1); PG8_BAR; PG8_SCHED;
	s_waitcnt lgkmcnt(0)
	v_mfma_f32_16x16x32_bf16 v[60:63], v[138:141], v[172:175], v[60:63]
	v_mfma_f32_16x16x32_bf16 v[56:59], v[148:151], v[172:175], v[56:59]
	v_mfma_f32_16x16x32_bf16 v[44:47], v[138:141], v[180:183], v[44:47]
	v_mfma_f32_16x16x32_bf16 v[40:43], v[148:151], v[180:183], v[40:43]
	v_mfma_f32_16x16x32_bf16 v[28:31], v[138:141], v[188:191], v[28:31]
	v_mfma_f32_16x16x32_bf16 v[24:27], v[148:151], v[188:191], v[24:27]
	v_mfma_f32_16x16x32_bf16 v[12:15], v[138:141], v[216:219], v[12:15]
	v_mfma_f32_16x16x32_bf16 v[8:11], v[148:151], v[216:219], v[8:11]
	v_mfma_f32_16x16x32_bf16 v[60:63], v[144:147], v[176:179], v[60:63]
	v_mfma_f32_16x16x32_bf16 v[56:59], v[152:155], v[176:179], v[56:59]
	v_mfma_f32_16x16x32_bf16 v[44:47], v[144:147], v[184:187], v[44:47]
	v_mfma_f32_16x16x32_bf16 v[40:43], v[152:155], v[184:187], v[40:43]
	v_mfma_f32_16x16x32_bf16 v[28:31], v[144:147], v[212:215], v[28:31]
	v_mfma_f32_16x16x32_bf16 v[24:27], v[152:155], v[212:215], v[24:27]
	v_mfma_f32_16x16x32_bf16 v[12:15], v[144:147], v[232:235], v[12:15]
	v_mfma_f32_16x16x32_bf16 v[8:11], v[152:155], v[232:235], v[8:11]
	v_mfma_f32_16x16x32_bf16 v[52:55], v[156:159], v[172:175], v[52:55]
	v_mfma_f32_16x16x32_bf16 v[48:51], v[164:167], v[172:175], v[48:51]
	v_mfma_f32_16x16x32_bf16 v[36:39], v[156:159], v[180:183], v[36:39]
	v_mfma_f32_16x16x32_bf16 v[32:35], v[164:167], v[180:183], v[32:35]
	v_mfma_f32_16x16x32_bf16 v[20:23], v[156:159], v[188:191], v[20:23]
	v_mfma_f32_16x16x32_bf16 v[16:19], v[164:167], v[188:191], v[16:19]
	v_mfma_f32_16x16x32_bf16 v[4:7], v[156:159], v[216:219], v[4:7]
	v_mfma_f32_16x16x32_bf16 v[0:3], v[164:167], v[216:219], v[0:3]
	v_mfma_f32_16x16x32_bf16 v[52:55], v[160:163], v[176:179], v[52:55]
	v_mfma_f32_16x16x32_bf16 v[48:51], v[168:171], v[176:179], v[48:51]
	v_mfma_f32_16x16x32_bf16 v[36:39], v[160:163], v[184:187], v[36:39]
	v_mfma_f32_16x16x32_bf16 v[32:35], v[168:171], v[184:187], v[32:35]
	v_mfma_f32_16x16x32_bf16 v[20:23], v[160:163], v[212:215], v[20:23]
	v_mfma_f32_16x16x32_bf16 v[16:19], v[168:171], v[212:215], v[16:19]
	v_mfma_f32_16x16x32_bf16 v[4:7], v[160:163], v[232:235], v[4:7]
	v_mfma_f32_16x16x32_bf16 v[0:3], v[168:171], v[232:235], v[0:3]
	s_barrier
	s_add_i32 s35, 0, 0x18000
	s_add_i32 s38, 0, 0x1c000
	v_add_u32_e32 v152, s35, v142
	v_add_u32_e32 v168, s38, v142
	ds_read_b128 v[138:141], v152
	ds_read_b128 v[144:147], v152 offset:1024
	ds_read_b128 v[148:151], v152 offset:2048
	ds_read_b128 v[152:155], v152 offset:3072
	ds_read_b128 v[156:159], v168
	ds_read_b128 v[160:163], v168 offset:1024
	ds_read_b128 v[164:167], v168 offset:2048
	ds_read_b128 v[168:171], v168 offset:3072
	s_add_u32 s40, s58, 0x20000
	s_addc_u32 s41, s59, 0
	s_mov_b32 m0, s85
	v_lshl_add_u64 v[206:207], s[40:41], 0, v[128:129]
	ds_read_b128 v[172:175], v143 offset:32768
	ds_read_b128 v[176:179], v143 offset:33792
	ds_read_b128 v[180:183], v143 offset:34816
	ds_read_b128 v[184:187], v143 offset:35840
	ds_read_b128 v[188:191], v143 offset:36864
	ds_read_b128 v[212:215], v143 offset:37888
	ds_read_b128 v[216:219], v143 offset:38912
	ds_read_b128 v[232:235], v143 offset:39936
	global_load_lds_dwordx4 v[206:207], off
	v_lshl_add_u64 v[206:207], s[40:41], 0, v[130:131]
	s_mov_b32 m0, s86
	s_nop 0
	global_load_lds_dwordx4 v[206:207], off
	s_waitcnt vmcnt(8)
	s_waitcnt lgkmcnt(0)
	s_barrier
	s_waitcnt lgkmcnt(0)
	v_mfma_f32_16x16x32_bf16 v[124:127], v[138:141], v[172:175], v[124:127]
	v_mfma_f32_16x16x32_bf16 v[120:123], v[148:151], v[172:175], v[120:123]
	v_mfma_f32_16x16x32_bf16 v[108:111], v[138:141], v[180:183], v[108:111]
	v_mfma_f32_16x16x32_bf16 v[104:107], v[148:151], v[180:183], v[104:107]
	v_mfma_f32_16x16x32_bf16 v[92:95], v[138:141], v[188:191], v[92:95]
	v_mfma_f32_16x16x32_bf16 v[88:91], v[148:151], v[188:191], v[88:91]
	v_mfma_f32_16x16x32_bf16 v[76:79], v[138:141], v[216:219], v[76:79]
	v_mfma_f32_16x16x32_bf16 v[72:75], v[148:151], v[216:219], v[72:75]
	v_mfma_f32_16x16x32_bf16 v[124:127], v[144:147], v[176:179], v[124:127]
	v_mfma_f32_16x16x32_bf16 v[120:123], v[152:155], v[176:179], v[120:123]
	v_mfma_f32_16x16x32_bf16 v[108:111], v[144:147], v[184:187], v[108:111]
	v_mfma_f32_16x16x32_bf16 v[104:107], v[152:155], v[184:187], v[104:107]
	v_mfma_f32_16x16x32_bf16 v[92:95], v[144:147], v[212:215], v[92:95]
	v_mfma_f32_16x16x32_bf16 v[88:91], v[152:155], v[212:215], v[88:91]
	v_mfma_f32_16x16x32_bf16 v[76:79], v[144:147], v[232:235], v[76:79]
	v_mfma_f32_16x16x32_bf16 v[72:75], v[152:155], v[232:235], v[72:75]
	v_mfma_f32_16x16x32_bf16 v[116:119], v[156:159], v[172:175], v[116:119]
	v_mfma_f32_16x16x32_bf16 v[112:115], v[164:167], v[172:175], v[112:115]
	v_mfma_f32_16x16x32_bf16 v[100:103], v[156:159], v[180:183], v[100:103]
	v_mfma_f32_16x16x32_bf16 v[96:99], v[164:167], v[180:183], v[96:99]
	v_mfma_f32_16x16x32_bf16 v[84:87], v[156:159], v[188:191], v[84:87]
	v_mfma_f32_16x16x32_bf16 v[80:83], v[164:167], v[188:191], v[80:83]
	v_mfma_f32_16x16x32_bf16 v[68:71], v[156:159], v[216:219], v[68:71]
	v_mfma_f32_16x16x32_bf16 v[64:67], v[164:167], v[216:219], v[64:67]
	v_mfma_f32_16x16x32_bf16 v[116:119], v[160:163], v[176:179], v[116:119]
	v_mfma_f32_16x16x32_bf16 v[112:115], v[168:171], v[176:179], v[112:115]
	v_mfma_f32_16x16x32_bf16 v[100:103], v[160:163], v[184:187], v[100:103]
	v_mfma_f32_16x16x32_bf16 v[96:99], v[168:171], v[184:187], v[96:99]
	v_mfma_f32_16x16x32_bf16 v[84:87], v[160:163], v[212:215], v[84:87]
	v_mfma_f32_16x16x32_bf16 v[80:83], v[168:171], v[212:215], v[80:83]
	v_mfma_f32_16x16x32_bf16 v[68:71], v[160:163], v[232:235], v[68:71]
	v_mfma_f32_16x16x32_bf16 v[64:67], v[168:171], v[232:235], v[64:67]
	s_barrier
; #define PG8_STAGE(bufoff, gbase, voff) do { _Pragma("unroll") for (int _i = 0; _i < 2; ++_i) \
;         __builtin_amdgcn_global_load_lds((const unsigned*)((const char*)(gbase) + (voff)[_i]), (PG8_LAS unsigned*)(lds + (bufoff) + ldsw + _i * 8192), 16, 0, 0); } while (0)
; #define PG8_LDA(dst, b, h) do { _Pragma("unroll") for (int m = 0; m < 4; ++m) _Pragma("unroll") for (int k = 0; k < 2; ++k) dst[m][k] = *(const PG8_LAS bf16x8*)(lds + PG8_SA(b, h) + aoff + m * 2048 + k * 1024); } while (0)
; #define PG8_MMA(ai, bj, At, Bt) do { __builtin_amdgcn_s_setprio(1); _Pragma("unroll") for (int m = 0; m < 4; ++m) _Pragma("unroll") for (int n = 0; n < 2; ++n) _Pragma("unroll") for (int k = 0; k < 2; ++k) \
;         acc[ai][bj][m][n] = __builtin_amdgcn_mfma_f32_16x16x32_bf16(Bt[n][k], At[m][k], acc[ai][bj][m][n], 0, 0, 0); __builtin_amdgcn_s_setprio(0); } while (0)
; #define PG8_WAIT_V(n) asm volatile("s_waitcnt vmcnt(" #n ")" ::: "memory")
; #define PG8_WAIT_L(n) asm volatile("s_waitcnt lgkmcnt(" #n ")" ::: "memory")
; #define PG8_BAR __builtin_amdgcn_s_barrier()
; #define PG8_SCHED __builtin_amdgcn_sched_barrier(0)
; template <class Epi, class Sched, bool ALIGN_EPI = false, bool SP2 = false>
; __device__ __forceinline__ void gemm_phase(PG8_LAS unsigned char* lds, const Gemm g, const Sched& S, const Epi& E, const int tid) {
;     ...
;         for (int t = 0; t < nt; t += 2) {
;     ...
;             PG8_LDA(At, 1, 1); PG8_STAGE(PG8_SB(1, 0), b3, voffB); PG8_STAGE(PG8_SB(1, 1), b3 + hstep, voffB); PG8_STAGE(PG8_SA(1, 0), a3, voffA);
;             PG8_WAIT_V(8); PG8_WAIT_L(0); PG8_BAR; PG8_MMA(1, 0, At, B0); PG8_MMA(1, 1, At, B1); PG8_BAR; PG8_SCHED;
	s_add_i32 s35, s35, s82
	v_lshl_add_u64 v[194:195], v[194:195], 0, s[36:37]
	s_mov_b32 m0, s35
	ds_read_b128 v[172:175], v143 offset:49152
	ds_read_b128 v[176:179], v143 offset:50176
	ds_read_b128 v[180:183], v143 offset:51200
	ds_read_b128 v[184:187], v143 offset:52224
	ds_read_b128 v[188:191], v143 offset:53248
	ds_read_b128 v[212:215], v143 offset:54272
	ds_read_b128 v[216:219], v143 offset:55296
	ds_read_b128 v[232:235], v143 offset:56320
	global_load_lds_dwordx4 v[194:195], off
	s_add_i32 m0, s35, 0x2000
	s_add_u32 s40, s44, 0x20080
	v_lshl_add_u64 v[194:195], v[196:197], 0, s[36:37]
	s_addc_u32 s41, s45, 0
	s_add_i32 s35, s38, s82
	global_load_lds_dwordx4 v[194:195], off
	v_lshl_add_u64 v[194:195], s[40:41], 0, v[192:193]
	s_mov_b32 m0, s35
	s_nop 0
	global_load_lds_dwordx4 v[194:195], off
	v_lshl_add_u64 v[194:195], s[40:41], 0, v[132:133]
	s_add_i32 m0, s35, 0x2000
	s_nop 0
	global_load_lds_dwordx4 v[194:195], off
	v_lshl_add_u64 v[194:195], v[202:203], 0, s[36:37]
	s_mov_b32 m0, s87
	s_nop 0
	global_load_lds_dwordx4 v[194:195], off
	v_lshl_add_u64 v[194:195], v[204:205], 0, s[36:37]
	s_mov_b32 m0, s88
	s_nop 0
	global_load_lds_dwordx4 v[194:195], off
	s_waitcnt vmcnt(8)
	s_waitcnt lgkmcnt(0)
	s_barrier
	s_waitcnt lgkmcnt(0)
	v_mfma_f32_16x16x32_bf16 v[60:63], v[138:141], v[172:175], v[60:63]
	v_mfma_f32_16x16x32_bf16 v[56:59], v[148:151], v[172:175], v[56:59]
	v_mfma_f32_16x16x32_bf16 v[44:47], v[138:141], v[180:183], v[44:47]
	v_mfma_f32_16x16x32_bf16 v[40:43], v[148:151], v[180:183], v[40:43]
	v_mfma_f32_16x16x32_bf16 v[28:31], v[138:141], v[188:191], v[28:31]
	v_mfma_f32_16x16x32_bf16 v[24:27], v[148:151], v[188:191], v[24:27]
	v_mfma_f32_16x16x32_bf16 v[12:15], v[138:141], v[216:219], v[12:15]
	v_mfma_f32_16x16x32_bf16 v[8:11], v[148:151], v[216:219], v[8:11]
	v_mfma_f32_16x16x32_bf16 v[60:63], v[144:147], v[176:179], v[60:63]
	v_mfma_f32_16x16x32_bf16 v[56:59], v[152:155], v[176:179], v[56:59]
	v_mfma_f32_16x16x32_bf16 v[44:47], v[144:147], v[184:187], v[44:47]
	v_mfma_f32_16x16x32_bf16 v[40:43], v[152:155], v[184:187], v[40:43]
	v_mfma_f32_16x16x32_bf16 v[28:31], v[144:147], v[212:215], v[28:31]
	v_mfma_f32_16x16x32_bf16 v[24:27], v[152:155], v[212:215], v[24:27]
	v_mfma_f32_16x16x32_bf16 v[12:15], v[144:147], v[232:235], v[12:15]
	v_mfma_f32_16x16x32_bf16 v[8:11], v[152:155], v[232:235], v[8:11]
	v_mfma_f32_16x16x32_bf16 v[52:55], v[156:159], v[172:175], v[52:55]
	v_mfma_f32_16x16x32_bf16 v[48:51], v[164:167], v[172:175], v[48:51]
	v_mfma_f32_16x16x32_bf16 v[36:39], v[156:159], v[180:183], v[36:39]
	v_mfma_f32_16x16x32_bf16 v[32:35], v[164:167], v[180:183], v[32:35]
	v_mfma_f32_16x16x32_bf16 v[20:23], v[156:159], v[188:191], v[20:23]
	v_mfma_f32_16x16x32_bf16 v[16:19], v[164:167], v[188:191], v[16:19]
	v_mfma_f32_16x16x32_bf16 v[4:7], v[156:159], v[216:219], v[4:7]
	v_mfma_f32_16x16x32_bf16 v[0:3], v[164:167], v[216:219], v[0:3]
	v_mfma_f32_16x16x32_bf16 v[52:55], v[160:163], v[176:179], v[52:55]
	v_mfma_f32_16x16x32_bf16 v[48:51], v[168:171], v[176:179], v[48:51]
	v_mfma_f32_16x16x32_bf16 v[36:39], v[160:163], v[184:187], v[36:39]
	v_mfma_f32_16x16x32_bf16 v[32:35], v[168:171], v[184:187], v[32:35]
	v_mfma_f32_16x16x32_bf16 v[20:23], v[160:163], v[212:215], v[20:23]
	v_mfma_f32_16x16x32_bf16 v[16:19], v[168:171], v[212:215], v[16:19]
	v_mfma_f32_16x16x32_bf16 v[4:7], v[160:163], v[232:235], v[4:7]
	v_mfma_f32_16x16x32_bf16 v[0:3], v[168:171], v[232:235], v[0:3]
	s_barrier
	s_add_i32 s34, s34, 2
	s_add_u32 s28, s28, 0x100
	s_addc_u32 s29, s29, 0
	s_add_u32 s23, s23, 0x100
	s_addc_u32 s26, s26, 0
	s_cmp_gt_u32 s34, 5
	s_cbranch_scc0 .LBB0_348
	s_and_b64 vcc, exec, s[12:13]
	s_cbranch_vccz .LBB0_351
	s_barrier

; #define PG8_STAGE(bufoff, gbase, voff) do { _Pragma("unroll") for (int _i = 0; _i < 2; ++_i) \
;         __builtin_amdgcn_global_load_lds((const unsigned*)((const char*)(gbase) + (voff)[_i]), (PG8_LAS unsigned*)(lds + (bufoff) + ldsw + _i * 8192), 16, 0, 0); } while (0)
; #define PG8_LDA(dst, b, h) do { _Pragma("unroll") for (int m = 0; m < 4; ++m) _Pragma("unroll") for (int k = 0; k < 2; ++k) dst[m][k] = *(const PG8_LAS bf16x8*)(lds + PG8_SA(b, h) + aoff + m * 2048 + k * 1024); } while (0)
; #define PG8_LDB(dst, b, h) do { _Pragma("unroll") for (int n = 0; n < 2; ++n) _Pragma("unroll") for (int k = 0; k < 2; ++k) dst[n][k] = *(const PG8_LAS bf16x8*)(lds + PG8_SB(b, h) + boff + n * 2048 + k * 1024); } while (0)
; #define PG8_MMA(ai, bj, At, Bt) do { __builtin_amdgcn_s_setprio(1); _Pragma("unroll") for (int m = 0; m < 4; ++m) _Pragma("unroll") for (int n = 0; n < 2; ++n) _Pragma("unroll") for (int k = 0; k < 2; ++k) \
;         acc[ai][bj][m][n] = __builtin_amdgcn_mfma_f32_16x16x32_bf16(Bt[n][k], At[m][k], acc[ai][bj][m][n], 0, 0, 0); __builtin_amdgcn_s_setprio(0); } while (0)
; #define PG8_WAIT_V(n) asm volatile("s_waitcnt vmcnt(" #n ")" ::: "memory")
; #define PG8_WAIT_L(n) asm volatile("s_waitcnt lgkmcnt(" #n ")" ::: "memory")
; #define PG8_BAR __builtin_amdgcn_s_barrier()
; #define PG8_SCHED __builtin_amdgcn_sched_barrier(0)
; template <class Epi, class Sched, bool ALIGN_EPI = false, bool SP2 = false>
; __device__ __forceinline__ void gemm_phase(PG8_LAS unsigned char* lds, const Gemm g, const Sched& S, const Epi& E, const int tid) {
;     ...
;             const bool last = (t == nt - 2);
;             const char* a1 = cA + (size_t)(t + 1) * kstep;
;             const char* a2 = last ? nA : cA + (size_t)(t + 2) * kstep; const char* b2 = last ? nB : cB + (size_t)(t + 2) * kstep;
;             const char* a3 = a2 + kstep; const char* b3 = b2 + kstep;
;             if (last && has_next) S.a_ready(nxt);
;             if constexpr (SP2) {
;             PG8_LDB(B0, 0, 0); PG8_LDB(B1, 0, 1); PG8_SCHED; PG8_LDA(At, 0, 0); PG8_STAGE(PG8_SA(1, 1), a1 + hstep, voffA);
;             PG8_WAIT_V(8); PG8_WAIT_L(0); PG8_BAR; PG8_MMA(0, 0, At, B0); PG8_MMA(0, 1, At, B1); PG8_BAR; PG8_SCHED;
;             PG8_LDA(At, 0, 1); PG8_STAGE(PG8_SB(0, 0), b2, voffB); PG8_STAGE(PG8_SB(0, 1), b2 + hstep, voffB); PG8_STAGE(PG8_SA(0, 0), a2, voffA);
.LBB0_485:
	s_add_u32 s38, s8, 0xfffc0080
	s_addc_u32 s40, s9, -1
	s_add_i32 s41, 0, 0x10000
	s_cmp_eq_u32 s35, 12
	s_cselect_b32 s59, s0, s40
	s_cselect_b32 s58, s1, s38
	s_cselect_b32 s45, s2, s34
	s_cselect_b32 s44, s15, s17
	s_add_i32 s38, 0, 0x14000
	v_add_u32_e32 v140, s41, v184
	v_add_u32_e32 v168, s38, v184
	ds_read_b128 v[128:131], v140
	ds_read_b128 v[132:135], v140 offset:1024
	ds_read_b128 v[136:139], v140 offset:2048
	ds_read_b128 v[140:143], v140 offset:3072
	ds_read_b128 v[144:147], v168
	ds_read_b128 v[148:151], v168 offset:1024
	ds_read_b128 v[164:167], v168 offset:2048
	ds_read_b128 v[168:171], v168 offset:3072
	v_lshl_add_u64 v[190:191], s[8:9], 0, v[160:161]
	s_add_i32 m0, s23, 0xc000
	ds_read_b128 v[172:175], v185
	ds_read_b128 v[176:179], v185 offset:1024
	ds_read_b128 v[180:183], v185 offset:2048
	ds_read_b128 v[186:189], v185 offset:3072
	ds_read_b128 v[212:215], v185 offset:4096
	ds_read_b128 v[216:219], v185 offset:5120
	ds_read_b128 v[232:235], v185 offset:6144
	ds_read_b128 v[236:239], v185 offset:7168
	global_load_lds_dwordx4 v[190:191], off
	v_lshl_add_u64 v[190:191], s[8:9], 0, v[162:163]
	s_add_i32 m0, s23, 0xe000
	s_nop 0
	global_load_lds_dwordx4 v[190:191], off
	s_waitcnt vmcnt(8)
	s_waitcnt lgkmcnt(0)
	s_barrier
	s_waitcnt lgkmcnt(0)
	v_mfma_f32_16x16x32_bf16 v[124:127], v[128:131], v[172:175], v[124:127]
	v_mfma_f32_16x16x32_bf16 v[120:123], v[136:139], v[172:175], v[120:123]
	v_mfma_f32_16x16x32_bf16 v[108:111], v[128:131], v[180:183], v[108:111]
	v_mfma_f32_16x16x32_bf16 v[104:107], v[136:139], v[180:183], v[104:107]
	v_mfma_f32_16x16x32_bf16 v[92:95], v[128:131], v[212:215], v[92:95]
	v_mfma_f32_16x16x32_bf16 v[88:91], v[136:139], v[212:215], v[88:91]
	v_mfma_f32_16x16x32_bf16 v[76:79], v[128:131], v[232:235], v[76:79]
	v_mfma_f32_16x16x32_bf16 v[72:75], v[136:139], v[232:235], v[72:75]
	v_mfma_f32_16x16x32_bf16 v[124:127], v[132:135], v[176:179], v[124:127]
	v_mfma_f32_16x16x32_bf16 v[120:123], v[140:143], v[176:179], v[120:123]
	v_mfma_f32_16x16x32_bf16 v[108:111], v[132:135], v[186:189], v[108:111]
	v_mfma_f32_16x16x32_bf16 v[104:107], v[140:143], v[186:189], v[104:107]
	v_mfma_f32_16x16x32_bf16 v[92:95], v[132:135], v[216:219], v[92:95]
	v_mfma_f32_16x16x32_bf16 v[88:91], v[140:143], v[216:219], v[88:91]
	v_mfma_f32_16x16x32_bf16 v[76:79], v[132:135], v[236:239], v[76:79]
	v_mfma_f32_16x16x32_bf16 v[72:75], v[140:143], v[236:239], v[72:75]
	v_mfma_f32_16x16x32_bf16 v[116:119], v[144:147], v[172:175], v[116:119]
	v_mfma_f32_16x16x32_bf16 v[112:115], v[164:167], v[172:175], v[112:115]
	v_mfma_f32_16x16x32_bf16 v[100:103], v[144:147], v[180:183], v[100:103]
	v_mfma_f32_16x16x32_bf16 v[96:99], v[164:167], v[180:183], v[96:99]
	v_mfma_f32_16x16x32_bf16 v[84:87], v[144:147], v[212:215], v[84:87]
	v_mfma_f32_16x16x32_bf16 v[80:83], v[164:167], v[212:215], v[80:83]
	v_mfma_f32_16x16x32_bf16 v[68:71], v[144:147], v[232:235], v[68:71]
	v_mfma_f32_16x16x32_bf16 v[64:67], v[164:167], v[232:235], v[64:67]
	v_mfma_f32_16x16x32_bf16 v[116:119], v[148:151], v[176:179], v[116:119]
	v_mfma_f32_16x16x32_bf16 v[112:115], v[168:171], v[176:179], v[112:115]
	v_mfma_f32_16x16x32_bf16 v[100:103], v[148:151], v[186:189], v[100:103]
	v_mfma_f32_16x16x32_bf16 v[96:99], v[168:171], v[186:189], v[96:99]
	v_mfma_f32_16x16x32_bf16 v[84:87], v[148:151], v[216:219], v[84:87]
	v_mfma_f32_16x16x32_bf16 v[80:83], v[168:171], v[216:219], v[80:83]
	v_mfma_f32_16x16x32_bf16 v[68:71], v[148:151], v[236:239], v[68:71]
	v_mfma_f32_16x16x32_bf16 v[64:67], v[168:171], v[236:239], v[64:67]
	s_barrier
	s_add_i32 s40, s41, s83
	v_lshl_add_u64 v[190:191], s[44:45], 0, v[154:155]
	s_mov_b32 m0, s40
	ds_read_b128 v[172:175], v185 offset:16384
	ds_read_b128 v[176:179], v185 offset:17408
	ds_read_b128 v[180:183], v185 offset:18432
	ds_read_b128 v[186:189], v185 offset:19456
	ds_read_b128 v[212:215], v185 offset:20480
	ds_read_b128 v[216:219], v185 offset:21504
	ds_read_b128 v[232:235], v185 offset:22528
	ds_read_b128 v[236:239], v185 offset:23552
	global_load_lds_dwordx4 v[190:191], off
	s_add_i32 m0, s40, 0x2000
	s_add_u32 s40, s44, 0x40000
	v_lshl_add_u64 v[194:195], s[44:45], 0, v[158:159]
	s_addc_u32 s41, s45, 0
	s_add_i32 s38, s38, s83
	global_load_lds_dwordx4 v[194:195], off
	v_lshl_add_u64 v[196:197], s[40:41], 0, v[154:155]
	s_mov_b32 m0, s38
	v_lshl_add_u64 v[202:203], s[58:59], 0, v[156:157]
	global_load_lds_dwordx4 v[196:197], off
	v_lshl_add_u64 v[196:197], s[40:41], 0, v[158:159]
	s_add_i32 m0, s38, 0x2000
	s_nop 0
	global_load_lds_dwordx4 v[196:197], off
	v_lshl_add_u64 v[196:197], s[58:59], 0, v[152:153]
	s_mov_b32 m0, s23
	s_nop 0
	global_load_lds_dwordx4 v[196:197], off
	s_mov_b32 m0, s29
	s_nop 0
	global_load_lds_dwordx4 v[202:203], off
	s_waitcnt vmcnt(8)
	s_waitcnt lgkmcnt(0)
	s_barrier
; #define PG8_STAGE(bufoff, gbase, voff) do { _Pragma("unroll") for (int _i = 0; _i < 2; ++_i) \
;         __builtin_amdgcn_global_load_lds((const unsigned*)((const char*)(gbase) + (voff)[_i]), (PG8_LAS unsigned*)(lds + (bufoff) + ldsw + _i * 8192), 16, 0, 0); } while (0)
; #define PG8_LDA(dst, b, h) do { _Pragma("unroll") for (int m = 0; m < 4; ++m) _Pragma("unroll") for (int k = 0; k < 2; ++k) dst[m][k] = *(const PG8_LAS bf16x8*)(lds + PG8_SA(b, h) + aoff + m * 2048 + k * 1024); } while (0)
; #define PG8_LDB(dst, b, h) do { _Pragma("unroll") for (int n = 0; n < 2; ++n) _Pragma("unroll") for (int k = 0; k < 2; ++k) dst[n][k] = *(const PG8_LAS bf16x8*)(lds + PG8_SB(b, h) + boff + n * 2048 + k * 1024); } while (0)
; #define PG8_MMA(ai, bj, At, Bt) do { __builtin_amdgcn_s_setprio(1); _Pragma("unroll") for (int m = 0; m < 4; ++m) _Pragma("unroll") for (int n = 0; n < 2; ++n) _Pragma("unroll") for (int k = 0; k < 2; ++k) \
;         acc[ai][bj][m][n] = __builtin_amdgcn_mfma_f32_16x16x32_bf16(Bt[n][k], At[m][k], acc[ai][bj][m][n], 0, 0, 0); __builtin_amdgcn_s_setprio(0); } while (0)
; #define PG8_WAIT_V(n) asm volatile("s_waitcnt vmcnt(" #n ")" ::: "memory")
; #define PG8_WAIT_L(n) asm volatile("s_waitcnt lgkmcnt(" #n ")" ::: "memory")
; #define PG8_BAR __builtin_amdgcn_s_barrier()
; #define PG8_SCHED __builtin_amdgcn_sched_barrier(0)
; template <class Epi, class Sched, bool ALIGN_EPI = false, bool SP2 = false>
; __device__ __forceinline__ void gemm_phase(PG8_LAS unsigned char* lds, const Gemm g, const Sched& S, const Epi& E, const int tid) {
;     ...
;             PG8_WAIT_V(8); PG8_WAIT_L(0); PG8_BAR; PG8_MMA(1, 0, At, B0); PG8_MMA(1, 1, At, B1); PG8_BAR; PG8_SCHED;
;             PG8_LDB(B0, 1, 0); PG8_LDB(B1, 1, 1); PG8_SCHED; PG8_LDA(At, 1, 0); PG8_STAGE(PG8_SA(0, 1), a2 + hstep, voffA);
;             PG8_WAIT_V(8); PG8_WAIT_L(0); PG8_BAR; PG8_MMA(0, 0, At, B0); PG8_MMA(0, 1, At, B1); PG8_BAR; PG8_SCHED;
	s_waitcnt lgkmcnt(0)
	v_mfma_f32_16x16x32_bf16 v[60:63], v[128:131], v[172:175], v[60:63]
	v_mfma_f32_16x16x32_bf16 v[56:59], v[136:139], v[172:175], v[56:59]
	v_mfma_f32_16x16x32_bf16 v[44:47], v[128:131], v[180:183], v[44:47]
	v_mfma_f32_16x16x32_bf16 v[40:43], v[136:139], v[180:183], v[40:43]
	v_mfma_f32_16x16x32_bf16 v[28:31], v[128:131], v[212:215], v[28:31]
	v_mfma_f32_16x16x32_bf16 v[24:27], v[136:139], v[212:215], v[24:27]
	v_mfma_f32_16x16x32_bf16 v[12:15], v[128:131], v[232:235], v[12:15]
	v_mfma_f32_16x16x32_bf16 v[8:11], v[136:139], v[232:235], v[8:11]
	v_mfma_f32_16x16x32_bf16 v[60:63], v[132:135], v[176:179], v[60:63]
	v_mfma_f32_16x16x32_bf16 v[56:59], v[140:143], v[176:179], v[56:59]
	v_mfma_f32_16x16x32_bf16 v[44:47], v[132:135], v[186:189], v[44:47]
	v_mfma_f32_16x16x32_bf16 v[40:43], v[140:143], v[186:189], v[40:43]
	v_mfma_f32_16x16x32_bf16 v[28:31], v[132:135], v[216:219], v[28:31]
	v_mfma_f32_16x16x32_bf16 v[24:27], v[140:143], v[216:219], v[24:27]
	v_mfma_f32_16x16x32_bf16 v[12:15], v[132:135], v[236:239], v[12:15]
	v_mfma_f32_16x16x32_bf16 v[8:11], v[140:143], v[236:239], v[8:11]
	v_mfma_f32_16x16x32_bf16 v[52:55], v[144:147], v[172:175], v[52:55]
	v_mfma_f32_16x16x32_bf16 v[48:51], v[164:167], v[172:175], v[48:51]
	v_mfma_f32_16x16x32_bf16 v[36:39], v[144:147], v[180:183], v[36:39]
	v_mfma_f32_16x16x32_bf16 v[32:35], v[164:167], v[180:183], v[32:35]
	v_mfma_f32_16x16x32_bf16 v[20:23], v[144:147], v[212:215], v[20:23]
	v_mfma_f32_16x16x32_bf16 v[16:19], v[164:167], v[212:215], v[16:19]
	v_mfma_f32_16x16x32_bf16 v[4:7], v[144:147], v[232:235], v[4:7]
	v_mfma_f32_16x16x32_bf16 v[0:3], v[164:167], v[232:235], v[0:3]
	v_mfma_f32_16x16x32_bf16 v[52:55], v[148:151], v[176:179], v[52:55]
	v_mfma_f32_16x16x32_bf16 v[48:51], v[168:171], v[176:179], v[48:51]
	v_mfma_f32_16x16x32_bf16 v[36:39], v[148:151], v[186:189], v[36:39]
	v_mfma_f32_16x16x32_bf16 v[32:35], v[168:171], v[186:189], v[32:35]
	v_mfma_f32_16x16x32_bf16 v[20:23], v[148:151], v[216:219], v[20:23]
	v_mfma_f32_16x16x32_bf16 v[16:19], v[168:171], v[216:219], v[16:19]
	v_mfma_f32_16x16x32_bf16 v[4:7], v[148:151], v[236:239], v[4:7]
	v_mfma_f32_16x16x32_bf16 v[0:3], v[168:171], v[236:239], v[0:3]
	s_barrier
	s_add_i32 s38, 0, 0x18000
	s_add_i32 s46, 0, 0x1c000
	v_add_u32_e32 v140, s38, v184
	v_add_u32_e32 v168, s46, v184
	ds_read_b128 v[128:131], v140
	ds_read_b128 v[132:135], v140 offset:1024
	ds_read_b128 v[136:139], v140 offset:2048
	ds_read_b128 v[140:143], v140 offset:3072
	ds_read_b128 v[144:147], v168
	ds_read_b128 v[148:151], v168 offset:1024
	ds_read_b128 v[164:167], v168 offset:2048
	ds_read_b128 v[168:171], v168 offset:3072
	s_add_u32 s40, s58, 0x40000
	s_addc_u32 s41, s59, 0
	s_mov_b32 m0, s84
	v_lshl_add_u64 v[204:205], s[40:41], 0, v[152:153]
	ds_read_b128 v[172:175], v185 offset:32768
	ds_read_b128 v[176:179], v185 offset:33792
	ds_read_b128 v[180:183], v185 offset:34816
	ds_read_b128 v[186:189], v185 offset:35840
	ds_read_b128 v[212:215], v185 offset:36864
	ds_read_b128 v[216:219], v185 offset:37888
	ds_read_b128 v[232:235], v185 offset:38912
	ds_read_b128 v[236:239], v185 offset:39936
	global_load_lds_dwordx4 v[204:205], off
	v_lshl_add_u64 v[204:205], s[40:41], 0, v[156:157]
	s_mov_b32 m0, s85
	s_nop 0
	global_load_lds_dwordx4 v[204:205], off
	s_waitcnt vmcnt(8)
	s_waitcnt lgkmcnt(0)
	s_barrier
	s_waitcnt lgkmcnt(0)
	v_mfma_f32_16x16x32_bf16 v[124:127], v[128:131], v[172:175], v[124:127]
	v_mfma_f32_16x16x32_bf16 v[120:123], v[136:139], v[172:175], v[120:123]
	v_mfma_f32_16x16x32_bf16 v[108:111], v[128:131], v[180:183], v[108:111]
	v_mfma_f32_16x16x32_bf16 v[104:107], v[136:139], v[180:183], v[104:107]
	v_mfma_f32_16x16x32_bf16 v[92:95], v[128:131], v[212:215], v[92:95]
	v_mfma_f32_16x16x32_bf16 v[88:91], v[136:139], v[212:215], v[88:91]
	v_mfma_f32_16x16x32_bf16 v[76:79], v[128:131], v[232:235], v[76:79]
	v_mfma_f32_16x16x32_bf16 v[72:75], v[136:139], v[232:235], v[72:75]
	v_mfma_f32_16x16x32_bf16 v[124:127], v[132:135], v[176:179], v[124:127]
	v_mfma_f32_16x16x32_bf16 v[120:123], v[140:143], v[176:179], v[120:123]
	v_mfma_f32_16x16x32_bf16 v[108:111], v[132:135], v[186:189], v[108:111]
	v_mfma_f32_16x16x32_bf16 v[104:107], v[140:143], v[186:189], v[104:107]
	v_mfma_f32_16x16x32_bf16 v[92:95], v[132:135], v[216:219], v[92:95]
	v_mfma_f32_16x16x32_bf16 v[88:91], v[140:143], v[216:219], v[88:91]
	v_mfma_f32_16x16x32_bf16 v[76:79], v[132:135], v[236:239], v[76:79]
	v_mfma_f32_16x16x32_bf16 v[72:75], v[140:143], v[236:239], v[72:75]
	v_mfma_f32_16x16x32_bf16 v[116:119], v[144:147], v[172:175], v[116:119]
	v_mfma_f32_16x16x32_bf16 v[112:115], v[164:167], v[172:175], v[112:115]
	v_mfma_f32_16x16x32_bf16 v[100:103], v[144:147], v[180:183], v[100:103]
	v_mfma_f32_16x16x32_bf16 v[96:99], v[164:167], v[180:183], v[96:99]
	v_mfma_f32_16x16x32_bf16 v[84:87], v[144:147], v[212:215], v[84:87]
	v_mfma_f32_16x16x32_bf16 v[80:83], v[164:167], v[212:215], v[80:83]
	v_mfma_f32_16x16x32_bf16 v[68:71], v[144:147], v[232:235], v[68:71]
	v_mfma_f32_16x16x32_bf16 v[64:67], v[164:167], v[232:235], v[64:67]
	v_mfma_f32_16x16x32_bf16 v[116:119], v[148:151], v[176:179], v[116:119]
	v_mfma_f32_16x16x32_bf16 v[112:115], v[168:171], v[176:179], v[112:115]
	v_mfma_f32_16x16x32_bf16 v[100:103], v[148:151], v[186:189], v[100:103]
	v_mfma_f32_16x16x32_bf16 v[96:99], v[168:171], v[186:189], v[96:99]
	v_mfma_f32_16x16x32_bf16 v[84:87], v[148:151], v[216:219], v[84:87]
	v_mfma_f32_16x16x32_bf16 v[80:83], v[168:171], v[216:219], v[80:83]
	v_mfma_f32_16x16x32_bf16 v[68:71], v[148:151], v[236:239], v[68:71]
	v_mfma_f32_16x16x32_bf16 v[64:67], v[168:171], v[236:239], v[64:67]
	s_barrier
; #define PG8_STAGE(bufoff, gbase, voff) do { _Pragma("unroll") for (int _i = 0; _i < 2; ++_i) \
;         __builtin_amdgcn_global_load_lds((const unsigned*)((const char*)(gbase) + (voff)[_i]), (PG8_LAS unsigned*)(lds + (bufoff) + ldsw + _i * 8192), 16, 0, 0); } while (0)
; #define PG8_LDA(dst, b, h) do { _Pragma("unroll") for (int m = 0; m < 4; ++m) _Pragma("unroll") for (int k = 0; k < 2; ++k) dst[m][k] = *(const PG8_LAS bf16x8*)(lds + PG8_SA(b, h) + aoff + m * 2048 + k * 1024); } while (0)
; #define PG8_MMA(ai, bj, At, Bt) do { __builtin_amdgcn_s_setprio(1); _Pragma("unroll") for (int m = 0; m < 4; ++m) _Pragma("unroll") for (int n = 0; n < 2; ++n) _Pragma("unroll") for (int k = 0; k < 2; ++k) \
;         acc[ai][bj][m][n] = __builtin_amdgcn_mfma_f32_16x16x32_bf16(Bt[n][k], At[m][k], acc[ai][bj][m][n], 0, 0, 0); __builtin_amdgcn_s_setprio(0); } while (0)
; #define PG8_WAIT_V(n) asm volatile("s_waitcnt vmcnt(" #n ")" ::: "memory")
; #define PG8_WAIT_L(n) asm volatile("s_waitcnt lgkmcnt(" #n ")" ::: "memory")
; #define PG8_BAR __builtin_amdgcn_s_barrier()
; #define PG8_SCHED __builtin_amdgcn_sched_barrier(0)
; template <class Epi, class Sched, bool ALIGN_EPI = false, bool SP2 = false>
; __device__ __forceinline__ void gemm_phase(PG8_LAS unsigned char* lds, const Gemm g, const Sched& S, const Epi& E, const int tid) {
;     ...
;         for (int t = 0; t < nt; t += 2) {
;     ...
;             PG8_LDA(At, 1, 1); PG8_STAGE(PG8_SB(1, 0), b3, voffB); PG8_STAGE(PG8_SB(1, 1), b3 + hstep, voffB); PG8_STAGE(PG8_SA(1, 0), a3, voffA);
;             PG8_WAIT_V(8); PG8_WAIT_L(0); PG8_BAR; PG8_MMA(1, 0, At, B0); PG8_MMA(1, 1, At, B1); PG8_BAR; PG8_SCHED;
	s_add_i32 s38, s38, s83
	v_lshl_add_u64 v[190:191], v[190:191], 0, s[36:37]
	s_mov_b32 m0, s38
	ds_read_b128 v[172:175], v185 offset:49152
	ds_read_b128 v[176:179], v185 offset:50176
	ds_read_b128 v[180:183], v185 offset:51200
	ds_read_b128 v[186:189], v185 offset:52224
	ds_read_b128 v[212:215], v185 offset:53248
	ds_read_b128 v[216:219], v185 offset:54272
	ds_read_b128 v[232:235], v185 offset:55296
	ds_read_b128 v[236:239], v185 offset:56320
	global_load_lds_dwordx4 v[190:191], off
	s_add_i32 m0, s38, 0x2000
	s_add_u32 s40, s44, 0x40080
	v_lshl_add_u64 v[190:191], v[194:195], 0, s[36:37]
	s_addc_u32 s41, s45, 0
	s_add_i32 s38, s46, s83
	global_load_lds_dwordx4 v[190:191], off
	v_lshl_add_u64 v[190:191], s[40:41], 0, v[154:155]
	s_mov_b32 m0, s38
	s_nop 0
	global_load_lds_dwordx4 v[190:191], off
	v_lshl_add_u64 v[190:191], s[40:41], 0, v[158:159]
	s_add_i32 m0, s38, 0x2000
	s_nop 0
	global_load_lds_dwordx4 v[190:191], off
	v_lshl_add_u64 v[190:191], v[196:197], 0, s[36:37]
	s_mov_b32 m0, s86
	s_nop 0
	global_load_lds_dwordx4 v[190:191], off
	v_lshl_add_u64 v[190:191], v[202:203], 0, s[36:37]
	s_mov_b32 m0, s87
	s_nop 0
	global_load_lds_dwordx4 v[190:191], off
	s_waitcnt vmcnt(8)
	s_waitcnt lgkmcnt(0)
	s_barrier
	s_waitcnt lgkmcnt(0)
	v_mfma_f32_16x16x32_bf16 v[60:63], v[128:131], v[172:175], v[60:63]
	v_mfma_f32_16x16x32_bf16 v[56:59], v[136:139], v[172:175], v[56:59]
	v_mfma_f32_16x16x32_bf16 v[44:47], v[128:131], v[180:183], v[44:47]
	v_mfma_f32_16x16x32_bf16 v[40:43], v[136:139], v[180:183], v[40:43]
	v_mfma_f32_16x16x32_bf16 v[28:31], v[128:131], v[212:215], v[28:31]
	v_mfma_f32_16x16x32_bf16 v[24:27], v[136:139], v[212:215], v[24:27]
	v_mfma_f32_16x16x32_bf16 v[12:15], v[128:131], v[232:235], v[12:15]
	v_mfma_f32_16x16x32_bf16 v[8:11], v[136:139], v[232:235], v[8:11]
	v_mfma_f32_16x16x32_bf16 v[60:63], v[132:135], v[176:179], v[60:63]
	v_mfma_f32_16x16x32_bf16 v[56:59], v[140:143], v[176:179], v[56:59]
	v_mfma_f32_16x16x32_bf16 v[44:47], v[132:135], v[186:189], v[44:47]
	v_mfma_f32_16x16x32_bf16 v[40:43], v[140:143], v[186:189], v[40:43]
	v_mfma_f32_16x16x32_bf16 v[28:31], v[132:135], v[216:219], v[28:31]
	v_mfma_f32_16x16x32_bf16 v[24:27], v[140:143], v[216:219], v[24:27]
	v_mfma_f32_16x16x32_bf16 v[12:15], v[132:135], v[236:239], v[12:15]
	v_mfma_f32_16x16x32_bf16 v[8:11], v[140:143], v[236:239], v[8:11]
	v_mfma_f32_16x16x32_bf16 v[52:55], v[144:147], v[172:175], v[52:55]
	v_mfma_f32_16x16x32_bf16 v[48:51], v[164:167], v[172:175], v[48:51]
	v_mfma_f32_16x16x32_bf16 v[36:39], v[144:147], v[180:183], v[36:39]
	v_mfma_f32_16x16x32_bf16 v[32:35], v[164:167], v[180:183], v[32:35]
	v_mfma_f32_16x16x32_bf16 v[20:23], v[144:147], v[212:215], v[20:23]
	v_mfma_f32_16x16x32_bf16 v[16:19], v[164:167], v[212:215], v[16:19]
	v_mfma_f32_16x16x32_bf16 v[4:7], v[144:147], v[232:235], v[4:7]
	v_mfma_f32_16x16x32_bf16 v[0:3], v[164:167], v[232:235], v[0:3]
	v_mfma_f32_16x16x32_bf16 v[52:55], v[148:151], v[176:179], v[52:55]
	v_mfma_f32_16x16x32_bf16 v[48:51], v[168:171], v[176:179], v[48:51]
	v_mfma_f32_16x16x32_bf16 v[36:39], v[148:151], v[186:189], v[36:39]
	v_mfma_f32_16x16x32_bf16 v[32:35], v[168:171], v[186:189], v[32:35]
	v_mfma_f32_16x16x32_bf16 v[20:23], v[148:151], v[216:219], v[20:23]
	v_mfma_f32_16x16x32_bf16 v[16:19], v[168:171], v[216:219], v[16:19]
	v_mfma_f32_16x16x32_bf16 v[4:7], v[148:151], v[236:239], v[4:7]
	v_mfma_f32_16x16x32_bf16 v[0:3], v[168:171], v[236:239], v[0:3]
	s_barrier
	s_add_i32 s35, s35, 2
	s_add_u32 s8, s8, 0x100
	s_addc_u32 s9, s9, 0
	s_add_u32 s17, s17, 0x100
	s_addc_u32 s34, s34, 0
	s_cmp_gt_u32 s35, 13
	s_cbranch_scc0 .LBB0_485
	s_and_b64 vcc, exec, s[12:13]
	s_cbranch_vccz .LBB0_488
	s_barrier
